# up epilogue rows overlap the next tile's first LDS-DMA; GEMM k-loops start their accumulators with C=0 on the first MFMA (no zero-fill in the tile prologue)
# speedup vs baseline: 1.1047x; 1.0047x over previous
.LBB0_122:
	s_cmp_lt_i32 s28, 0
	s_cbranch_scc1 .LBB0_115
	s_lshl_b64 s[2:3], s[28:29], 19
	s_add_u32 s8, s20, s2
	s_addc_u32 s9, s21, s3
	s_ashr_i32 s31, s30, 31
	v_mov_b32_e32 v0, v184
	s_lshl_b64 s[10:11], s[30:31], 19
	s_add_u32 s12, s46, s10
	v_ashrrev_i32_e32 v1, 6, v0
	v_bfe_u32 v2, v0, 3, 3
	v_bitop3_b32 v4, v2, v0, 7 bitop3:0x78
	v_readfirstlane_b32 s4, v1
	s_addc_u32 s13, s47, s11
	v_lshlrev_b32_e32 v4, 4, v4
	s_lshl_b32 s7, s4, 2
	s_lshl_b32 s5, s4, 16
	v_lshlrev_b32_e32 v2, 11, v2
	s_lshl_b32 s4, s4, 12
	s_waitcnt lgkmcnt(0)
	s_barrier
	v_or3_b32 v128, v2, s5, v4
	s_mov_b32 m0, s4
	s_or_b32 s5, s7, 1
	global_load_lds_dwordx4 v128, s[8:9]
	s_add_i32 m0, s4, 0x8000
	s_lshl_b32 s6, s5, 14
	s_lshl_b32 s5, s5, 10
	global_load_lds_dwordx4 v128, s[12:13]
	v_or3_b32 v5, s6, v2, v4
	s_mov_b32 m0, s5
	s_or_b32 s6, s7, 2
	global_load_lds_dwordx4 v5, s[8:9]
	s_add_i32 m0, s5, 0x8000
	s_lshl_b32 s14, s6, 14
	s_lshl_b32 s6, s6, 10
	global_load_lds_dwordx4 v5, s[12:13]
	v_or3_b32 v5, s14, v2, v4
	s_mov_b32 m0, s6
	s_or_b32 s7, s7, 3
	global_load_lds_dwordx4 v5, s[8:9]
	s_add_i32 m0, s6, 0x8000
	s_lshl_b32 s14, s7, 14
	s_lshl_b32 s7, s7, 10
	global_load_lds_dwordx4 v5, s[12:13]
	v_or3_b32 v2, s14, v2, v4
	s_mov_b32 m0, s7
	v_and_b32_e32 v3, 7, v0
	global_load_lds_dwordx4 v2, s[8:9]
	s_add_i32 m0, s7, 0x8000
	v_lshlrev_b32_e32 v1, 13, v1
	global_load_lds_dwordx4 v2, s[12:13]
	v_bfe_u32 v2, v0, 4, 2
	v_bitop3_b32 v4, v2, v0, 7 bitop3:0x78
	v_lshlrev_b32_e32 v149, 4, v4
	v_lshlrev_b32_e32 v4, 7, v0
	v_and_b32_e32 v4, 0x780, v4
	v_lshlrev_b32_e32 v0, 6, v0
	v_and_or_b32 v146, v0, s51, v4
	v_bitop3_b32 v0, v2, v3, 4 bitop3:0x36
	s_add_u32 s2, s44, s2
	s_waitcnt vmcnt(0)
	v_and_or_b32 v147, v1, s50, v4
	v_lshlrev_b32_e32 v148, 4, v0
	s_addc_u32 s3, s45, s3
	v_or_b32_e32 v0, 0x4000, v128
	v_mov_b32_e32 v1, v129
	v_or_b32_e32 v2, 0x8000, v128
	v_mov_b32_e32 v3, v129
	v_or_b32_e32 v4, 0xc000, v128
	v_mov_b32_e32 v5, v129
	s_waitcnt lgkmcnt(0)
	s_barrier
	v_lshl_add_u64 v[130:131], s[2:3], 0, v[128:129]
	v_lshl_add_u64 v[132:133], s[2:3], 0, v[0:1]
	v_lshl_add_u64 v[134:135], s[2:3], 0, v[2:3]
	v_lshl_add_u64 v[136:137], s[2:3], 0, v[4:5]
	s_add_u32 s2, s48, s10
	s_addc_u32 s3, s49, s11
	v_lshl_add_u64 v[138:139], s[2:3], 0, v[128:129]
	v_lshl_add_u64 v[140:141], s[2:3], 0, v[0:1]
	v_lshl_add_u64 v[142:143], s[2:3], 0, v[2:3]
	v_lshl_add_u64 v[144:145], s[2:3], 0, v[4:5]
	s_mov_b64 s[2:3], 0
	s_mov_b32 s8, 0
.LBB0_124:
	s_waitcnt lgkmcnt(0)
	s_mov_b32 s99, 0x10000
	s_mov_b32 s100, 0x80
	s_mov_b32 s101, 0
	s_add_i32 m0, s4, 0x10000
	s_nop 0
	global_load_lds_dwordx4 v[130:131], off
	v_lshl_add_u64 v[130:131], v[130:131], 0, s[100:101]
	s_add_i32 m0, s4, 0x18000
	s_nop 0
	global_load_lds_dwordx4 v[138:139], off
	v_lshl_add_u64 v[138:139], v[138:139], 0, s[100:101]
	s_add_i32 m0, s5, 0x10000
	s_nop 0
	global_load_lds_dwordx4 v[132:133], off
	v_lshl_add_u64 v[132:133], v[132:133], 0, s[100:101]
	s_add_i32 m0, s5, 0x18000
	s_nop 0
	global_load_lds_dwordx4 v[140:141], off
	v_lshl_add_u64 v[140:141], v[140:141], 0, s[100:101]
	s_add_i32 m0, s6, 0x10000
	s_nop 0
	global_load_lds_dwordx4 v[134:135], off
	v_lshl_add_u64 v[134:135], v[134:135], 0, s[100:101]
	s_add_i32 m0, s6, 0x18000
	s_nop 0
	global_load_lds_dwordx4 v[142:143], off
	v_lshl_add_u64 v[142:143], v[142:143], 0, s[100:101]
	s_add_i32 m0, s7, 0x10000
	s_nop 0
	global_load_lds_dwordx4 v[136:137], off
	v_lshl_add_u64 v[136:137], v[136:137], 0, s[100:101]
	s_add_i32 m0, s7, 0x18000
	s_nop 0
	global_load_lds_dwordx4 v[144:145], off
	v_lshl_add_u64 v[144:145], v[144:145], 0, s[100:101]
	v_add_u32_e32 v162, v149, v147
	v_add_u32_e32 v128, v149, v146
	ds_read_b128 v[150:153], v162 offset:32768
	ds_read_b128 v[154:157], v162 offset:34816
	ds_read_b128 v[158:161], v162 offset:36864
	ds_read_b128 v[162:165], v162 offset:38912
	ds_read_b128 v[166:169], v128 offset:0
	ds_read_b128 v[170:173], v128 offset:2048
	ds_read_b128 v[174:177], v128 offset:4096
	ds_read_b128 v[180:183], v128 offset:6144
	ds_read_b128 v[186:189], v128 offset:8192
	ds_read_b128 v[190:193], v128 offset:10240
	ds_read_b128 v[194:197], v128 offset:12288
	ds_read_b128 v[198:201], v128 offset:14336
	s_waitcnt lgkmcnt(4)
	v_mfma_f32_16x16x32_bf16 v[124:127], v[166:169], v[150:153], 0
	v_mfma_f32_16x16x32_bf16 v[120:123], v[166:169], v[154:157], 0
	v_mfma_f32_16x16x32_bf16 v[116:119], v[166:169], v[158:161], 0
	v_mfma_f32_16x16x32_bf16 v[112:115], v[166:169], v[162:165], 0
	v_mfma_f32_16x16x32_bf16 v[108:111], v[170:173], v[150:153], 0
	v_mfma_f32_16x16x32_bf16 v[104:107], v[170:173], v[154:157], 0
	v_mfma_f32_16x16x32_bf16 v[100:103], v[170:173], v[158:161], 0
	v_mfma_f32_16x16x32_bf16 v[96:99], v[170:173], v[162:165], 0
	v_mfma_f32_16x16x32_bf16 v[92:95], v[174:177], v[150:153], 0
	v_mfma_f32_16x16x32_bf16 v[84:87], v[174:177], v[154:157], 0
	v_mfma_f32_16x16x32_bf16 v[80:83], v[174:177], v[158:161], 0
	v_mfma_f32_16x16x32_bf16 v[76:79], v[174:177], v[162:165], 0
	v_mfma_f32_16x16x32_bf16 v[72:75], v[180:183], v[150:153], 0
	v_mfma_f32_16x16x32_bf16 v[68:71], v[180:183], v[154:157], 0
	v_mfma_f32_16x16x32_bf16 v[64:67], v[180:183], v[158:161], 0
	v_mfma_f32_16x16x32_bf16 v[60:63], v[180:183], v[162:165], 0
	v_add_u32_e32 v180, v148, v147
	v_add_u32_e32 v128, v148, v146
	ds_read_b128 v[166:169], v180 offset:32768
	ds_read_b128 v[170:173], v180 offset:34816
	ds_read_b128 v[174:177], v180 offset:36864
	ds_read_b128 v[180:183], v180 offset:38912
	ds_read_b128 v[202:205], v128 offset:0
	ds_read_b128 v[206:209], v128 offset:2048
	ds_read_b128 v[210:213], v128 offset:4096
	ds_read_b128 v[214:217], v128 offset:6144
	s_waitcnt lgkmcnt(8)
	v_mfma_f32_16x16x32_bf16 v[56:59], v[186:189], v[150:153], 0
	v_mfma_f32_16x16x32_bf16 v[52:55], v[186:189], v[154:157], 0
	v_mfma_f32_16x16x32_bf16 v[48:51], v[186:189], v[158:161], 0
	v_mfma_f32_16x16x32_bf16 v[44:47], v[186:189], v[162:165], 0
	v_mfma_f32_16x16x32_bf16 v[40:43], v[190:193], v[150:153], 0
	v_mfma_f32_16x16x32_bf16 v[36:39], v[190:193], v[154:157], 0
	v_mfma_f32_16x16x32_bf16 v[32:35], v[190:193], v[158:161], 0
	v_mfma_f32_16x16x32_bf16 v[28:31], v[190:193], v[162:165], 0
	v_mfma_f32_16x16x32_bf16 v[24:27], v[194:197], v[150:153], 0
	v_mfma_f32_16x16x32_bf16 v[20:23], v[194:197], v[154:157], 0
	v_mfma_f32_16x16x32_bf16 v[16:19], v[194:197], v[158:161], 0
	v_mfma_f32_16x16x32_bf16 v[12:15], v[194:197], v[162:165], 0
	v_mfma_f32_16x16x32_bf16 v[8:11], v[198:201], v[150:153], 0
	v_mfma_f32_16x16x32_bf16 v[4:7], v[198:201], v[154:157], 0
	v_mfma_f32_16x16x32_bf16 v[0:3], v[198:201], v[158:161], 0
	v_mfma_f32_16x16x32_bf16 v[88:91], v[198:201], v[162:165], 0
	ds_read_b128 v[150:153], v128 offset:8192
	ds_read_b128 v[154:157], v128 offset:10240
	ds_read_b128 v[158:161], v128 offset:12288
	ds_read_b128 v[162:165], v128 offset:14336
	s_waitcnt lgkmcnt(4)
	v_mfma_f32_16x16x32_bf16 v[124:127], v[202:205], v[166:169], v[124:127]
	v_mfma_f32_16x16x32_bf16 v[120:123], v[202:205], v[170:173], v[120:123]
	v_mfma_f32_16x16x32_bf16 v[116:119], v[202:205], v[174:177], v[116:119]
	v_mfma_f32_16x16x32_bf16 v[112:115], v[202:205], v[180:183], v[112:115]
	v_mfma_f32_16x16x32_bf16 v[108:111], v[206:209], v[166:169], v[108:111]
	v_mfma_f32_16x16x32_bf16 v[104:107], v[206:209], v[170:173], v[104:107]
	v_mfma_f32_16x16x32_bf16 v[100:103], v[206:209], v[174:177], v[100:103]
	v_mfma_f32_16x16x32_bf16 v[96:99], v[206:209], v[180:183], v[96:99]
	v_mfma_f32_16x16x32_bf16 v[92:95], v[210:213], v[166:169], v[92:95]
	v_mfma_f32_16x16x32_bf16 v[84:87], v[210:213], v[170:173], v[84:87]
	v_mfma_f32_16x16x32_bf16 v[80:83], v[210:213], v[174:177], v[80:83]
	v_mfma_f32_16x16x32_bf16 v[76:79], v[210:213], v[180:183], v[76:79]
	v_mfma_f32_16x16x32_bf16 v[72:75], v[214:217], v[166:169], v[72:75]
	v_mfma_f32_16x16x32_bf16 v[68:71], v[214:217], v[170:173], v[68:71]
	v_mfma_f32_16x16x32_bf16 v[64:67], v[214:217], v[174:177], v[64:67]
	v_mfma_f32_16x16x32_bf16 v[60:63], v[214:217], v[180:183], v[60:63]
	s_waitcnt lgkmcnt(0)
	v_mfma_f32_16x16x32_bf16 v[56:59], v[150:153], v[166:169], v[56:59]
	s_waitcnt vmcnt(0)
	s_barrier
	v_add3_u32 v198, v149, v147, s99
	v_add3_u32 v128, v149, v146, s99
	v_mfma_f32_16x16x32_bf16 v[52:55], v[150:153], v[170:173], v[52:55]
	ds_read_b128 v[186:189], v198 offset:32768
	ds_read_b128 v[190:193], v198 offset:34816
	v_mfma_f32_16x16x32_bf16 v[48:51], v[150:153], v[174:177], v[48:51]
	ds_read_b128 v[194:197], v198 offset:36864
	ds_read_b128 v[198:201], v198 offset:38912
	v_mfma_f32_16x16x32_bf16 v[44:47], v[150:153], v[180:183], v[44:47]
	ds_read_b128 v[202:205], v128 offset:0
	ds_read_b128 v[206:209], v128 offset:2048
	v_mfma_f32_16x16x32_bf16 v[40:43], v[154:157], v[166:169], v[40:43]
	ds_read_b128 v[210:213], v128 offset:4096
	ds_read_b128 v[214:217], v128 offset:6144
	s_mov_b32 m0, s4
	v_mfma_f32_16x16x32_bf16 v[36:39], v[154:157], v[170:173], v[36:39]
	global_load_lds_dwordx4 v[130:131], off
	v_lshl_add_u64 v[130:131], v[130:131], 0, s[100:101]
	s_add_i32 m0, s4, 0x8000
	v_mfma_f32_16x16x32_bf16 v[32:35], v[154:157], v[174:177], v[32:35]
	global_load_lds_dwordx4 v[138:139], off
	v_lshl_add_u64 v[138:139], v[138:139], 0, s[100:101]
	s_mov_b32 m0, s5
	v_mfma_f32_16x16x32_bf16 v[28:31], v[154:157], v[180:183], v[28:31]
	global_load_lds_dwordx4 v[132:133], off
	v_lshl_add_u64 v[132:133], v[132:133], 0, s[100:101]
	s_add_i32 m0, s5, 0x8000
	v_mfma_f32_16x16x32_bf16 v[24:27], v[158:161], v[166:169], v[24:27]
	global_load_lds_dwordx4 v[140:141], off
	v_lshl_add_u64 v[140:141], v[140:141], 0, s[100:101]
	s_mov_b32 m0, s6
	v_mfma_f32_16x16x32_bf16 v[20:23], v[158:161], v[170:173], v[20:23]
	global_load_lds_dwordx4 v[134:135], off
	v_lshl_add_u64 v[134:135], v[134:135], 0, s[100:101]
	s_add_i32 m0, s6, 0x8000
	v_mfma_f32_16x16x32_bf16 v[16:19], v[158:161], v[174:177], v[16:19]
	global_load_lds_dwordx4 v[142:143], off
	v_lshl_add_u64 v[142:143], v[142:143], 0, s[100:101]
	s_mov_b32 m0, s7
	v_mfma_f32_16x16x32_bf16 v[12:15], v[158:161], v[180:183], v[12:15]
	global_load_lds_dwordx4 v[136:137], off
	v_lshl_add_u64 v[136:137], v[136:137], 0, s[100:101]
	s_add_i32 m0, s7, 0x8000
	v_mfma_f32_16x16x32_bf16 v[8:11], v[162:165], v[166:169], v[8:11]
	global_load_lds_dwordx4 v[144:145], off
	v_lshl_add_u64 v[144:145], v[144:145], 0, s[100:101]
	v_mfma_f32_16x16x32_bf16 v[4:7], v[162:165], v[170:173], v[4:7]
	v_mfma_f32_16x16x32_bf16 v[0:3], v[162:165], v[174:177], v[0:3]
	v_mfma_f32_16x16x32_bf16 v[88:91], v[162:165], v[180:183], v[88:91]
	ds_read_b128 v[150:153], v128 offset:8192
	ds_read_b128 v[154:157], v128 offset:10240
	ds_read_b128 v[158:161], v128 offset:12288
	ds_read_b128 v[162:165], v128 offset:14336
	s_waitcnt lgkmcnt(4)
	v_mfma_f32_16x16x32_bf16 v[124:127], v[202:205], v[186:189], v[124:127]
	v_mfma_f32_16x16x32_bf16 v[120:123], v[202:205], v[190:193], v[120:123]
	v_mfma_f32_16x16x32_bf16 v[116:119], v[202:205], v[194:197], v[116:119]
	v_mfma_f32_16x16x32_bf16 v[112:115], v[202:205], v[198:201], v[112:115]
	v_mfma_f32_16x16x32_bf16 v[108:111], v[206:209], v[186:189], v[108:111]
	v_mfma_f32_16x16x32_bf16 v[104:107], v[206:209], v[190:193], v[104:107]
	v_mfma_f32_16x16x32_bf16 v[100:103], v[206:209], v[194:197], v[100:103]
	v_mfma_f32_16x16x32_bf16 v[96:99], v[206:209], v[198:201], v[96:99]
	v_mfma_f32_16x16x32_bf16 v[92:95], v[210:213], v[186:189], v[92:95]
	v_mfma_f32_16x16x32_bf16 v[84:87], v[210:213], v[190:193], v[84:87]
	v_mfma_f32_16x16x32_bf16 v[80:83], v[210:213], v[194:197], v[80:83]
	v_mfma_f32_16x16x32_bf16 v[76:79], v[210:213], v[198:201], v[76:79]
	v_mfma_f32_16x16x32_bf16 v[72:75], v[214:217], v[186:189], v[72:75]
	v_mfma_f32_16x16x32_bf16 v[68:71], v[214:217], v[190:193], v[68:71]
	v_mfma_f32_16x16x32_bf16 v[64:67], v[214:217], v[194:197], v[64:67]
	v_mfma_f32_16x16x32_bf16 v[60:63], v[214:217], v[198:201], v[60:63]
	v_add3_u32 v214, v148, v147, s99
	v_add3_u32 v128, v148, v146, s99
	ds_read_b128 v[202:205], v214 offset:32768
	ds_read_b128 v[206:209], v214 offset:34816
	ds_read_b128 v[210:213], v214 offset:36864
	ds_read_b128 v[214:217], v214 offset:38912
	ds_read_b128 v[166:169], v128 offset:0
	ds_read_b128 v[170:173], v128 offset:2048
	ds_read_b128 v[174:177], v128 offset:4096
	ds_read_b128 v[180:183], v128 offset:6144
	s_waitcnt lgkmcnt(8)
	v_mfma_f32_16x16x32_bf16 v[56:59], v[150:153], v[186:189], v[56:59]
	v_mfma_f32_16x16x32_bf16 v[52:55], v[150:153], v[190:193], v[52:55]
	v_mfma_f32_16x16x32_bf16 v[48:51], v[150:153], v[194:197], v[48:51]
	v_mfma_f32_16x16x32_bf16 v[44:47], v[150:153], v[198:201], v[44:47]
	v_mfma_f32_16x16x32_bf16 v[40:43], v[154:157], v[186:189], v[40:43]
	v_mfma_f32_16x16x32_bf16 v[36:39], v[154:157], v[190:193], v[36:39]
	v_mfma_f32_16x16x32_bf16 v[32:35], v[154:157], v[194:197], v[32:35]
	v_mfma_f32_16x16x32_bf16 v[28:31], v[154:157], v[198:201], v[28:31]
	v_mfma_f32_16x16x32_bf16 v[24:27], v[158:161], v[186:189], v[24:27]
	v_mfma_f32_16x16x32_bf16 v[20:23], v[158:161], v[190:193], v[20:23]
	v_mfma_f32_16x16x32_bf16 v[16:19], v[158:161], v[194:197], v[16:19]
	v_mfma_f32_16x16x32_bf16 v[12:15], v[158:161], v[198:201], v[12:15]
	v_mfma_f32_16x16x32_bf16 v[8:11], v[162:165], v[186:189], v[8:11]
	v_mfma_f32_16x16x32_bf16 v[4:7], v[162:165], v[190:193], v[4:7]
	v_mfma_f32_16x16x32_bf16 v[0:3], v[162:165], v[194:197], v[0:3]
	v_mfma_f32_16x16x32_bf16 v[88:91], v[162:165], v[198:201], v[88:91]
	ds_read_b128 v[186:189], v128 offset:8192
	ds_read_b128 v[190:193], v128 offset:10240
	ds_read_b128 v[194:197], v128 offset:12288
	ds_read_b128 v[198:201], v128 offset:14336
	s_waitcnt lgkmcnt(4)
	v_mfma_f32_16x16x32_bf16 v[124:127], v[166:169], v[202:205], v[124:127]
	v_mfma_f32_16x16x32_bf16 v[120:123], v[166:169], v[206:209], v[120:123]
	v_mfma_f32_16x16x32_bf16 v[116:119], v[166:169], v[210:213], v[116:119]
	v_mfma_f32_16x16x32_bf16 v[112:115], v[166:169], v[214:217], v[112:115]
	v_mfma_f32_16x16x32_bf16 v[108:111], v[170:173], v[202:205], v[108:111]
	v_mfma_f32_16x16x32_bf16 v[104:107], v[170:173], v[206:209], v[104:107]
	v_mfma_f32_16x16x32_bf16 v[100:103], v[170:173], v[210:213], v[100:103]
	v_mfma_f32_16x16x32_bf16 v[96:99], v[170:173], v[214:217], v[96:99]
	v_mfma_f32_16x16x32_bf16 v[92:95], v[174:177], v[202:205], v[92:95]
	v_mfma_f32_16x16x32_bf16 v[84:87], v[174:177], v[206:209], v[84:87]
	v_mfma_f32_16x16x32_bf16 v[80:83], v[174:177], v[210:213], v[80:83]
	v_mfma_f32_16x16x32_bf16 v[76:79], v[174:177], v[214:217], v[76:79]
	v_mfma_f32_16x16x32_bf16 v[72:75], v[180:183], v[202:205], v[72:75]
	v_mfma_f32_16x16x32_bf16 v[68:71], v[180:183], v[206:209], v[68:71]
	v_mfma_f32_16x16x32_bf16 v[64:67], v[180:183], v[210:213], v[64:67]
	v_mfma_f32_16x16x32_bf16 v[60:63], v[180:183], v[214:217], v[60:63]
	s_waitcnt lgkmcnt(0)
	v_mfma_f32_16x16x32_bf16 v[56:59], v[186:189], v[202:205], v[56:59]
	s_waitcnt vmcnt(0)
	s_barrier
	v_add_u32_e32 v162, v149, v147
	v_add_u32_e32 v128, v149, v146
	v_mfma_f32_16x16x32_bf16 v[52:55], v[186:189], v[206:209], v[52:55]
	ds_read_b128 v[150:153], v162 offset:32768
	ds_read_b128 v[154:157], v162 offset:34816
	v_mfma_f32_16x16x32_bf16 v[48:51], v[186:189], v[210:213], v[48:51]
	ds_read_b128 v[158:161], v162 offset:36864
	ds_read_b128 v[162:165], v162 offset:38912
	v_mfma_f32_16x16x32_bf16 v[44:47], v[186:189], v[214:217], v[44:47]
	ds_read_b128 v[166:169], v128 offset:0
	ds_read_b128 v[170:173], v128 offset:2048
	v_mfma_f32_16x16x32_bf16 v[40:43], v[190:193], v[202:205], v[40:43]
	ds_read_b128 v[174:177], v128 offset:4096
	ds_read_b128 v[180:183], v128 offset:6144
	s_add_i32 m0, s4, 0x10000
	v_mfma_f32_16x16x32_bf16 v[36:39], v[190:193], v[206:209], v[36:39]
	global_load_lds_dwordx4 v[130:131], off
	v_lshl_add_u64 v[130:131], v[130:131], 0, s[100:101]
	s_add_i32 m0, s4, 0x18000
	v_mfma_f32_16x16x32_bf16 v[32:35], v[190:193], v[210:213], v[32:35]
	global_load_lds_dwordx4 v[138:139], off
	v_lshl_add_u64 v[138:139], v[138:139], 0, s[100:101]
	s_add_i32 m0, s5, 0x10000
	v_mfma_f32_16x16x32_bf16 v[28:31], v[190:193], v[214:217], v[28:31]
	global_load_lds_dwordx4 v[132:133], off
	v_lshl_add_u64 v[132:133], v[132:133], 0, s[100:101]
	s_add_i32 m0, s5, 0x18000
	v_mfma_f32_16x16x32_bf16 v[24:27], v[194:197], v[202:205], v[24:27]
	global_load_lds_dwordx4 v[140:141], off
	v_lshl_add_u64 v[140:141], v[140:141], 0, s[100:101]
	s_add_i32 m0, s6, 0x10000
	v_mfma_f32_16x16x32_bf16 v[20:23], v[194:197], v[206:209], v[20:23]
	global_load_lds_dwordx4 v[134:135], off
	v_lshl_add_u64 v[134:135], v[134:135], 0, s[100:101]
	s_add_i32 m0, s6, 0x18000
	v_mfma_f32_16x16x32_bf16 v[16:19], v[194:197], v[210:213], v[16:19]
	global_load_lds_dwordx4 v[142:143], off
	v_lshl_add_u64 v[142:143], v[142:143], 0, s[100:101]
	s_add_i32 m0, s7, 0x10000
	v_mfma_f32_16x16x32_bf16 v[12:15], v[194:197], v[214:217], v[12:15]
	global_load_lds_dwordx4 v[136:137], off
	v_lshl_add_u64 v[136:137], v[136:137], 0, s[100:101]
	s_add_i32 m0, s7, 0x18000
	v_mfma_f32_16x16x32_bf16 v[8:11], v[198:201], v[202:205], v[8:11]
	global_load_lds_dwordx4 v[144:145], off
	v_lshl_add_u64 v[144:145], v[144:145], 0, s[100:101]
	v_mfma_f32_16x16x32_bf16 v[4:7], v[198:201], v[206:209], v[4:7]
	v_mfma_f32_16x16x32_bf16 v[0:3], v[198:201], v[210:213], v[0:3]
	v_mfma_f32_16x16x32_bf16 v[88:91], v[198:201], v[214:217], v[88:91]
	s_movk_i32 s2, 0x100

.LBB0_2295:
	s_or_b64 exec, exec, s[2:3]
	s_mov_b64 s[2:3], s[0:1]
	s_barrier
	s_mov_b32 s32, 0
	s_load_dwordx2 s[4:5], s[2:3], 0xc0
	s_load_dwordx8 s[8:15], s[2:3], 0x98
	s_lshl_b64 s[18:19], s[86:87], 12
	v_readlane_b32 s2, v255, 7
	v_readlane_b32 s3, v255, 8
	s_waitcnt lgkmcnt(0)
	s_add_u32 s20, s4, 0xe400000
	s_addc_u32 s21, s5, 0
	s_andn2_b64 vcc, exec, s[2:3]
	s_cbranch_vccnz .LBB0_2312
	s_mul_i32 s2, s86, 0xb00000
	s_add_u32 s28, s20, s2
	s_addc_u32 s29, s21, 0
	s_add_u32 s22, s4, 0x14800000
	s_addc_u32 s23, s5, 0
	s_mul_i32 s3, s86, 0x8400
	s_add_u32 s10, s10, s3
	s_addc_u32 s11, s11, 0
	s_mul_i32 s3, s86, 0x2c00
	s_add_u32 s12, s12, s3
	s_addc_u32 s13, s13, 0
	s_add_u32 s24, s4, 0x2400000
	s_addc_u32 s25, s5, 0
	s_add_u32 s2, s4, s2
	s_addc_u32 s3, s5, 0
	s_add_u32 s31, s2, 0xe400080
	s_addc_u32 s87, s3, 0
	s_add_u32 s26, s4, 0x2400080
	s_addc_u32 s27, s5, 0
	v_readlane_b32 s2, v255, 6
	v_readlane_b32 s90, v255, 2
	s_branch .LBB0_2298

.LBB0_2303:
	s_cmp_lt_i32 s44, 0
	s_cbranch_scc1 .LBB0_2297
	v_mov_b32_e32 v6, v184
	s_mul_i32 s36, s91, 0xfe
	s_add_i32 s92, s36, -1
	v_ashrrev_i32_e32 v7, 6, v6
	v_bfe_u32 v8, v6, 3, 3
	s_lshl_b64 s[2:3], s[44:45], 19
	v_bitop3_b32 v0, v8, v6, 7 bitop3:0x78
	v_readfirstlane_b32 s37, v7
	s_add_u32 vcc_lo, s28, s2
	v_lshlrev_b32_e32 v10, 4, v0
	v_lshl_or_b32 v0, s37, 5, v8
	s_addc_u32 vcc_hi, s29, s3
	s_lshl_b32 s96, s37, 2
	v_lshl_or_b32 v1, v0, 11, v10
	v_add_u32_e32 v0, s92, v0
	s_lshl_b32 s93, s37, 12
	v_med3_i32 v0, v0, 0, v192
	s_or_b32 s94, s96, 1
	s_waitcnt lgkmcnt(0)
	s_barrier
	s_mov_b32 m0, s93
	v_lshl_or_b32 v134, v0, 11, v10
	v_lshl_or_b32 v0, s94, 3, v8
	global_load_lds_dwordx4 v1, vcc
	s_add_i32 m0, s93, 0x8000
	v_lshl_or_b32 v1, v0, 11, v10
	s_lshl_b32 s94, s94, 10
	v_add_u32_e32 v0, s92, v0
	s_or_b32 s95, s96, 2
	global_load_lds_dwordx4 v134, s[24:25]
	s_mov_b32 m0, s94
	v_med3_i32 v0, v0, 0, v192
	v_lshl_or_b32 v2, s95, 3, v8
	global_load_lds_dwordx4 v1, vcc
	v_lshl_or_b32 v0, v0, 11, v10
	s_add_i32 m0, s94, 0x8000
	v_lshl_or_b32 v3, v2, 11, v10
	s_lshl_b32 s95, s95, 10
	v_add_u32_e32 v2, s92, v2
	s_or_b32 s96, s96, 3
	global_load_lds_dwordx4 v0, s[24:25]
	s_mov_b32 m0, s95
	v_med3_i32 v2, v2, 0, v192
	v_lshl_or_b32 v4, s96, 3, v8
	global_load_lds_dwordx4 v3, vcc
	v_lshl_or_b32 v2, v2, 11, v10
	s_add_i32 m0, s95, 0x8000
	v_lshl_or_b32 v5, v4, 11, v10
	s_lshl_b32 s96, s96, 10
	v_add_u32_e32 v4, s92, v4
	global_load_lds_dwordx4 v2, s[24:25]
	s_mov_b32 m0, s96
	v_med3_i32 v4, v4, 0, v192
	global_load_lds_dwordx4 v5, vcc
	v_lshl_or_b32 v4, v4, 11, v10
	s_add_i32 m0, s96, 0x8000
	v_bfe_u32 v11, v6, 4, 2
	global_load_lds_dwordx4 v4, s[24:25]
	v_bitop3_b32 v12, v11, v6, 7 bitop3:0x78
	v_lshlrev_b32_e32 v151, 4, v12
	v_lshlrev_b32_e32 v12, 7, v6
	v_and_b32_e32 v9, 7, v6
	v_and_b32_e32 v12, 0x780, v12
	v_lshlrev_b32_e32 v6, 6, v6
	v_and_or_b32 v148, v6, s85, v12
	v_bitop3_b32 v6, v11, v9, 4 bitop3:0x36
	v_lshlrev_b32_e32 v149, 4, v6
	s_lshl_b32 s37, s37, 16
	v_lshlrev_b32_e32 v6, 11, v8
	s_cmp_eq_u32 s32, 0
	s_cbranch_scc1 .Lup_nopend
	s_branch .Lup_rows
.Lup_rows_ret1:
	s_waitcnt vmcnt(8)
	s_branch .Lup_after_wait

.Lup_after_wait:
	v_lshlrev_b32_e32 v7, 13, v7
	v_or3_b32 v6, v6, s37, v10
	s_add_u32 s2, s31, s2
	s_waitcnt lgkmcnt(0)
	s_barrier
	v_and_or_b32 v150, v7, s83, v12
	v_mov_b32_e32 v7, v135
	s_addc_u32 s3, s87, s3
	v_or_b32_e32 v8, 0x4000, v6
	v_mov_b32_e32 v9, v135
	v_mov_b32_e32 v1, v135
	v_mov_b32_e32 v3, v135
	v_mov_b32_e32 v5, v135
	v_lshl_add_u64 v[128:129], s[2:3], 0, v[6:7]
	v_lshl_add_u64 v[130:131], s[2:3], 0, v[8:9]
	v_or_b32_e32 v8, 0x8000, v6
	v_or_b32_e32 v6, 0xc000, v6
	s_mov_b32 s97, 0
	v_lshl_add_u64 v[136:137], s[2:3], 0, v[8:9]
	v_lshl_add_u64 v[138:139], s[2:3], 0, v[6:7]
	v_lshl_add_u64 v[140:141], s[26:27], 0, v[134:135]
	v_lshl_add_u64 v[142:143], s[26:27], 0, v[0:1]
	v_lshl_add_u64 v[144:145], s[26:27], 0, v[2:3]
	v_lshl_add_u64 v[146:147], s[26:27], 0, v[4:5]
	s_mov_b64 s[2:3], 0
.LBB0_2305:
	s_waitcnt lgkmcnt(0)
	s_mov_b32 s99, 0x10000
	s_mov_b32 s100, 0x80
	s_mov_b32 s101, 0
	s_add_i32 m0, s93, 0x10000
	s_nop 0
	global_load_lds_dwordx4 v[128:129], off
	v_lshl_add_u64 v[128:129], v[128:129], 0, s[100:101]
	s_add_i32 m0, s93, 0x18000
	s_nop 0
	global_load_lds_dwordx4 v[140:141], off
	v_lshl_add_u64 v[140:141], v[140:141], 0, s[100:101]
	s_add_i32 m0, s94, 0x10000
	s_nop 0
	global_load_lds_dwordx4 v[130:131], off
	v_lshl_add_u64 v[130:131], v[130:131], 0, s[100:101]
	s_add_i32 m0, s94, 0x18000
	s_nop 0
	global_load_lds_dwordx4 v[142:143], off
	v_lshl_add_u64 v[142:143], v[142:143], 0, s[100:101]
	s_add_i32 m0, s95, 0x10000
	s_nop 0
	global_load_lds_dwordx4 v[136:137], off
	v_lshl_add_u64 v[136:137], v[136:137], 0, s[100:101]
	s_add_i32 m0, s95, 0x18000
	s_nop 0
	global_load_lds_dwordx4 v[144:145], off
	v_lshl_add_u64 v[144:145], v[144:145], 0, s[100:101]
	s_add_i32 m0, s96, 0x10000
	s_nop 0
	global_load_lds_dwordx4 v[138:139], off
	v_lshl_add_u64 v[138:139], v[138:139], 0, s[100:101]
	s_add_i32 m0, s96, 0x18000
	s_nop 0
	global_load_lds_dwordx4 v[146:147], off
	v_lshl_add_u64 v[146:147], v[146:147], 0, s[100:101]
	v_add_u32_e32 v164, v151, v150
	v_add_u32_e32 v134, v151, v148
	ds_read_b128 v[152:155], v164 offset:32768
	ds_read_b128 v[156:159], v164 offset:34816
	ds_read_b128 v[160:163], v164 offset:36864
	ds_read_b128 v[164:167], v164 offset:38912
	ds_read_b128 v[168:171], v134 offset:0
	ds_read_b128 v[172:175], v134 offset:2048
	ds_read_b128 v[176:179], v134 offset:4096
	ds_read_b128 v[180:183], v134 offset:6144
	ds_read_b128 v[198:201], v134 offset:8192
	ds_read_b128 v[202:205], v134 offset:10240
	ds_read_b128 v[206:209], v134 offset:12288
	ds_read_b128 v[210:213], v134 offset:14336
	s_waitcnt lgkmcnt(4)
	v_mfma_f32_16x16x32_bf16 v[124:127], v[168:171], v[152:155], 0
	v_mfma_f32_16x16x32_bf16 v[120:123], v[168:171], v[156:159], 0
	v_mfma_f32_16x16x32_bf16 v[116:119], v[168:171], v[160:163], 0
	v_mfma_f32_16x16x32_bf16 v[112:115], v[168:171], v[164:167], 0
	v_mfma_f32_16x16x32_bf16 v[108:111], v[172:175], v[152:155], 0
	v_mfma_f32_16x16x32_bf16 v[104:107], v[172:175], v[156:159], 0
	v_mfma_f32_16x16x32_bf16 v[100:103], v[172:175], v[160:163], 0
	v_mfma_f32_16x16x32_bf16 v[96:99], v[172:175], v[164:167], 0
	v_mfma_f32_16x16x32_bf16 v[92:95], v[176:179], v[152:155], 0
	v_mfma_f32_16x16x32_bf16 v[84:87], v[176:179], v[156:159], 0
	v_mfma_f32_16x16x32_bf16 v[80:83], v[176:179], v[160:163], 0
	v_mfma_f32_16x16x32_bf16 v[76:79], v[176:179], v[164:167], 0
	v_mfma_f32_16x16x32_bf16 v[72:75], v[180:183], v[152:155], 0
	v_mfma_f32_16x16x32_bf16 v[68:71], v[180:183], v[156:159], 0
	v_mfma_f32_16x16x32_bf16 v[64:67], v[180:183], v[160:163], 0
	v_mfma_f32_16x16x32_bf16 v[60:63], v[180:183], v[164:167], 0
	v_add_u32_e32 v180, v149, v150
	v_add_u32_e32 v134, v149, v148
	ds_read_b128 v[168:171], v180 offset:32768
	ds_read_b128 v[172:175], v180 offset:34816
	ds_read_b128 v[176:179], v180 offset:36864
	ds_read_b128 v[180:183], v180 offset:38912
	ds_read_b128 v[214:217], v134 offset:0
	ds_read_b128 v[218:221], v134 offset:2048
	ds_read_b128 v[222:225], v134 offset:4096
	ds_read_b128 v[226:229], v134 offset:6144
	s_waitcnt lgkmcnt(8)
	v_mfma_f32_16x16x32_bf16 v[56:59], v[198:201], v[152:155], 0
	v_mfma_f32_16x16x32_bf16 v[52:55], v[198:201], v[156:159], 0
	v_mfma_f32_16x16x32_bf16 v[48:51], v[198:201], v[160:163], 0
	v_mfma_f32_16x16x32_bf16 v[44:47], v[198:201], v[164:167], 0
	v_mfma_f32_16x16x32_bf16 v[40:43], v[202:205], v[152:155], 0
	v_mfma_f32_16x16x32_bf16 v[36:39], v[202:205], v[156:159], 0
	v_mfma_f32_16x16x32_bf16 v[32:35], v[202:205], v[160:163], 0
	v_mfma_f32_16x16x32_bf16 v[28:31], v[202:205], v[164:167], 0
	v_mfma_f32_16x16x32_bf16 v[24:27], v[206:209], v[152:155], 0
	v_mfma_f32_16x16x32_bf16 v[20:23], v[206:209], v[156:159], 0
	v_mfma_f32_16x16x32_bf16 v[16:19], v[206:209], v[160:163], 0
	v_mfma_f32_16x16x32_bf16 v[12:15], v[206:209], v[164:167], 0
	v_mfma_f32_16x16x32_bf16 v[8:11], v[210:213], v[152:155], 0
	v_mfma_f32_16x16x32_bf16 v[4:7], v[210:213], v[156:159], 0
	v_mfma_f32_16x16x32_bf16 v[0:3], v[210:213], v[160:163], 0
	v_mfma_f32_16x16x32_bf16 v[88:91], v[210:213], v[164:167], 0
	ds_read_b128 v[152:155], v134 offset:8192
	ds_read_b128 v[156:159], v134 offset:10240
	ds_read_b128 v[160:163], v134 offset:12288
	ds_read_b128 v[164:167], v134 offset:14336
	s_waitcnt lgkmcnt(4)
	v_mfma_f32_16x16x32_bf16 v[124:127], v[214:217], v[168:171], v[124:127]
	v_mfma_f32_16x16x32_bf16 v[120:123], v[214:217], v[172:175], v[120:123]
	v_mfma_f32_16x16x32_bf16 v[116:119], v[214:217], v[176:179], v[116:119]
	v_mfma_f32_16x16x32_bf16 v[112:115], v[214:217], v[180:183], v[112:115]
	v_mfma_f32_16x16x32_bf16 v[108:111], v[218:221], v[168:171], v[108:111]
	v_mfma_f32_16x16x32_bf16 v[104:107], v[218:221], v[172:175], v[104:107]
	v_mfma_f32_16x16x32_bf16 v[100:103], v[218:221], v[176:179], v[100:103]
	v_mfma_f32_16x16x32_bf16 v[96:99], v[218:221], v[180:183], v[96:99]
	v_mfma_f32_16x16x32_bf16 v[92:95], v[222:225], v[168:171], v[92:95]
	v_mfma_f32_16x16x32_bf16 v[84:87], v[222:225], v[172:175], v[84:87]
	v_mfma_f32_16x16x32_bf16 v[80:83], v[222:225], v[176:179], v[80:83]
	v_mfma_f32_16x16x32_bf16 v[76:79], v[222:225], v[180:183], v[76:79]
	v_mfma_f32_16x16x32_bf16 v[72:75], v[226:229], v[168:171], v[72:75]
	v_mfma_f32_16x16x32_bf16 v[68:71], v[226:229], v[172:175], v[68:71]
	v_mfma_f32_16x16x32_bf16 v[64:67], v[226:229], v[176:179], v[64:67]
	v_mfma_f32_16x16x32_bf16 v[60:63], v[226:229], v[180:183], v[60:63]
	s_waitcnt lgkmcnt(0)
	v_mfma_f32_16x16x32_bf16 v[56:59], v[152:155], v[168:171], v[56:59]
	s_waitcnt vmcnt(0)
	s_barrier
	v_add3_u32 v210, v151, v150, s99
	v_add3_u32 v134, v151, v148, s99
	v_mfma_f32_16x16x32_bf16 v[52:55], v[152:155], v[172:175], v[52:55]
	ds_read_b128 v[198:201], v210 offset:32768
	ds_read_b128 v[202:205], v210 offset:34816
	v_mfma_f32_16x16x32_bf16 v[48:51], v[152:155], v[176:179], v[48:51]
	ds_read_b128 v[206:209], v210 offset:36864
	ds_read_b128 v[210:213], v210 offset:38912
	v_mfma_f32_16x16x32_bf16 v[44:47], v[152:155], v[180:183], v[44:47]
	ds_read_b128 v[214:217], v134 offset:0
	ds_read_b128 v[218:221], v134 offset:2048
	v_mfma_f32_16x16x32_bf16 v[40:43], v[156:159], v[168:171], v[40:43]
	ds_read_b128 v[222:225], v134 offset:4096
	ds_read_b128 v[226:229], v134 offset:6144
	s_mov_b32 m0, s93
	v_mfma_f32_16x16x32_bf16 v[36:39], v[156:159], v[172:175], v[36:39]
	global_load_lds_dwordx4 v[128:129], off
	v_lshl_add_u64 v[128:129], v[128:129], 0, s[100:101]
	s_add_i32 m0, s93, 0x8000
	v_mfma_f32_16x16x32_bf16 v[32:35], v[156:159], v[176:179], v[32:35]
	global_load_lds_dwordx4 v[140:141], off
	v_lshl_add_u64 v[140:141], v[140:141], 0, s[100:101]
	s_mov_b32 m0, s94
	v_mfma_f32_16x16x32_bf16 v[28:31], v[156:159], v[180:183], v[28:31]
	global_load_lds_dwordx4 v[130:131], off
	v_lshl_add_u64 v[130:131], v[130:131], 0, s[100:101]
	s_add_i32 m0, s94, 0x8000
	v_mfma_f32_16x16x32_bf16 v[24:27], v[160:163], v[168:171], v[24:27]
	global_load_lds_dwordx4 v[142:143], off
	v_lshl_add_u64 v[142:143], v[142:143], 0, s[100:101]
	s_mov_b32 m0, s95
	v_mfma_f32_16x16x32_bf16 v[20:23], v[160:163], v[172:175], v[20:23]
	global_load_lds_dwordx4 v[136:137], off
	v_lshl_add_u64 v[136:137], v[136:137], 0, s[100:101]
	s_add_i32 m0, s95, 0x8000
	v_mfma_f32_16x16x32_bf16 v[16:19], v[160:163], v[176:179], v[16:19]
	global_load_lds_dwordx4 v[144:145], off
	v_lshl_add_u64 v[144:145], v[144:145], 0, s[100:101]
	s_mov_b32 m0, s96
	v_mfma_f32_16x16x32_bf16 v[12:15], v[160:163], v[180:183], v[12:15]
	global_load_lds_dwordx4 v[138:139], off
	v_lshl_add_u64 v[138:139], v[138:139], 0, s[100:101]
	s_add_i32 m0, s96, 0x8000
	v_mfma_f32_16x16x32_bf16 v[8:11], v[164:167], v[168:171], v[8:11]
	global_load_lds_dwordx4 v[146:147], off
	v_lshl_add_u64 v[146:147], v[146:147], 0, s[100:101]
	v_mfma_f32_16x16x32_bf16 v[4:7], v[164:167], v[172:175], v[4:7]
	v_mfma_f32_16x16x32_bf16 v[0:3], v[164:167], v[176:179], v[0:3]
	v_mfma_f32_16x16x32_bf16 v[88:91], v[164:167], v[180:183], v[88:91]
	ds_read_b128 v[152:155], v134 offset:8192
	ds_read_b128 v[156:159], v134 offset:10240
	ds_read_b128 v[160:163], v134 offset:12288
	ds_read_b128 v[164:167], v134 offset:14336
	s_waitcnt lgkmcnt(4)
	v_mfma_f32_16x16x32_bf16 v[124:127], v[214:217], v[198:201], v[124:127]
	v_mfma_f32_16x16x32_bf16 v[120:123], v[214:217], v[202:205], v[120:123]
	v_mfma_f32_16x16x32_bf16 v[116:119], v[214:217], v[206:209], v[116:119]
	v_mfma_f32_16x16x32_bf16 v[112:115], v[214:217], v[210:213], v[112:115]
	v_mfma_f32_16x16x32_bf16 v[108:111], v[218:221], v[198:201], v[108:111]
	v_mfma_f32_16x16x32_bf16 v[104:107], v[218:221], v[202:205], v[104:107]
	v_mfma_f32_16x16x32_bf16 v[100:103], v[218:221], v[206:209], v[100:103]
	v_mfma_f32_16x16x32_bf16 v[96:99], v[218:221], v[210:213], v[96:99]
	v_mfma_f32_16x16x32_bf16 v[92:95], v[222:225], v[198:201], v[92:95]
	v_mfma_f32_16x16x32_bf16 v[84:87], v[222:225], v[202:205], v[84:87]
	v_mfma_f32_16x16x32_bf16 v[80:83], v[222:225], v[206:209], v[80:83]
	v_mfma_f32_16x16x32_bf16 v[76:79], v[222:225], v[210:213], v[76:79]
	v_mfma_f32_16x16x32_bf16 v[72:75], v[226:229], v[198:201], v[72:75]
	v_mfma_f32_16x16x32_bf16 v[68:71], v[226:229], v[202:205], v[68:71]
	v_mfma_f32_16x16x32_bf16 v[64:67], v[226:229], v[206:209], v[64:67]
	v_mfma_f32_16x16x32_bf16 v[60:63], v[226:229], v[210:213], v[60:63]
	v_add3_u32 v226, v149, v150, s99
	v_add3_u32 v134, v149, v148, s99
	ds_read_b128 v[214:217], v226 offset:32768
	ds_read_b128 v[218:221], v226 offset:34816
	ds_read_b128 v[222:225], v226 offset:36864
	ds_read_b128 v[226:229], v226 offset:38912
	ds_read_b128 v[168:171], v134 offset:0
	ds_read_b128 v[172:175], v134 offset:2048
	ds_read_b128 v[176:179], v134 offset:4096
	ds_read_b128 v[180:183], v134 offset:6144
	s_waitcnt lgkmcnt(8)
	v_mfma_f32_16x16x32_bf16 v[56:59], v[152:155], v[198:201], v[56:59]
	v_mfma_f32_16x16x32_bf16 v[52:55], v[152:155], v[202:205], v[52:55]
	v_mfma_f32_16x16x32_bf16 v[48:51], v[152:155], v[206:209], v[48:51]
	v_mfma_f32_16x16x32_bf16 v[44:47], v[152:155], v[210:213], v[44:47]
	v_mfma_f32_16x16x32_bf16 v[40:43], v[156:159], v[198:201], v[40:43]
	v_mfma_f32_16x16x32_bf16 v[36:39], v[156:159], v[202:205], v[36:39]
	v_mfma_f32_16x16x32_bf16 v[32:35], v[156:159], v[206:209], v[32:35]
	v_mfma_f32_16x16x32_bf16 v[28:31], v[156:159], v[210:213], v[28:31]
	v_mfma_f32_16x16x32_bf16 v[24:27], v[160:163], v[198:201], v[24:27]
	v_mfma_f32_16x16x32_bf16 v[20:23], v[160:163], v[202:205], v[20:23]
	v_mfma_f32_16x16x32_bf16 v[16:19], v[160:163], v[206:209], v[16:19]
	v_mfma_f32_16x16x32_bf16 v[12:15], v[160:163], v[210:213], v[12:15]
	v_mfma_f32_16x16x32_bf16 v[8:11], v[164:167], v[198:201], v[8:11]
	v_mfma_f32_16x16x32_bf16 v[4:7], v[164:167], v[202:205], v[4:7]
	v_mfma_f32_16x16x32_bf16 v[0:3], v[164:167], v[206:209], v[0:3]
	v_mfma_f32_16x16x32_bf16 v[88:91], v[164:167], v[210:213], v[88:91]
	ds_read_b128 v[198:201], v134 offset:8192
	ds_read_b128 v[202:205], v134 offset:10240
	ds_read_b128 v[206:209], v134 offset:12288
	ds_read_b128 v[210:213], v134 offset:14336
	s_waitcnt lgkmcnt(4)
	v_mfma_f32_16x16x32_bf16 v[124:127], v[168:171], v[214:217], v[124:127]
	v_mfma_f32_16x16x32_bf16 v[120:123], v[168:171], v[218:221], v[120:123]
	v_mfma_f32_16x16x32_bf16 v[116:119], v[168:171], v[222:225], v[116:119]
	v_mfma_f32_16x16x32_bf16 v[112:115], v[168:171], v[226:229], v[112:115]
	v_mfma_f32_16x16x32_bf16 v[108:111], v[172:175], v[214:217], v[108:111]
	v_mfma_f32_16x16x32_bf16 v[104:107], v[172:175], v[218:221], v[104:107]
	v_mfma_f32_16x16x32_bf16 v[100:103], v[172:175], v[222:225], v[100:103]
	v_mfma_f32_16x16x32_bf16 v[96:99], v[172:175], v[226:229], v[96:99]
	v_mfma_f32_16x16x32_bf16 v[92:95], v[176:179], v[214:217], v[92:95]
	v_mfma_f32_16x16x32_bf16 v[84:87], v[176:179], v[218:221], v[84:87]
	v_mfma_f32_16x16x32_bf16 v[80:83], v[176:179], v[222:225], v[80:83]
	v_mfma_f32_16x16x32_bf16 v[76:79], v[176:179], v[226:229], v[76:79]
	v_mfma_f32_16x16x32_bf16 v[72:75], v[180:183], v[214:217], v[72:75]
	v_mfma_f32_16x16x32_bf16 v[68:71], v[180:183], v[218:221], v[68:71]
	v_mfma_f32_16x16x32_bf16 v[64:67], v[180:183], v[222:225], v[64:67]
	v_mfma_f32_16x16x32_bf16 v[60:63], v[180:183], v[226:229], v[60:63]
	s_waitcnt lgkmcnt(0)
	v_mfma_f32_16x16x32_bf16 v[56:59], v[198:201], v[214:217], v[56:59]
	s_waitcnt vmcnt(0)
	s_barrier
	v_add_u32_e32 v164, v151, v150
	v_add_u32_e32 v134, v151, v148
	v_mfma_f32_16x16x32_bf16 v[52:55], v[198:201], v[218:221], v[52:55]
	ds_read_b128 v[152:155], v164 offset:32768
	ds_read_b128 v[156:159], v164 offset:34816
	v_mfma_f32_16x16x32_bf16 v[48:51], v[198:201], v[222:225], v[48:51]
	ds_read_b128 v[160:163], v164 offset:36864
	ds_read_b128 v[164:167], v164 offset:38912
	v_mfma_f32_16x16x32_bf16 v[44:47], v[198:201], v[226:229], v[44:47]
	ds_read_b128 v[168:171], v134 offset:0
	ds_read_b128 v[172:175], v134 offset:2048
	v_mfma_f32_16x16x32_bf16 v[40:43], v[202:205], v[214:217], v[40:43]
	ds_read_b128 v[176:179], v134 offset:4096
	ds_read_b128 v[180:183], v134 offset:6144
	s_add_i32 m0, s93, 0x10000
	v_mfma_f32_16x16x32_bf16 v[36:39], v[202:205], v[218:221], v[36:39]
	global_load_lds_dwordx4 v[128:129], off
	v_lshl_add_u64 v[128:129], v[128:129], 0, s[100:101]
	s_add_i32 m0, s93, 0x18000
	v_mfma_f32_16x16x32_bf16 v[32:35], v[202:205], v[222:225], v[32:35]
	global_load_lds_dwordx4 v[140:141], off
	v_lshl_add_u64 v[140:141], v[140:141], 0, s[100:101]
	s_add_i32 m0, s94, 0x10000
	v_mfma_f32_16x16x32_bf16 v[28:31], v[202:205], v[226:229], v[28:31]
	global_load_lds_dwordx4 v[130:131], off
	v_lshl_add_u64 v[130:131], v[130:131], 0, s[100:101]
	s_add_i32 m0, s94, 0x18000
	v_mfma_f32_16x16x32_bf16 v[24:27], v[206:209], v[214:217], v[24:27]
	global_load_lds_dwordx4 v[142:143], off
	v_lshl_add_u64 v[142:143], v[142:143], 0, s[100:101]
	s_add_i32 m0, s95, 0x10000
	v_mfma_f32_16x16x32_bf16 v[20:23], v[206:209], v[218:221], v[20:23]
	global_load_lds_dwordx4 v[136:137], off
	v_lshl_add_u64 v[136:137], v[136:137], 0, s[100:101]
	s_add_i32 m0, s95, 0x18000
	v_mfma_f32_16x16x32_bf16 v[16:19], v[206:209], v[222:225], v[16:19]
	global_load_lds_dwordx4 v[144:145], off
	v_lshl_add_u64 v[144:145], v[144:145], 0, s[100:101]
	s_add_i32 m0, s96, 0x10000
	v_mfma_f32_16x16x32_bf16 v[12:15], v[206:209], v[226:229], v[12:15]
	global_load_lds_dwordx4 v[138:139], off
	v_lshl_add_u64 v[138:139], v[138:139], 0, s[100:101]
	s_add_i32 m0, s96, 0x18000
	v_mfma_f32_16x16x32_bf16 v[8:11], v[210:213], v[214:217], v[8:11]
	global_load_lds_dwordx4 v[146:147], off
	v_lshl_add_u64 v[146:147], v[146:147], 0, s[100:101]
	v_mfma_f32_16x16x32_bf16 v[4:7], v[210:213], v[218:221], v[4:7]
	v_mfma_f32_16x16x32_bf16 v[0:3], v[210:213], v[222:225], v[0:3]
	v_mfma_f32_16x16x32_bf16 v[88:91], v[210:213], v[226:229], v[88:91]
	s_movk_i32 s2, 0x100
.Lg_up_loop:
	ds_read_b128 v[198:201], v134 offset:8192
	ds_read_b128 v[202:205], v134 offset:10240
	ds_read_b128 v[206:209], v134 offset:12288
	ds_read_b128 v[210:213], v134 offset:14336
	s_waitcnt lgkmcnt(4)
	v_mfma_f32_16x16x32_bf16 v[124:127], v[168:171], v[152:155], v[124:127]
	v_mfma_f32_16x16x32_bf16 v[120:123], v[168:171], v[156:159], v[120:123]
	v_mfma_f32_16x16x32_bf16 v[116:119], v[168:171], v[160:163], v[116:119]
	v_mfma_f32_16x16x32_bf16 v[112:115], v[168:171], v[164:167], v[112:115]
	v_mfma_f32_16x16x32_bf16 v[108:111], v[172:175], v[152:155], v[108:111]
	v_mfma_f32_16x16x32_bf16 v[104:107], v[172:175], v[156:159], v[104:107]
	v_mfma_f32_16x16x32_bf16 v[100:103], v[172:175], v[160:163], v[100:103]
	v_mfma_f32_16x16x32_bf16 v[96:99], v[172:175], v[164:167], v[96:99]
	v_mfma_f32_16x16x32_bf16 v[92:95], v[176:179], v[152:155], v[92:95]
	v_mfma_f32_16x16x32_bf16 v[84:87], v[176:179], v[156:159], v[84:87]
	v_mfma_f32_16x16x32_bf16 v[80:83], v[176:179], v[160:163], v[80:83]
	v_mfma_f32_16x16x32_bf16 v[76:79], v[176:179], v[164:167], v[76:79]
	v_mfma_f32_16x16x32_bf16 v[72:75], v[180:183], v[152:155], v[72:75]
	v_mfma_f32_16x16x32_bf16 v[68:71], v[180:183], v[156:159], v[68:71]
	v_mfma_f32_16x16x32_bf16 v[64:67], v[180:183], v[160:163], v[64:67]
	v_mfma_f32_16x16x32_bf16 v[60:63], v[180:183], v[164:167], v[60:63]
	v_add_u32_e32 v180, v149, v150
	v_add_u32_e32 v134, v149, v148
	ds_read_b128 v[168:171], v180 offset:32768
	ds_read_b128 v[172:175], v180 offset:34816
	ds_read_b128 v[176:179], v180 offset:36864
	ds_read_b128 v[180:183], v180 offset:38912
	ds_read_b128 v[214:217], v134 offset:0
	ds_read_b128 v[218:221], v134 offset:2048
	ds_read_b128 v[222:225], v134 offset:4096
	ds_read_b128 v[226:229], v134 offset:6144
	s_waitcnt lgkmcnt(8)
	v_mfma_f32_16x16x32_bf16 v[56:59], v[198:201], v[152:155], v[56:59]
	v_mfma_f32_16x16x32_bf16 v[52:55], v[198:201], v[156:159], v[52:55]
	v_mfma_f32_16x16x32_bf16 v[48:51], v[198:201], v[160:163], v[48:51]
	v_mfma_f32_16x16x32_bf16 v[44:47], v[198:201], v[164:167], v[44:47]
	v_mfma_f32_16x16x32_bf16 v[40:43], v[202:205], v[152:155], v[40:43]
	v_mfma_f32_16x16x32_bf16 v[36:39], v[202:205], v[156:159], v[36:39]
	v_mfma_f32_16x16x32_bf16 v[32:35], v[202:205], v[160:163], v[32:35]
	v_mfma_f32_16x16x32_bf16 v[28:31], v[202:205], v[164:167], v[28:31]
	v_mfma_f32_16x16x32_bf16 v[24:27], v[206:209], v[152:155], v[24:27]
	v_mfma_f32_16x16x32_bf16 v[20:23], v[206:209], v[156:159], v[20:23]
	v_mfma_f32_16x16x32_bf16 v[16:19], v[206:209], v[160:163], v[16:19]
	v_mfma_f32_16x16x32_bf16 v[12:15], v[206:209], v[164:167], v[12:15]
	v_mfma_f32_16x16x32_bf16 v[8:11], v[210:213], v[152:155], v[8:11]
	v_mfma_f32_16x16x32_bf16 v[4:7], v[210:213], v[156:159], v[4:7]
	v_mfma_f32_16x16x32_bf16 v[0:3], v[210:213], v[160:163], v[0:3]
	v_mfma_f32_16x16x32_bf16 v[88:91], v[210:213], v[164:167], v[88:91]
	ds_read_b128 v[152:155], v134 offset:8192
	ds_read_b128 v[156:159], v134 offset:10240
	ds_read_b128 v[160:163], v134 offset:12288
	ds_read_b128 v[164:167], v134 offset:14336
	s_waitcnt lgkmcnt(4)
	v_mfma_f32_16x16x32_bf16 v[124:127], v[214:217], v[168:171], v[124:127]
	v_mfma_f32_16x16x32_bf16 v[120:123], v[214:217], v[172:175], v[120:123]
	v_mfma_f32_16x16x32_bf16 v[116:119], v[214:217], v[176:179], v[116:119]
	v_mfma_f32_16x16x32_bf16 v[112:115], v[214:217], v[180:183], v[112:115]
	v_mfma_f32_16x16x32_bf16 v[108:111], v[218:221], v[168:171], v[108:111]
	v_mfma_f32_16x16x32_bf16 v[104:107], v[218:221], v[172:175], v[104:107]
	v_mfma_f32_16x16x32_bf16 v[100:103], v[218:221], v[176:179], v[100:103]
	v_mfma_f32_16x16x32_bf16 v[96:99], v[218:221], v[180:183], v[96:99]
	v_mfma_f32_16x16x32_bf16 v[92:95], v[222:225], v[168:171], v[92:95]
	v_mfma_f32_16x16x32_bf16 v[84:87], v[222:225], v[172:175], v[84:87]
	v_mfma_f32_16x16x32_bf16 v[80:83], v[222:225], v[176:179], v[80:83]
	v_mfma_f32_16x16x32_bf16 v[76:79], v[222:225], v[180:183], v[76:79]
	v_mfma_f32_16x16x32_bf16 v[72:75], v[226:229], v[168:171], v[72:75]
	v_mfma_f32_16x16x32_bf16 v[68:71], v[226:229], v[172:175], v[68:71]
	v_mfma_f32_16x16x32_bf16 v[64:67], v[226:229], v[176:179], v[64:67]
	v_mfma_f32_16x16x32_bf16 v[60:63], v[226:229], v[180:183], v[60:63]
	s_waitcnt lgkmcnt(0)
	v_mfma_f32_16x16x32_bf16 v[56:59], v[152:155], v[168:171], v[56:59]
	s_waitcnt vmcnt(0)
	s_barrier
	v_add3_u32 v210, v151, v150, s99
	v_add3_u32 v134, v151, v148, s99
	v_mfma_f32_16x16x32_bf16 v[52:55], v[152:155], v[172:175], v[52:55]
	ds_read_b128 v[198:201], v210 offset:32768
	ds_read_b128 v[202:205], v210 offset:34816
	v_mfma_f32_16x16x32_bf16 v[48:51], v[152:155], v[176:179], v[48:51]
	ds_read_b128 v[206:209], v210 offset:36864
	ds_read_b128 v[210:213], v210 offset:38912
	v_mfma_f32_16x16x32_bf16 v[44:47], v[152:155], v[180:183], v[44:47]
	ds_read_b128 v[214:217], v134 offset:0
	ds_read_b128 v[218:221], v134 offset:2048
	v_mfma_f32_16x16x32_bf16 v[40:43], v[156:159], v[168:171], v[40:43]
	ds_read_b128 v[222:225], v134 offset:4096
	ds_read_b128 v[226:229], v134 offset:6144
	s_mov_b32 m0, s93
	v_mfma_f32_16x16x32_bf16 v[36:39], v[156:159], v[172:175], v[36:39]
	global_load_lds_dwordx4 v[128:129], off
	v_lshl_add_u64 v[128:129], v[128:129], 0, s[100:101]
	s_add_i32 m0, s93, 0x8000
	v_mfma_f32_16x16x32_bf16 v[32:35], v[156:159], v[176:179], v[32:35]
	global_load_lds_dwordx4 v[140:141], off
	v_lshl_add_u64 v[140:141], v[140:141], 0, s[100:101]
	s_mov_b32 m0, s94
	v_mfma_f32_16x16x32_bf16 v[28:31], v[156:159], v[180:183], v[28:31]
	global_load_lds_dwordx4 v[130:131], off
	v_lshl_add_u64 v[130:131], v[130:131], 0, s[100:101]
	s_add_i32 m0, s94, 0x8000
	v_mfma_f32_16x16x32_bf16 v[24:27], v[160:163], v[168:171], v[24:27]
	global_load_lds_dwordx4 v[142:143], off
	v_lshl_add_u64 v[142:143], v[142:143], 0, s[100:101]
	s_mov_b32 m0, s95
	v_mfma_f32_16x16x32_bf16 v[20:23], v[160:163], v[172:175], v[20:23]
	global_load_lds_dwordx4 v[136:137], off
	v_lshl_add_u64 v[136:137], v[136:137], 0, s[100:101]
	s_add_i32 m0, s95, 0x8000
	v_mfma_f32_16x16x32_bf16 v[16:19], v[160:163], v[176:179], v[16:19]
	global_load_lds_dwordx4 v[144:145], off
	v_lshl_add_u64 v[144:145], v[144:145], 0, s[100:101]
	s_mov_b32 m0, s96
	v_mfma_f32_16x16x32_bf16 v[12:15], v[160:163], v[180:183], v[12:15]
	global_load_lds_dwordx4 v[138:139], off
	v_lshl_add_u64 v[138:139], v[138:139], 0, s[100:101]
	s_add_i32 m0, s96, 0x8000
	v_mfma_f32_16x16x32_bf16 v[8:11], v[164:167], v[168:171], v[8:11]
	global_load_lds_dwordx4 v[146:147], off
	v_lshl_add_u64 v[146:147], v[146:147], 0, s[100:101]
	v_mfma_f32_16x16x32_bf16 v[4:7], v[164:167], v[172:175], v[4:7]
	v_mfma_f32_16x16x32_bf16 v[0:3], v[164:167], v[176:179], v[0:3]
	v_mfma_f32_16x16x32_bf16 v[88:91], v[164:167], v[180:183], v[88:91]
	ds_read_b128 v[152:155], v134 offset:8192
	ds_read_b128 v[156:159], v134 offset:10240
	ds_read_b128 v[160:163], v134 offset:12288
	ds_read_b128 v[164:167], v134 offset:14336
	s_waitcnt lgkmcnt(4)
	v_mfma_f32_16x16x32_bf16 v[124:127], v[214:217], v[198:201], v[124:127]
	v_mfma_f32_16x16x32_bf16 v[120:123], v[214:217], v[202:205], v[120:123]
	v_mfma_f32_16x16x32_bf16 v[116:119], v[214:217], v[206:209], v[116:119]
	v_mfma_f32_16x16x32_bf16 v[112:115], v[214:217], v[210:213], v[112:115]
	v_mfma_f32_16x16x32_bf16 v[108:111], v[218:221], v[198:201], v[108:111]
	v_mfma_f32_16x16x32_bf16 v[104:107], v[218:221], v[202:205], v[104:107]
	v_mfma_f32_16x16x32_bf16 v[100:103], v[218:221], v[206:209], v[100:103]
	v_mfma_f32_16x16x32_bf16 v[96:99], v[218:221], v[210:213], v[96:99]
	v_mfma_f32_16x16x32_bf16 v[92:95], v[222:225], v[198:201], v[92:95]
	v_mfma_f32_16x16x32_bf16 v[84:87], v[222:225], v[202:205], v[84:87]
	v_mfma_f32_16x16x32_bf16 v[80:83], v[222:225], v[206:209], v[80:83]
	v_mfma_f32_16x16x32_bf16 v[76:79], v[222:225], v[210:213], v[76:79]
	v_mfma_f32_16x16x32_bf16 v[72:75], v[226:229], v[198:201], v[72:75]
	v_mfma_f32_16x16x32_bf16 v[68:71], v[226:229], v[202:205], v[68:71]
	v_mfma_f32_16x16x32_bf16 v[64:67], v[226:229], v[206:209], v[64:67]
	v_mfma_f32_16x16x32_bf16 v[60:63], v[226:229], v[210:213], v[60:63]
	v_add3_u32 v226, v149, v150, s99
	v_add3_u32 v134, v149, v148, s99
	ds_read_b128 v[214:217], v226 offset:32768
	ds_read_b128 v[218:221], v226 offset:34816
	ds_read_b128 v[222:225], v226 offset:36864
	ds_read_b128 v[226:229], v226 offset:38912
	ds_read_b128 v[168:171], v134 offset:0
	ds_read_b128 v[172:175], v134 offset:2048
	ds_read_b128 v[176:179], v134 offset:4096
	ds_read_b128 v[180:183], v134 offset:6144
	s_waitcnt lgkmcnt(8)
	v_mfma_f32_16x16x32_bf16 v[56:59], v[152:155], v[198:201], v[56:59]
	v_mfma_f32_16x16x32_bf16 v[52:55], v[152:155], v[202:205], v[52:55]
	v_mfma_f32_16x16x32_bf16 v[48:51], v[152:155], v[206:209], v[48:51]
	v_mfma_f32_16x16x32_bf16 v[44:47], v[152:155], v[210:213], v[44:47]
	v_mfma_f32_16x16x32_bf16 v[40:43], v[156:159], v[198:201], v[40:43]
	v_mfma_f32_16x16x32_bf16 v[36:39], v[156:159], v[202:205], v[36:39]
	v_mfma_f32_16x16x32_bf16 v[32:35], v[156:159], v[206:209], v[32:35]
	v_mfma_f32_16x16x32_bf16 v[28:31], v[156:159], v[210:213], v[28:31]
	v_mfma_f32_16x16x32_bf16 v[24:27], v[160:163], v[198:201], v[24:27]
	v_mfma_f32_16x16x32_bf16 v[20:23], v[160:163], v[202:205], v[20:23]
	v_mfma_f32_16x16x32_bf16 v[16:19], v[160:163], v[206:209], v[16:19]
	v_mfma_f32_16x16x32_bf16 v[12:15], v[160:163], v[210:213], v[12:15]
	v_mfma_f32_16x16x32_bf16 v[8:11], v[164:167], v[198:201], v[8:11]
	v_mfma_f32_16x16x32_bf16 v[4:7], v[164:167], v[202:205], v[4:7]
	v_mfma_f32_16x16x32_bf16 v[0:3], v[164:167], v[206:209], v[0:3]
	v_mfma_f32_16x16x32_bf16 v[88:91], v[164:167], v[210:213], v[88:91]
	ds_read_b128 v[198:201], v134 offset:8192
	ds_read_b128 v[202:205], v134 offset:10240
	ds_read_b128 v[206:209], v134 offset:12288
	ds_read_b128 v[210:213], v134 offset:14336
	s_waitcnt lgkmcnt(4)
	v_mfma_f32_16x16x32_bf16 v[124:127], v[168:171], v[214:217], v[124:127]
	v_mfma_f32_16x16x32_bf16 v[120:123], v[168:171], v[218:221], v[120:123]
	v_mfma_f32_16x16x32_bf16 v[116:119], v[168:171], v[222:225], v[116:119]
	v_mfma_f32_16x16x32_bf16 v[112:115], v[168:171], v[226:229], v[112:115]
	v_mfma_f32_16x16x32_bf16 v[108:111], v[172:175], v[214:217], v[108:111]
	v_mfma_f32_16x16x32_bf16 v[104:107], v[172:175], v[218:221], v[104:107]
	v_mfma_f32_16x16x32_bf16 v[100:103], v[172:175], v[222:225], v[100:103]
	v_mfma_f32_16x16x32_bf16 v[96:99], v[172:175], v[226:229], v[96:99]
	v_mfma_f32_16x16x32_bf16 v[92:95], v[176:179], v[214:217], v[92:95]
	v_mfma_f32_16x16x32_bf16 v[84:87], v[176:179], v[218:221], v[84:87]
	v_mfma_f32_16x16x32_bf16 v[80:83], v[176:179], v[222:225], v[80:83]
	v_mfma_f32_16x16x32_bf16 v[76:79], v[176:179], v[226:229], v[76:79]
	v_mfma_f32_16x16x32_bf16 v[72:75], v[180:183], v[214:217], v[72:75]
	v_mfma_f32_16x16x32_bf16 v[68:71], v[180:183], v[218:221], v[68:71]
	v_mfma_f32_16x16x32_bf16 v[64:67], v[180:183], v[222:225], v[64:67]
	v_mfma_f32_16x16x32_bf16 v[60:63], v[180:183], v[226:229], v[60:63]
	s_waitcnt lgkmcnt(0)
	v_mfma_f32_16x16x32_bf16 v[56:59], v[198:201], v[214:217], v[56:59]
	s_waitcnt vmcnt(0)
	s_barrier
	v_add_u32_e32 v164, v151, v150
	v_add_u32_e32 v134, v151, v148
	v_mfma_f32_16x16x32_bf16 v[52:55], v[198:201], v[218:221], v[52:55]
	ds_read_b128 v[152:155], v164 offset:32768
	ds_read_b128 v[156:159], v164 offset:34816
	v_mfma_f32_16x16x32_bf16 v[48:51], v[198:201], v[222:225], v[48:51]
	ds_read_b128 v[160:163], v164 offset:36864
	ds_read_b128 v[164:167], v164 offset:38912
	v_mfma_f32_16x16x32_bf16 v[44:47], v[198:201], v[226:229], v[44:47]
	ds_read_b128 v[168:171], v134 offset:0
	ds_read_b128 v[172:175], v134 offset:2048
	v_mfma_f32_16x16x32_bf16 v[40:43], v[202:205], v[214:217], v[40:43]
	ds_read_b128 v[176:179], v134 offset:4096
	ds_read_b128 v[180:183], v134 offset:6144
	s_add_i32 m0, s93, 0x10000
	v_mfma_f32_16x16x32_bf16 v[36:39], v[202:205], v[218:221], v[36:39]
	global_load_lds_dwordx4 v[128:129], off
	v_lshl_add_u64 v[128:129], v[128:129], 0, s[100:101]
	s_add_i32 m0, s93, 0x18000
	v_mfma_f32_16x16x32_bf16 v[32:35], v[202:205], v[222:225], v[32:35]
	global_load_lds_dwordx4 v[140:141], off
	v_lshl_add_u64 v[140:141], v[140:141], 0, s[100:101]
	s_add_i32 m0, s94, 0x10000
	v_mfma_f32_16x16x32_bf16 v[28:31], v[202:205], v[226:229], v[28:31]
	global_load_lds_dwordx4 v[130:131], off
	v_lshl_add_u64 v[130:131], v[130:131], 0, s[100:101]
	s_add_i32 m0, s94, 0x18000
	v_mfma_f32_16x16x32_bf16 v[24:27], v[206:209], v[214:217], v[24:27]
	global_load_lds_dwordx4 v[142:143], off
	v_lshl_add_u64 v[142:143], v[142:143], 0, s[100:101]
	s_add_i32 m0, s95, 0x10000
	v_mfma_f32_16x16x32_bf16 v[20:23], v[206:209], v[218:221], v[20:23]
	global_load_lds_dwordx4 v[136:137], off
	v_lshl_add_u64 v[136:137], v[136:137], 0, s[100:101]
	s_add_i32 m0, s95, 0x18000
	v_mfma_f32_16x16x32_bf16 v[16:19], v[206:209], v[222:225], v[16:19]
	global_load_lds_dwordx4 v[144:145], off
	v_lshl_add_u64 v[144:145], v[144:145], 0, s[100:101]
	s_add_i32 m0, s96, 0x10000
	v_mfma_f32_16x16x32_bf16 v[12:15], v[206:209], v[226:229], v[12:15]
	global_load_lds_dwordx4 v[138:139], off
	v_lshl_add_u64 v[138:139], v[138:139], 0, s[100:101]
	s_add_i32 m0, s96, 0x18000
	v_mfma_f32_16x16x32_bf16 v[8:11], v[210:213], v[214:217], v[8:11]
	global_load_lds_dwordx4 v[146:147], off
	v_lshl_add_u64 v[146:147], v[146:147], 0, s[100:101]
	v_mfma_f32_16x16x32_bf16 v[4:7], v[210:213], v[218:221], v[4:7]
	v_mfma_f32_16x16x32_bf16 v[0:3], v[210:213], v[222:225], v[0:3]
	v_mfma_f32_16x16x32_bf16 v[88:91], v[210:213], v[226:229], v[88:91]
	s_add_u32 s2, s2, 0x100
	s_cmpk_lg_i32 s2, 0x700
	s_cbranch_scc1 .Lg_up_loop
	ds_read_b128 v[198:201], v134 offset:8192
	ds_read_b128 v[202:205], v134 offset:10240
	ds_read_b128 v[206:209], v134 offset:12288
	ds_read_b128 v[210:213], v134 offset:14336
	s_waitcnt lgkmcnt(4)
	v_mfma_f32_16x16x32_bf16 v[124:127], v[168:171], v[152:155], v[124:127]
	v_mfma_f32_16x16x32_bf16 v[120:123], v[168:171], v[156:159], v[120:123]
	v_mfma_f32_16x16x32_bf16 v[116:119], v[168:171], v[160:163], v[116:119]
	v_mfma_f32_16x16x32_bf16 v[112:115], v[168:171], v[164:167], v[112:115]
	v_mfma_f32_16x16x32_bf16 v[108:111], v[172:175], v[152:155], v[108:111]
	v_mfma_f32_16x16x32_bf16 v[104:107], v[172:175], v[156:159], v[104:107]
	v_mfma_f32_16x16x32_bf16 v[100:103], v[172:175], v[160:163], v[100:103]
	v_mfma_f32_16x16x32_bf16 v[96:99], v[172:175], v[164:167], v[96:99]
	v_mfma_f32_16x16x32_bf16 v[92:95], v[176:179], v[152:155], v[92:95]
	v_mfma_f32_16x16x32_bf16 v[84:87], v[176:179], v[156:159], v[84:87]
	v_mfma_f32_16x16x32_bf16 v[80:83], v[176:179], v[160:163], v[80:83]
	v_mfma_f32_16x16x32_bf16 v[76:79], v[176:179], v[164:167], v[76:79]
	v_mfma_f32_16x16x32_bf16 v[72:75], v[180:183], v[152:155], v[72:75]
	v_mfma_f32_16x16x32_bf16 v[68:71], v[180:183], v[156:159], v[68:71]
	v_mfma_f32_16x16x32_bf16 v[64:67], v[180:183], v[160:163], v[64:67]
	v_mfma_f32_16x16x32_bf16 v[60:63], v[180:183], v[164:167], v[60:63]
	v_add_u32_e32 v180, v149, v150
	v_add_u32_e32 v134, v149, v148
	ds_read_b128 v[168:171], v180 offset:32768
	ds_read_b128 v[172:175], v180 offset:34816
	ds_read_b128 v[176:179], v180 offset:36864
	ds_read_b128 v[180:183], v180 offset:38912
	ds_read_b128 v[214:217], v134 offset:0
	ds_read_b128 v[218:221], v134 offset:2048
	ds_read_b128 v[222:225], v134 offset:4096
	ds_read_b128 v[226:229], v134 offset:6144
	s_waitcnt lgkmcnt(8)
	v_mfma_f32_16x16x32_bf16 v[56:59], v[198:201], v[152:155], v[56:59]
	v_mfma_f32_16x16x32_bf16 v[52:55], v[198:201], v[156:159], v[52:55]
	v_mfma_f32_16x16x32_bf16 v[48:51], v[198:201], v[160:163], v[48:51]
	v_mfma_f32_16x16x32_bf16 v[44:47], v[198:201], v[164:167], v[44:47]
	v_mfma_f32_16x16x32_bf16 v[40:43], v[202:205], v[152:155], v[40:43]
	v_mfma_f32_16x16x32_bf16 v[36:39], v[202:205], v[156:159], v[36:39]
	v_mfma_f32_16x16x32_bf16 v[32:35], v[202:205], v[160:163], v[32:35]
	v_mfma_f32_16x16x32_bf16 v[28:31], v[202:205], v[164:167], v[28:31]
	v_mfma_f32_16x16x32_bf16 v[24:27], v[206:209], v[152:155], v[24:27]
	v_mfma_f32_16x16x32_bf16 v[20:23], v[206:209], v[156:159], v[20:23]
	v_mfma_f32_16x16x32_bf16 v[16:19], v[206:209], v[160:163], v[16:19]
	v_mfma_f32_16x16x32_bf16 v[12:15], v[206:209], v[164:167], v[12:15]
	v_mfma_f32_16x16x32_bf16 v[8:11], v[210:213], v[152:155], v[8:11]
	v_mfma_f32_16x16x32_bf16 v[4:7], v[210:213], v[156:159], v[4:7]
	v_mfma_f32_16x16x32_bf16 v[0:3], v[210:213], v[160:163], v[0:3]
	v_mfma_f32_16x16x32_bf16 v[88:91], v[210:213], v[164:167], v[88:91]
	ds_read_b128 v[152:155], v134 offset:8192
	ds_read_b128 v[156:159], v134 offset:10240
	ds_read_b128 v[160:163], v134 offset:12288
	ds_read_b128 v[164:167], v134 offset:14336
	s_waitcnt lgkmcnt(4)
	v_mfma_f32_16x16x32_bf16 v[124:127], v[214:217], v[168:171], v[124:127]
	v_mfma_f32_16x16x32_bf16 v[120:123], v[214:217], v[172:175], v[120:123]
	v_mfma_f32_16x16x32_bf16 v[116:119], v[214:217], v[176:179], v[116:119]
	v_mfma_f32_16x16x32_bf16 v[112:115], v[214:217], v[180:183], v[112:115]
	v_mfma_f32_16x16x32_bf16 v[108:111], v[218:221], v[168:171], v[108:111]
	v_mfma_f32_16x16x32_bf16 v[104:107], v[218:221], v[172:175], v[104:107]
	v_mfma_f32_16x16x32_bf16 v[100:103], v[218:221], v[176:179], v[100:103]
	v_mfma_f32_16x16x32_bf16 v[96:99], v[218:221], v[180:183], v[96:99]
	v_mfma_f32_16x16x32_bf16 v[92:95], v[222:225], v[168:171], v[92:95]
	v_mfma_f32_16x16x32_bf16 v[84:87], v[222:225], v[172:175], v[84:87]
	v_mfma_f32_16x16x32_bf16 v[80:83], v[222:225], v[176:179], v[80:83]
	v_mfma_f32_16x16x32_bf16 v[76:79], v[222:225], v[180:183], v[76:79]
	v_mfma_f32_16x16x32_bf16 v[72:75], v[226:229], v[168:171], v[72:75]
	v_mfma_f32_16x16x32_bf16 v[68:71], v[226:229], v[172:175], v[68:71]
	v_mfma_f32_16x16x32_bf16 v[64:67], v[226:229], v[176:179], v[64:67]
	v_mfma_f32_16x16x32_bf16 v[60:63], v[226:229], v[180:183], v[60:63]
	s_waitcnt lgkmcnt(0)
	v_mfma_f32_16x16x32_bf16 v[56:59], v[152:155], v[168:171], v[56:59]
	s_waitcnt vmcnt(0)
	s_barrier
	v_lshlrev_b32_e32 v254, 3, v184
	v_and_b32_e32 v254, 0x78, v254
	v_lshl_or_b32 v254, s44, 7, v254
	v_lshlrev_b32_e32 v254, 2, v254
	v_add_u32_e32 v222, 0x2c00, v254
	v_add_u32_e32 v223, 0x5800, v254
	global_load_dwordx4 v[234:237], v254, s[10:11]
	global_load_dwordx4 v[230:233], v254, s[10:11] offset:16
	global_load_dwordx4 v[238:241], v222, s[10:11]
	global_load_dwordx4 v[242:245], v222, s[10:11] offset:16
	global_load_dwordx4 v[246:249], v223, s[10:11]
	global_load_dwordx4 v[250:253], v223, s[10:11] offset:16
	global_load_dwordx4 v[214:217], v254, s[12:13] offset:16
	global_load_dwordx4 v[218:221], v254, s[12:13]
	v_mfma_f32_16x16x32_bf16 v[52:55], v[152:155], v[172:175], v[52:55]
	v_mfma_f32_16x16x32_bf16 v[48:51], v[152:155], v[176:179], v[48:51]
	v_mfma_f32_16x16x32_bf16 v[44:47], v[152:155], v[180:183], v[44:47]
	v_mfma_f32_16x16x32_bf16 v[40:43], v[156:159], v[168:171], v[40:43]
	v_mfma_f32_16x16x32_bf16 v[36:39], v[156:159], v[172:175], v[36:39]
	v_mfma_f32_16x16x32_bf16 v[32:35], v[156:159], v[176:179], v[32:35]
	v_mfma_f32_16x16x32_bf16 v[28:31], v[156:159], v[180:183], v[28:31]
	v_mfma_f32_16x16x32_bf16 v[24:27], v[160:163], v[168:171], v[24:27]
	v_mfma_f32_16x16x32_bf16 v[20:23], v[160:163], v[172:175], v[20:23]
	v_mfma_f32_16x16x32_bf16 v[16:19], v[160:163], v[176:179], v[16:19]
	v_mfma_f32_16x16x32_bf16 v[12:15], v[160:163], v[180:183], v[12:15]
	v_mfma_f32_16x16x32_bf16 v[8:11], v[164:167], v[168:171], v[8:11]
	v_mfma_f32_16x16x32_bf16 v[4:7], v[164:167], v[172:175], v[4:7]
	v_mfma_f32_16x16x32_bf16 v[0:3], v[164:167], v[176:179], v[0:3]
	v_mfma_f32_16x16x32_bf16 v[88:91], v[164:167], v[180:183], v[88:91]
	s_movk_i32 s2, 0x780
	s_mov_b32 s97, 0xf0000
	v_add3_u32 v134, v148, v151, s75
	ds_read_b128 v[128:131], v134 offset:14336
	ds_read_b128 v[136:139], v134 offset:12288
	ds_read_b128 v[140:143], v134 offset:10240
	ds_read_b128 v[144:147], v134 offset:8192
	ds_read_b128 v[152:155], v134 offset:6144
	ds_read_b128 v[156:159], v134 offset:4096
	ds_read_b128 v[160:163], v134 offset:2048
	ds_read_b128 v[164:167], v134
	v_add3_u32 v134, v150, v151, s63
	ds_read_b128 v[168:171], v134 offset:6144
	ds_read_b128 v[172:175], v134 offset:4096
	ds_read_b128 v[176:179], v134 offset:2048
	ds_read_b128 v[180:183], v134
	s_waitcnt lgkmcnt(0)
	v_mfma_f32_16x16x32_bf16 v[124:127], v[164:167], v[180:183], v[124:127]
	v_mfma_f32_16x16x32_bf16 v[120:123], v[164:167], v[176:179], v[120:123]
	v_mfma_f32_16x16x32_bf16 v[116:119], v[164:167], v[172:175], v[116:119]
	v_mfma_f32_16x16x32_bf16 v[112:115], v[164:167], v[168:171], v[112:115]
	v_mfma_f32_16x16x32_bf16 v[108:111], v[160:163], v[180:183], v[108:111]
	v_mfma_f32_16x16x32_bf16 v[104:107], v[160:163], v[176:179], v[104:107]
	v_mfma_f32_16x16x32_bf16 v[100:103], v[160:163], v[172:175], v[100:103]
	v_mfma_f32_16x16x32_bf16 v[96:99], v[160:163], v[168:171], v[96:99]
	v_mfma_f32_16x16x32_bf16 v[92:95], v[156:159], v[180:183], v[92:95]
	v_mfma_f32_16x16x32_bf16 v[84:87], v[156:159], v[176:179], v[84:87]
	v_mfma_f32_16x16x32_bf16 v[80:83], v[156:159], v[172:175], v[80:83]
	v_mfma_f32_16x16x32_bf16 v[76:79], v[156:159], v[168:171], v[76:79]
	v_mfma_f32_16x16x32_bf16 v[72:75], v[152:155], v[180:183], v[72:75]
	v_mfma_f32_16x16x32_bf16 v[68:71], v[152:155], v[176:179], v[68:71]
	v_mfma_f32_16x16x32_bf16 v[64:67], v[152:155], v[172:175], v[64:67]
	v_mfma_f32_16x16x32_bf16 v[60:63], v[152:155], v[168:171], v[60:63]
	v_add3_u32 v134, v150, v149, s63
	ds_read_b128 v[150:153], v134
	ds_read_b128 v[154:157], v134 offset:2048
	ds_read_b128 v[158:161], v134 offset:4096
	ds_read_b128 v[162:165], v134 offset:6144
	v_add3_u32 v134, v148, v149, s75
	ds_read_b128 v[198:201], v134
	ds_read_b128 v[202:205], v134 offset:2048
	ds_read_b128 v[206:209], v134 offset:4096
	ds_read_b128 v[210:213], v134 offset:6144
	v_mfma_f32_16x16x32_bf16 v[44:47], v[144:147], v[168:171], v[44:47]
	v_mfma_f32_16x16x32_bf16 v[40:43], v[140:143], v[180:183], v[40:43]
	v_mfma_f32_16x16x32_bf16 v[28:31], v[140:143], v[168:171], v[28:31]
	v_mfma_f32_16x16x32_bf16 v[24:27], v[136:139], v[180:183], v[24:27]
	v_mfma_f32_16x16x32_bf16 v[20:23], v[136:139], v[176:179], v[20:23]
	v_mfma_f32_16x16x32_bf16 v[16:19], v[136:139], v[172:175], v[16:19]
	v_mfma_f32_16x16x32_bf16 v[12:15], v[136:139], v[168:171], v[12:15]
	v_mfma_f32_16x16x32_bf16 v[8:11], v[128:131], v[180:183], v[8:11]
	v_mfma_f32_16x16x32_bf16 v[4:7], v[128:131], v[176:179], v[4:7]
	v_mfma_f32_16x16x32_bf16 v[0:3], v[128:131], v[172:175], v[0:3]
	v_mfma_f32_16x16x32_bf16 v[56:59], v[144:147], v[180:183], v[56:59]
	v_mfma_f32_16x16x32_bf16 v[52:55], v[144:147], v[176:179], v[52:55]
	v_mfma_f32_16x16x32_bf16 v[48:51], v[144:147], v[172:175], v[48:51]
	v_mfma_f32_16x16x32_bf16 v[36:39], v[140:143], v[176:179], v[36:39]
	v_mfma_f32_16x16x32_bf16 v[32:35], v[140:143], v[172:175], v[32:35]
	v_mfma_f32_16x16x32_bf16 v[88:91], v[128:131], v[168:171], v[88:91]
	ds_read_b128 v[128:131], v134 offset:8192
	ds_read_b128 v[136:139], v134 offset:10240
	ds_read_b128 v[140:143], v134 offset:12288
	ds_read_b128 v[144:147], v134 offset:14336
	s_waitcnt lgkmcnt(0)
	v_mfma_f32_16x16x32_bf16 v[124:127], v[198:201], v[150:153], v[124:127]
	v_mfma_f32_16x16x32_bf16 v[120:123], v[198:201], v[154:157], v[120:123]
	v_mfma_f32_16x16x32_bf16 v[116:119], v[198:201], v[158:161], v[116:119]
	v_mfma_f32_16x16x32_bf16 v[112:115], v[198:201], v[162:165], v[112:115]
	v_mfma_f32_16x16x32_bf16 v[108:111], v[202:205], v[150:153], v[108:111]
	v_mfma_f32_16x16x32_bf16 v[104:107], v[202:205], v[154:157], v[104:107]
	v_mfma_f32_16x16x32_bf16 v[100:103], v[202:205], v[158:161], v[100:103]
	v_mfma_f32_16x16x32_bf16 v[96:99], v[202:205], v[162:165], v[96:99]
	v_mfma_f32_16x16x32_bf16 v[92:95], v[206:209], v[150:153], v[92:95]
	v_mfma_f32_16x16x32_bf16 v[84:87], v[206:209], v[154:157], v[84:87]
	v_mfma_f32_16x16x32_bf16 v[80:83], v[206:209], v[158:161], v[80:83]
	v_mfma_f32_16x16x32_bf16 v[76:79], v[206:209], v[162:165], v[76:79]
	v_mfma_f32_16x16x32_bf16 v[72:75], v[210:213], v[150:153], v[72:75]
	v_mfma_f32_16x16x32_bf16 v[68:71], v[210:213], v[154:157], v[68:71]
	v_mfma_f32_16x16x32_bf16 v[64:67], v[210:213], v[158:161], v[64:67]
	v_mfma_f32_16x16x32_bf16 v[60:63], v[210:213], v[162:165], v[60:63]
	v_mov_b32_e32 v148, v184
	v_mfma_f32_16x16x32_bf16 v[24:27], v[140:143], v[150:153], v[24:27]
	s_waitcnt lgkmcnt(0)
	s_barrier
	v_mfma_f32_16x16x32_bf16 v[8:11], v[144:147], v[150:153], v[8:11]
	s_nop 5
	v_cvt_pk_bf16_f32 v24, v24, v25
	v_lshrrev_b32_e32 v134, 8, v148
	v_mul_i32_i24_e32 v134, 0x11000, v134
	v_lshrrev_b32_e32 v166, 1, v148
	v_and_b32_e32 v149, 0xcf, v148
	v_and_or_b32 v134, v166, 24, v134
	v_mfma_f32_16x16x32_bf16 v[56:59], v[128:131], v[150:153], v[56:59]
	v_cvt_pk_bf16_f32 v25, v26, v27
	v_cvt_pk_bf16_f32 v8, v8, v9
	v_cvt_pk_bf16_f32 v9, v10, v11
	v_mfma_f32_16x16x32_bf16 v[52:55], v[128:131], v[154:157], v[52:55]
	s_mov_b64 s[2:3], 0x2c00
	s_nop 2
	v_cvt_pk_bf16_f32 v56, v56, v57
	v_cvt_pk_bf16_f32 v57, v58, v59
	v_mfma_f32_16x16x32_bf16 v[48:51], v[128:131], v[158:161], v[48:51]
	v_cvt_pk_bf16_f32 v124, v124, v125
	v_cvt_pk_bf16_f32 v125, v126, v127
	v_cvt_pk_bf16_f32 v108, v108, v109
	v_mfma_f32_16x16x32_bf16 v[44:47], v[128:131], v[162:165], v[44:47]
	v_mad_u32_u24 v128, v149, s51, v134
	ds_write2_b64 v128, v[24:25], v[8:9] offset0:24 offset1:28
	v_cvt_pk_bf16_f32 v24, v52, v53
	v_mfma_f32_16x16x32_bf16 v[40:43], v[136:139], v[150:153], v[40:43]
	v_cvt_pk_bf16_f32 v25, v54, v55
	v_cvt_pk_bf16_f32 v109, v110, v111
	v_cvt_pk_bf16_f32 v92, v92, v93
	v_mfma_f32_16x16x32_bf16 v[8:11], v[140:143], v[154:157], v[20:23]
	v_cvt_pk_bf16_f32 v93, v94, v95
	s_nop 2
	v_cvt_pk_bf16_f32 v40, v40, v41
	v_cvt_pk_bf16_f32 v41, v42, v43
	v_mfma_f32_16x16x32_bf16 v[4:7], v[144:147], v[154:157], v[4:7]
	ds_write2_b64 v128, v[56:57], v[40:41] offset0:16 offset1:20
	v_add_u32_e32 v40, 0x1000, v128
	v_cvt_pk_bf16_f32 v8, v8, v9
	v_mfma_f32_16x16x32_bf16 v[32:35], v[136:139], v[158:161], v[32:35]
	v_cvt_pk_bf16_f32 v9, v10, v11
	s_nop 2
	v_cvt_pk_bf16_f32 v4, v4, v5
	v_cvt_pk_bf16_f32 v5, v6, v7
	v_mfma_f32_16x16x32_bf16 v[16:19], v[140:143], v[158:161], v[16:19]
	ds_write2_b64 v40, v[8:9], v[4:5] offset0:56 offset1:60
	v_cvt_pk_bf16_f32 v4, v116, v117
	v_cvt_pk_bf16_f32 v5, v118, v119
	v_mfma_f32_16x16x32_bf16 v[0:3], v[144:147], v[158:161], v[0:3]
	v_cvt_pk_bf16_f32 v6, v100, v101
	v_cvt_pk_bf16_f32 v7, v102, v103
	v_add_u32_e32 v8, 0x2000, v128
	v_cvt_pk_bf16_f32 v20, v120, v121
	v_cvt_pk_bf16_f32 v21, v122, v123
	v_cvt_pk_bf16_f32 v22, v104, v105
	v_cvt_pk_bf16_f32 v23, v106, v107
	ds_write2_b64 v8, v[4:5], v[6:7] offset0:64 offset1:68
	v_cvt_pk_bf16_f32 v4, v80, v81
	v_cvt_pk_bf16_f32 v5, v82, v83
	v_cvt_pk_bf16_f32 v6, v64, v65
	v_cvt_pk_bf16_f32 v7, v66, v67
	v_mfma_f32_16x16x32_bf16 v[28:31], v[136:139], v[162:165], v[28:31]
	ds_write2_b64 v40, v[20:21], v[22:23] offset0:32 offset1:36
	v_cvt_pk_bf16_f32 v20, v84, v85
	v_cvt_pk_bf16_f32 v21, v86, v87
	v_cvt_pk_bf16_f32 v22, v68, v69
	v_cvt_pk_bf16_f32 v23, v70, v71
	ds_write2_b64 v8, v[4:5], v[6:7] offset0:72 offset1:76
	v_cvt_pk_bf16_f32 v4, v48, v49
	v_cvt_pk_bf16_f32 v5, v50, v51
	v_cvt_pk_bf16_f32 v6, v32, v33
	v_cvt_pk_bf16_f32 v7, v34, v35
	v_mfma_f32_16x16x32_bf16 v[12:15], v[140:143], v[162:165], v[12:15]
	ds_write2_b64 v40, v[20:21], v[22:23] offset0:40 offset1:44
	ds_write2_b64 v8, v[4:5], v[6:7] offset0:80 offset1:84
	v_cvt_pk_bf16_f32 v4, v16, v17
	v_mfma_f32_16x16x32_bf16 v[20:23], v[144:147], v[162:165], v[88:91]
	v_cvt_pk_bf16_f32 v5, v18, v19
	v_cvt_pk_bf16_f32 v0, v0, v1
	v_cvt_pk_bf16_f32 v1, v2, v3
	ds_write2_b64 v8, v[4:5], v[0:1] offset0:88 offset1:92
	v_cvt_pk_bf16_f32 v0, v112, v113
	v_cvt_pk_bf16_f32 v1, v114, v115
	v_cvt_pk_bf16_f32 v2, v96, v97
	v_cvt_pk_bf16_f32 v3, v98, v99
	v_add_u32_e32 v4, 0x3000, v128
	ds_write2_b64 v4, v[0:1], v[2:3] offset0:96 offset1:100
	v_cvt_pk_bf16_f32 v0, v76, v77
	v_cvt_pk_bf16_f32 v1, v78, v79
	v_cvt_pk_bf16_f32 v2, v60, v61
	v_cvt_pk_bf16_f32 v3, v62, v63
	v_mfma_f32_16x16x32_bf16 v[36:39], v[136:139], v[154:157], v[36:39]
	ds_write2_b64 v4, v[0:1], v[2:3] offset0:104 offset1:108
	v_cvt_pk_bf16_f32 v0, v44, v45
	v_cvt_pk_bf16_f32 v1, v46, v47
	v_cvt_pk_bf16_f32 v2, v28, v29
	v_cvt_pk_bf16_f32 v3, v30, v31
	ds_write2_b64 v4, v[0:1], v[2:3] offset0:112 offset1:116
	v_cvt_pk_bf16_f32 v0, v12, v13
	v_cvt_pk_bf16_f32 v1, v14, v15
	v_cvt_pk_bf16_f32 v2, v20, v21
	v_cvt_pk_bf16_f32 v3, v22, v23
	ds_write2_b64 v4, v[0:1], v[2:3] offset0:120 offset1:124
	v_lshlrev_b32_e32 v0, 3, v148
	v_and_b32_e32 v32, 0x78, v0
	v_cvt_pk_bf16_f32 v26, v36, v37
	v_cvt_pk_bf16_f32 v27, v38, v39
	v_lshl_or_b32 v134, s44, 7, v32
	ds_write2_b64 v40, v[24:25], v[26:27] offset0:48 offset1:52
	v_lshlrev_b64 v[24:25], 2, v[134:135]
	v_lshl_add_u64 v[16:17], s[10:11], 0, v[24:25]
	v_cvt_pk_bf16_f32 v72, v72, v73
	v_cvt_pk_bf16_f32 v73, v74, v75
	v_lshl_add_u64 v[12:13], v[16:17], 0, s[2:3]
	s_movk_i32 s2, 0x2000
	ds_write2_b64 v128, v[124:125], v[108:109] offset1:4
	ds_write2_b64 v128, v[92:93], v[72:73] offset0:8 offset1:12
	v_add_co_u32_e32 v8, vcc, s2, v16
	s_mov_b64 s[2:3], 0x5800
	s_waitcnt lgkmcnt(0)
	s_barrier
	v_addc_co_u32_e32 v9, vcc, 0, v17, vcc
	v_lshl_add_u64 v[20:21], v[16:17], 0, s[2:3]
	s_movk_i32 s2, 0x5000
	v_add_co_u32_e32 v16, vcc, s2, v16
	v_lshl_add_u64 v[28:29], s[12:13], 0, v[24:25]
	s_nop 0
	v_addc_co_u32_e32 v17, vcc, 0, v17, vcc
	s_nop 0
	s_nop 0
	s_nop 0
	s_nop 0
	s_nop 0
	v_ashrrev_i32_e32 v33, 4, v148
	v_mul_lo_u32 v34, v33, s51
	s_mov_b32 s44, 0
	v_lshl_add_u64 v[40:41], v[134:135], 1, s[22:23]
	v_lshl_add_u32 v44, v32, 1, v34
	v_add_u32_e32 v45, 31, v33
	s_waitcnt vmcnt(0)
	s_add_i32 s2, s92, 0xff
	s_ashr_i32 s2, s2, 12
	s_ashr_i32 s3, s92, 12
	s_cmp_eq_u32 s2, s3
	s_cbranch_scc0 .LBB0_2308
	v_mov_b32_e32 v183, 0x3e6d3388
	v_mov_b32_e32 v126, 0xbf38aa3b
	v_mov_b32_e32 v127, 0xbf38aa3b
	v_mov_b64_e32 v[180:181], s[76:77]
	v_lshlrev_b32_e32 v13, 1, v32
	v_lshl_add_u32 v222, v34, 3, v13
	v_add_u32_e32 v223, 0x11000, v222
	v_subrev_u32_e32 v213, 0x110, v222
	v_max_i32_e32 v213, v213, v13
	v_mov_b32_e32 v212, v33
	v_lshl_add_u32 v13, v33, 3, s36
	v_add_u32_e32 v13, -1, v13
	v_mad_i64_i32 v[228:229], vcc, v13, s35, v[40:41]
	ds_read_b128 v[16:19], v213
	ds_read_b128 v[20:23], v222
	ds_read_b128 v[24:27], v222 offset:272
	ds_read_b128 v[56:59], v223
	ds_read_b128 v[28:31], v222 offset:544
	ds_read_b128 v[60:63], v223 offset:272
	ds_read_b128 v[32:35], v222 offset:816
	ds_read_b128 v[64:67], v223 offset:544
	ds_read_b128 v[36:39], v222 offset:1088
	ds_read_b128 v[68:71], v223 offset:816
	ds_read_b128 v[40:43], v222 offset:1360
	ds_read_b128 v[72:75], v223 offset:1088
	ds_read_b128 v[44:47], v222 offset:1632
	ds_read_b128 v[76:79], v223 offset:1360
	ds_read_b128 v[48:51], v222 offset:1904
	ds_read_b128 v[80:83], v223 offset:1632
	ds_read_b128 v[52:55], v222 offset:2176
	ds_read_b128 v[84:87], v223 offset:1904
	s_mov_b32 s32, 1
	s_branch .LBB0_2297
.Lup_rows:
	s_mov_b32 s98, 0x1600
	s_mov_b32 s99, 0
	s_waitcnt lgkmcnt(0)
	v_lshlrev_b32_e32 v88, 16, v16
	v_and_b32_e32 v89, 0xffff0000, v16
	v_lshlrev_b32_e32 v90, 16, v17
	v_and_b32_e32 v91, 0xffff0000, v17
	v_lshlrev_b32_e32 v92, 16, v18
	v_and_b32_e32 v93, 0xffff0000, v18
	v_lshlrev_b32_e32 v94, 16, v19
	v_and_b32_e32 v95, 0xffff0000, v19
	v_lshlrev_b32_e32 v96, 16, v20
	v_and_b32_e32 v97, 0xffff0000, v20
	v_lshlrev_b32_e32 v98, 16, v21
	v_and_b32_e32 v99, 0xffff0000, v21
	v_lshlrev_b32_e32 v100, 16, v22
	v_and_b32_e32 v101, 0xffff0000, v22
	v_lshlrev_b32_e32 v102, 16, v23
	v_and_b32_e32 v103, 0xffff0000, v23
	v_lshlrev_b32_e32 v104, 16, v24
	v_and_b32_e32 v105, 0xffff0000, v24
	v_lshlrev_b32_e32 v106, 16, v25
	v_and_b32_e32 v107, 0xffff0000, v25
	v_lshlrev_b32_e32 v108, 16, v26
	v_and_b32_e32 v109, 0xffff0000, v26
	v_lshlrev_b32_e32 v110, 16, v27
	v_and_b32_e32 v111, 0xffff0000, v27
	v_pk_fma_f32 v[112:113], v[234:235], v[88:89], v[218:219]
	v_pk_fma_f32 v[152:153], v[236:237], v[90:91], v[220:221]
	v_pk_fma_f32 v[166:167], v[230:231], v[92:93], v[214:215]
	v_pk_fma_f32 v[198:199], v[232:233], v[94:95], v[216:217]
	v_pk_fma_f32 v[112:113], v[238:239], v[96:97], v[112:113]
	v_pk_fma_f32 v[152:153], v[240:241], v[98:99], v[152:153]
	v_pk_fma_f32 v[166:167], v[242:243], v[100:101], v[166:167]
	v_pk_fma_f32 v[198:199], v[244:245], v[102:103], v[198:199]
	v_pk_fma_f32 v[112:113], v[246:247], v[104:105], v[112:113]
	v_pk_fma_f32 v[152:153], v[248:249], v[106:107], v[152:153]
	v_pk_fma_f32 v[166:167], v[250:251], v[108:109], v[166:167]
	v_pk_fma_f32 v[198:199], v[252:253], v[110:111], v[198:199]
	v_fma_f32 v114, |v112|, v183, 1.0
	v_fma_f32 v115, |v113|, v183, 1.0
	v_fma_f32 v154, |v152|, v183, 1.0
	v_fma_f32 v155, |v153|, v183, 1.0
	v_fma_f32 v168, |v166|, v183, 1.0
	v_fma_f32 v169, |v167|, v183, 1.0
	v_fma_f32 v200, |v198|, v183, 1.0
	v_fma_f32 v201, |v199|, v183, 1.0
	v_mul_f32_e32 v116, v114, v115
	v_mul_f32_e32 v156, v154, v155
	v_mul_f32_e32 v170, v168, v169
	v_mul_f32_e32 v202, v200, v201
	v_pk_mul_f32 v[118:119], v[112:113], v[112:113]
	v_pk_mul_f32 v[158:159], v[152:153], v[152:153]
	v_pk_mul_f32 v[172:173], v[166:167], v[166:167]
	v_pk_mul_f32 v[204:205], v[198:199], v[198:199]
	v_rcp_f32_e32 v116, v116
	v_rcp_f32_e32 v156, v156
	v_rcp_f32_e32 v170, v170
	v_rcp_f32_e32 v202, v202
	v_pk_mul_f32 v[118:119], v[118:119], v[126:127]
	v_pk_mul_f32 v[158:159], v[158:159], v[126:127]
	v_pk_mul_f32 v[172:173], v[172:173], v[126:127]
	v_pk_mul_f32 v[204:205], v[204:205], v[126:127]
	v_pk_mul_f32 v[114:115], v[114:115], v[116:117] op_sel:[1,0] op_sel_hi:[0,0]
	v_pk_mul_f32 v[154:155], v[154:155], v[156:157] op_sel:[1,0] op_sel_hi:[0,0]
	v_pk_mul_f32 v[168:169], v[168:169], v[170:171] op_sel:[1,0] op_sel_hi:[0,0]
	v_pk_mul_f32 v[200:201], v[200:201], v[202:203] op_sel:[1,0] op_sel_hi:[0,0]
	v_exp_f32_e32 v118, v118
	v_exp_f32_e32 v119, v119
	v_exp_f32_e32 v158, v158
	v_exp_f32_e32 v159, v159
	v_exp_f32_e32 v172, v172
	v_exp_f32_e32 v173, v173
	v_exp_f32_e32 v204, v204
	v_exp_f32_e32 v205, v205
	v_pk_fma_f32 v[120:121], v[114:115], s[74:75], v[180:181] op_sel_hi:[1,0,0]
	v_pk_fma_f32 v[160:161], v[154:155], s[74:75], v[180:181] op_sel_hi:[1,0,0]
	v_pk_fma_f32 v[174:175], v[168:169], s[74:75], v[180:181] op_sel_hi:[1,0,0]
	v_pk_fma_f32 v[206:207], v[200:201], s[74:75], v[180:181] op_sel_hi:[1,0,0]
	v_pk_fma_f32 v[120:121], v[114:115], v[120:121], s[78:79] op_sel_hi:[1,1,0]
	v_pk_fma_f32 v[160:161], v[154:155], v[160:161], s[78:79] op_sel_hi:[1,1,0]
	v_pk_fma_f32 v[174:175], v[168:169], v[174:175], s[78:79] op_sel_hi:[1,1,0]
	v_pk_fma_f32 v[206:207], v[200:201], v[206:207], s[78:79] op_sel_hi:[1,1,0]
	v_pk_fma_f32 v[120:121], v[114:115], v[120:121], s[80:81] op_sel_hi:[1,1,0]
	v_pk_fma_f32 v[160:161], v[154:155], v[160:161], s[80:81] op_sel_hi:[1,1,0]
	v_pk_fma_f32 v[174:175], v[168:169], v[174:175], s[80:81] op_sel_hi:[1,1,0]
	v_pk_fma_f32 v[206:207], v[200:201], v[206:207], s[80:81] op_sel_hi:[1,1,0]
	v_pk_fma_f32 v[120:121], v[114:115], v[120:121], s[82:83] op_sel_hi:[1,1,0]
	v_pk_fma_f32 v[160:161], v[154:155], v[160:161], s[82:83] op_sel_hi:[1,1,0]
	v_pk_fma_f32 v[174:175], v[168:169], v[174:175], s[82:83] op_sel_hi:[1,1,0]
	v_pk_fma_f32 v[206:207], v[200:201], v[206:207], s[82:83] op_sel_hi:[1,1,0]
	v_pk_mul_f32 v[120:121], v[114:115], v[120:121]
	v_pk_mul_f32 v[160:161], v[154:155], v[160:161]
	v_pk_mul_f32 v[174:175], v[168:169], v[174:175]
	v_pk_mul_f32 v[206:207], v[200:201], v[206:207]
	v_pk_fma_f32 v[118:119], v[118:119], v[120:121], 1.0 op_sel_hi:[1,1,0] neg_lo:[1,0,0] neg_hi:[1,0,0]
	v_pk_fma_f32 v[158:159], v[158:159], v[160:161], 1.0 op_sel_hi:[1,1,0] neg_lo:[1,0,0] neg_hi:[1,0,0]
	v_pk_fma_f32 v[172:173], v[172:173], v[174:175], 1.0 op_sel_hi:[1,1,0] neg_lo:[1,0,0] neg_hi:[1,0,0]
	v_pk_fma_f32 v[204:205], v[204:205], v[206:207], 1.0 op_sel_hi:[1,1,0] neg_lo:[1,0,0] neg_hi:[1,0,0]
	v_bfi_b32 v119, s34, v119, v113
	v_bfi_b32 v118, s34, v118, v112
	v_bfi_b32 v159, s34, v159, v153
	v_bfi_b32 v158, s34, v158, v152
	v_bfi_b32 v173, s34, v173, v167
	v_bfi_b32 v172, s34, v172, v166
	v_bfi_b32 v205, s34, v205, v199
	v_bfi_b32 v204, s34, v204, v198
	v_pk_mul_f32 v[122:123], v[112:113], 0.5 op_sel_hi:[1,0]
	v_pk_mul_f32 v[162:163], v[152:153], 0.5 op_sel_hi:[1,0]
	v_pk_mul_f32 v[176:177], v[166:167], 0.5 op_sel_hi:[1,0]
	v_pk_mul_f32 v[208:209], v[198:199], 0.5 op_sel_hi:[1,0]
	v_lshlrev_b32_e32 v124, 16, v56
	v_and_b32_e32 v125, 0xffff0000, v56
	v_lshlrev_b32_e32 v164, 16, v57
	v_and_b32_e32 v165, 0xffff0000, v57
	v_lshlrev_b32_e32 v178, 16, v58
	v_and_b32_e32 v179, 0xffff0000, v58
	v_lshlrev_b32_e32 v210, 16, v59
	v_and_b32_e32 v211, 0xffff0000, v59
	v_pk_fma_f32 v[122:123], v[122:123], v[118:119], v[122:123]
	v_pk_fma_f32 v[162:163], v[162:163], v[158:159], v[162:163]
	v_pk_fma_f32 v[176:177], v[176:177], v[172:173], v[176:177]
	v_pk_fma_f32 v[208:209], v[208:209], v[204:205], v[208:209]
	v_pk_mul_f32 v[122:123], v[122:123], v[124:125]
	v_pk_mul_f32 v[162:163], v[162:163], v[164:165]
	v_pk_mul_f32 v[176:177], v[176:177], v[178:179]
	v_pk_mul_f32 v[208:209], v[208:209], v[210:211]
	v_cvt_pk_bf16_f32 v224, v122, v123
	v_cvt_pk_bf16_f32 v225, v162, v163
	v_cvt_pk_bf16_f32 v226, v176, v177
	v_cvt_pk_bf16_f32 v227, v208, v209
	v_cmp_ne_u32_e32 vcc, 0, v212
	s_and_saveexec_b64 s[100:101], vcc
	global_store_dwordx4 v[228:229], v[224:227], off nt
	s_mov_b64 exec, s[100:101]
	v_lshl_add_u64 v[228:229], v[228:229], 0, s[98:99]
	v_lshlrev_b32_e32 v88, 16, v28
	v_and_b32_e32 v89, 0xffff0000, v28
	v_lshlrev_b32_e32 v90, 16, v29
	v_and_b32_e32 v91, 0xffff0000, v29
	v_lshlrev_b32_e32 v92, 16, v30
	v_and_b32_e32 v93, 0xffff0000, v30
	v_lshlrev_b32_e32 v94, 16, v31
	v_and_b32_e32 v95, 0xffff0000, v31
	v_pk_fma_f32 v[112:113], v[234:235], v[96:97], v[218:219]
	v_pk_fma_f32 v[152:153], v[236:237], v[98:99], v[220:221]
	v_pk_fma_f32 v[166:167], v[230:231], v[100:101], v[214:215]
	v_pk_fma_f32 v[198:199], v[232:233], v[102:103], v[216:217]
	v_pk_fma_f32 v[112:113], v[238:239], v[104:105], v[112:113]
	v_pk_fma_f32 v[152:153], v[240:241], v[106:107], v[152:153]
	v_pk_fma_f32 v[166:167], v[242:243], v[108:109], v[166:167]
	v_pk_fma_f32 v[198:199], v[244:245], v[110:111], v[198:199]
	v_pk_fma_f32 v[112:113], v[246:247], v[88:89], v[112:113]
	v_pk_fma_f32 v[152:153], v[248:249], v[90:91], v[152:153]
	v_pk_fma_f32 v[166:167], v[250:251], v[92:93], v[166:167]
	v_pk_fma_f32 v[198:199], v[252:253], v[94:95], v[198:199]
	v_fma_f32 v114, |v112|, v183, 1.0
	v_fma_f32 v115, |v113|, v183, 1.0
	v_fma_f32 v154, |v152|, v183, 1.0
	v_fma_f32 v155, |v153|, v183, 1.0
	v_fma_f32 v168, |v166|, v183, 1.0
	v_fma_f32 v169, |v167|, v183, 1.0
	v_fma_f32 v200, |v198|, v183, 1.0
	v_fma_f32 v201, |v199|, v183, 1.0
	v_mul_f32_e32 v116, v114, v115
	v_mul_f32_e32 v156, v154, v155
	v_mul_f32_e32 v170, v168, v169
	v_mul_f32_e32 v202, v200, v201
	v_pk_mul_f32 v[118:119], v[112:113], v[112:113]
	v_pk_mul_f32 v[158:159], v[152:153], v[152:153]
	v_pk_mul_f32 v[172:173], v[166:167], v[166:167]
	v_pk_mul_f32 v[204:205], v[198:199], v[198:199]
	v_rcp_f32_e32 v116, v116
	v_rcp_f32_e32 v156, v156
	v_rcp_f32_e32 v170, v170
	v_rcp_f32_e32 v202, v202
	v_pk_mul_f32 v[118:119], v[118:119], v[126:127]
	v_pk_mul_f32 v[158:159], v[158:159], v[126:127]
	v_pk_mul_f32 v[172:173], v[172:173], v[126:127]
	v_pk_mul_f32 v[204:205], v[204:205], v[126:127]
	v_pk_mul_f32 v[114:115], v[114:115], v[116:117] op_sel:[1,0] op_sel_hi:[0,0]
	v_pk_mul_f32 v[154:155], v[154:155], v[156:157] op_sel:[1,0] op_sel_hi:[0,0]
	v_pk_mul_f32 v[168:169], v[168:169], v[170:171] op_sel:[1,0] op_sel_hi:[0,0]
	v_pk_mul_f32 v[200:201], v[200:201], v[202:203] op_sel:[1,0] op_sel_hi:[0,0]
	v_exp_f32_e32 v118, v118
	v_exp_f32_e32 v119, v119
	v_exp_f32_e32 v158, v158
	v_exp_f32_e32 v159, v159
	v_exp_f32_e32 v172, v172
	v_exp_f32_e32 v173, v173
	v_exp_f32_e32 v204, v204
	v_exp_f32_e32 v205, v205
	v_pk_fma_f32 v[120:121], v[114:115], s[74:75], v[180:181] op_sel_hi:[1,0,0]
	v_pk_fma_f32 v[160:161], v[154:155], s[74:75], v[180:181] op_sel_hi:[1,0,0]
	v_pk_fma_f32 v[174:175], v[168:169], s[74:75], v[180:181] op_sel_hi:[1,0,0]
	v_pk_fma_f32 v[206:207], v[200:201], s[74:75], v[180:181] op_sel_hi:[1,0,0]
	v_pk_fma_f32 v[120:121], v[114:115], v[120:121], s[78:79] op_sel_hi:[1,1,0]
	v_pk_fma_f32 v[160:161], v[154:155], v[160:161], s[78:79] op_sel_hi:[1,1,0]
	v_pk_fma_f32 v[174:175], v[168:169], v[174:175], s[78:79] op_sel_hi:[1,1,0]
	v_pk_fma_f32 v[206:207], v[200:201], v[206:207], s[78:79] op_sel_hi:[1,1,0]
	v_pk_fma_f32 v[120:121], v[114:115], v[120:121], s[80:81] op_sel_hi:[1,1,0]
	v_pk_fma_f32 v[160:161], v[154:155], v[160:161], s[80:81] op_sel_hi:[1,1,0]
	v_pk_fma_f32 v[174:175], v[168:169], v[174:175], s[80:81] op_sel_hi:[1,1,0]
	v_pk_fma_f32 v[206:207], v[200:201], v[206:207], s[80:81] op_sel_hi:[1,1,0]
	v_pk_fma_f32 v[120:121], v[114:115], v[120:121], s[82:83] op_sel_hi:[1,1,0]
	v_pk_fma_f32 v[160:161], v[154:155], v[160:161], s[82:83] op_sel_hi:[1,1,0]
	v_pk_fma_f32 v[174:175], v[168:169], v[174:175], s[82:83] op_sel_hi:[1,1,0]
	v_pk_fma_f32 v[206:207], v[200:201], v[206:207], s[82:83] op_sel_hi:[1,1,0]
	v_pk_mul_f32 v[120:121], v[114:115], v[120:121]
	v_pk_mul_f32 v[160:161], v[154:155], v[160:161]
	v_pk_mul_f32 v[174:175], v[168:169], v[174:175]
	v_pk_mul_f32 v[206:207], v[200:201], v[206:207]
	v_pk_fma_f32 v[118:119], v[118:119], v[120:121], 1.0 op_sel_hi:[1,1,0] neg_lo:[1,0,0] neg_hi:[1,0,0]
	v_pk_fma_f32 v[158:159], v[158:159], v[160:161], 1.0 op_sel_hi:[1,1,0] neg_lo:[1,0,0] neg_hi:[1,0,0]
	v_pk_fma_f32 v[172:173], v[172:173], v[174:175], 1.0 op_sel_hi:[1,1,0] neg_lo:[1,0,0] neg_hi:[1,0,0]
	v_pk_fma_f32 v[204:205], v[204:205], v[206:207], 1.0 op_sel_hi:[1,1,0] neg_lo:[1,0,0] neg_hi:[1,0,0]
	v_bfi_b32 v119, s34, v119, v113
	v_bfi_b32 v118, s34, v118, v112
	v_bfi_b32 v159, s34, v159, v153
	v_bfi_b32 v158, s34, v158, v152
	v_bfi_b32 v173, s34, v173, v167
	v_bfi_b32 v172, s34, v172, v166
	v_bfi_b32 v205, s34, v205, v199
	v_bfi_b32 v204, s34, v204, v198
	v_pk_mul_f32 v[122:123], v[112:113], 0.5 op_sel_hi:[1,0]
	v_pk_mul_f32 v[162:163], v[152:153], 0.5 op_sel_hi:[1,0]
	v_pk_mul_f32 v[176:177], v[166:167], 0.5 op_sel_hi:[1,0]
	v_pk_mul_f32 v[208:209], v[198:199], 0.5 op_sel_hi:[1,0]
	v_lshlrev_b32_e32 v124, 16, v60
	v_and_b32_e32 v125, 0xffff0000, v60
	v_lshlrev_b32_e32 v164, 16, v61
	v_and_b32_e32 v165, 0xffff0000, v61
	v_lshlrev_b32_e32 v178, 16, v62
	v_and_b32_e32 v179, 0xffff0000, v62
	v_lshlrev_b32_e32 v210, 16, v63
	v_and_b32_e32 v211, 0xffff0000, v63
	v_pk_fma_f32 v[122:123], v[122:123], v[118:119], v[122:123]
	v_pk_fma_f32 v[162:163], v[162:163], v[158:159], v[162:163]
	v_pk_fma_f32 v[176:177], v[176:177], v[172:173], v[176:177]
	v_pk_fma_f32 v[208:209], v[208:209], v[204:205], v[208:209]
	v_pk_mul_f32 v[122:123], v[122:123], v[124:125]
	v_pk_mul_f32 v[162:163], v[162:163], v[164:165]
	v_pk_mul_f32 v[176:177], v[176:177], v[178:179]
	v_pk_mul_f32 v[208:209], v[208:209], v[210:211]
	v_cvt_pk_bf16_f32 v224, v122, v123
	v_cvt_pk_bf16_f32 v225, v162, v163
	v_cvt_pk_bf16_f32 v226, v176, v177
	v_cvt_pk_bf16_f32 v227, v208, v209
	global_store_dwordx4 v[228:229], v[224:227], off nt
	v_lshl_add_u64 v[228:229], v[228:229], 0, s[98:99]
	v_lshlrev_b32_e32 v96, 16, v32
	v_and_b32_e32 v97, 0xffff0000, v32
	v_lshlrev_b32_e32 v98, 16, v33
	v_and_b32_e32 v99, 0xffff0000, v33
	v_lshlrev_b32_e32 v100, 16, v34
	v_and_b32_e32 v101, 0xffff0000, v34
	v_lshlrev_b32_e32 v102, 16, v35
	v_and_b32_e32 v103, 0xffff0000, v35
	v_pk_fma_f32 v[112:113], v[234:235], v[104:105], v[218:219]
	v_pk_fma_f32 v[152:153], v[236:237], v[106:107], v[220:221]
	v_pk_fma_f32 v[166:167], v[230:231], v[108:109], v[214:215]
	v_pk_fma_f32 v[198:199], v[232:233], v[110:111], v[216:217]
	v_pk_fma_f32 v[112:113], v[238:239], v[88:89], v[112:113]
	v_pk_fma_f32 v[152:153], v[240:241], v[90:91], v[152:153]
	v_pk_fma_f32 v[166:167], v[242:243], v[92:93], v[166:167]
	v_pk_fma_f32 v[198:199], v[244:245], v[94:95], v[198:199]
	v_pk_fma_f32 v[112:113], v[246:247], v[96:97], v[112:113]
	v_pk_fma_f32 v[152:153], v[248:249], v[98:99], v[152:153]
	v_pk_fma_f32 v[166:167], v[250:251], v[100:101], v[166:167]
	v_pk_fma_f32 v[198:199], v[252:253], v[102:103], v[198:199]
	v_fma_f32 v114, |v112|, v183, 1.0
	v_fma_f32 v115, |v113|, v183, 1.0
	v_fma_f32 v154, |v152|, v183, 1.0
	v_fma_f32 v155, |v153|, v183, 1.0
	v_fma_f32 v168, |v166|, v183, 1.0
	v_fma_f32 v169, |v167|, v183, 1.0
	v_fma_f32 v200, |v198|, v183, 1.0
	v_fma_f32 v201, |v199|, v183, 1.0
	v_mul_f32_e32 v116, v114, v115
	v_mul_f32_e32 v156, v154, v155
	v_mul_f32_e32 v170, v168, v169
	v_mul_f32_e32 v202, v200, v201
	v_pk_mul_f32 v[118:119], v[112:113], v[112:113]
	v_pk_mul_f32 v[158:159], v[152:153], v[152:153]
	v_pk_mul_f32 v[172:173], v[166:167], v[166:167]
	v_pk_mul_f32 v[204:205], v[198:199], v[198:199]
	v_rcp_f32_e32 v116, v116
	v_rcp_f32_e32 v156, v156
	v_rcp_f32_e32 v170, v170
	v_rcp_f32_e32 v202, v202
	v_pk_mul_f32 v[118:119], v[118:119], v[126:127]
	v_pk_mul_f32 v[158:159], v[158:159], v[126:127]
	v_pk_mul_f32 v[172:173], v[172:173], v[126:127]
	v_pk_mul_f32 v[204:205], v[204:205], v[126:127]
	v_pk_mul_f32 v[114:115], v[114:115], v[116:117] op_sel:[1,0] op_sel_hi:[0,0]
	v_pk_mul_f32 v[154:155], v[154:155], v[156:157] op_sel:[1,0] op_sel_hi:[0,0]
	v_pk_mul_f32 v[168:169], v[168:169], v[170:171] op_sel:[1,0] op_sel_hi:[0,0]
	v_pk_mul_f32 v[200:201], v[200:201], v[202:203] op_sel:[1,0] op_sel_hi:[0,0]
	v_exp_f32_e32 v118, v118
	v_exp_f32_e32 v119, v119
	v_exp_f32_e32 v158, v158
	v_exp_f32_e32 v159, v159
	v_exp_f32_e32 v172, v172
	v_exp_f32_e32 v173, v173
	v_exp_f32_e32 v204, v204
	v_exp_f32_e32 v205, v205
	v_pk_fma_f32 v[120:121], v[114:115], s[74:75], v[180:181] op_sel_hi:[1,0,0]
	v_pk_fma_f32 v[160:161], v[154:155], s[74:75], v[180:181] op_sel_hi:[1,0,0]
	v_pk_fma_f32 v[174:175], v[168:169], s[74:75], v[180:181] op_sel_hi:[1,0,0]
	v_pk_fma_f32 v[206:207], v[200:201], s[74:75], v[180:181] op_sel_hi:[1,0,0]
	v_pk_fma_f32 v[120:121], v[114:115], v[120:121], s[78:79] op_sel_hi:[1,1,0]
	v_pk_fma_f32 v[160:161], v[154:155], v[160:161], s[78:79] op_sel_hi:[1,1,0]
	v_pk_fma_f32 v[174:175], v[168:169], v[174:175], s[78:79] op_sel_hi:[1,1,0]
	v_pk_fma_f32 v[206:207], v[200:201], v[206:207], s[78:79] op_sel_hi:[1,1,0]
	v_pk_fma_f32 v[120:121], v[114:115], v[120:121], s[80:81] op_sel_hi:[1,1,0]
	v_pk_fma_f32 v[160:161], v[154:155], v[160:161], s[80:81] op_sel_hi:[1,1,0]
	v_pk_fma_f32 v[174:175], v[168:169], v[174:175], s[80:81] op_sel_hi:[1,1,0]
	v_pk_fma_f32 v[206:207], v[200:201], v[206:207], s[80:81] op_sel_hi:[1,1,0]
	v_pk_fma_f32 v[120:121], v[114:115], v[120:121], s[82:83] op_sel_hi:[1,1,0]
	v_pk_fma_f32 v[160:161], v[154:155], v[160:161], s[82:83] op_sel_hi:[1,1,0]
	v_pk_fma_f32 v[174:175], v[168:169], v[174:175], s[82:83] op_sel_hi:[1,1,0]
	v_pk_fma_f32 v[206:207], v[200:201], v[206:207], s[82:83] op_sel_hi:[1,1,0]
	v_pk_mul_f32 v[120:121], v[114:115], v[120:121]
	v_pk_mul_f32 v[160:161], v[154:155], v[160:161]
	v_pk_mul_f32 v[174:175], v[168:169], v[174:175]
	v_pk_mul_f32 v[206:207], v[200:201], v[206:207]
	v_pk_fma_f32 v[118:119], v[118:119], v[120:121], 1.0 op_sel_hi:[1,1,0] neg_lo:[1,0,0] neg_hi:[1,0,0]
	v_pk_fma_f32 v[158:159], v[158:159], v[160:161], 1.0 op_sel_hi:[1,1,0] neg_lo:[1,0,0] neg_hi:[1,0,0]
	v_pk_fma_f32 v[172:173], v[172:173], v[174:175], 1.0 op_sel_hi:[1,1,0] neg_lo:[1,0,0] neg_hi:[1,0,0]
	v_pk_fma_f32 v[204:205], v[204:205], v[206:207], 1.0 op_sel_hi:[1,1,0] neg_lo:[1,0,0] neg_hi:[1,0,0]
	v_bfi_b32 v119, s34, v119, v113
	v_bfi_b32 v118, s34, v118, v112
	v_bfi_b32 v159, s34, v159, v153
	v_bfi_b32 v158, s34, v158, v152
	v_bfi_b32 v173, s34, v173, v167
	v_bfi_b32 v172, s34, v172, v166
	v_bfi_b32 v205, s34, v205, v199
	v_bfi_b32 v204, s34, v204, v198
	v_pk_mul_f32 v[122:123], v[112:113], 0.5 op_sel_hi:[1,0]
	v_pk_mul_f32 v[162:163], v[152:153], 0.5 op_sel_hi:[1,0]
	v_pk_mul_f32 v[176:177], v[166:167], 0.5 op_sel_hi:[1,0]
	v_pk_mul_f32 v[208:209], v[198:199], 0.5 op_sel_hi:[1,0]
	v_lshlrev_b32_e32 v124, 16, v64
	v_and_b32_e32 v125, 0xffff0000, v64
	v_lshlrev_b32_e32 v164, 16, v65
	v_and_b32_e32 v165, 0xffff0000, v65
	v_lshlrev_b32_e32 v178, 16, v66
	v_and_b32_e32 v179, 0xffff0000, v66
	v_lshlrev_b32_e32 v210, 16, v67
	v_and_b32_e32 v211, 0xffff0000, v67
	v_pk_fma_f32 v[122:123], v[122:123], v[118:119], v[122:123]
	v_pk_fma_f32 v[162:163], v[162:163], v[158:159], v[162:163]
	v_pk_fma_f32 v[176:177], v[176:177], v[172:173], v[176:177]
	v_pk_fma_f32 v[208:209], v[208:209], v[204:205], v[208:209]
	v_pk_mul_f32 v[122:123], v[122:123], v[124:125]
	v_pk_mul_f32 v[162:163], v[162:163], v[164:165]
	v_pk_mul_f32 v[176:177], v[176:177], v[178:179]
	v_pk_mul_f32 v[208:209], v[208:209], v[210:211]
	v_cvt_pk_bf16_f32 v224, v122, v123
	v_cvt_pk_bf16_f32 v225, v162, v163
	v_cvt_pk_bf16_f32 v226, v176, v177
	v_cvt_pk_bf16_f32 v227, v208, v209
	global_store_dwordx4 v[228:229], v[224:227], off nt
	v_lshl_add_u64 v[228:229], v[228:229], 0, s[98:99]
	v_lshlrev_b32_e32 v104, 16, v36
	v_and_b32_e32 v105, 0xffff0000, v36
	v_lshlrev_b32_e32 v106, 16, v37
	v_and_b32_e32 v107, 0xffff0000, v37
	v_lshlrev_b32_e32 v108, 16, v38
	v_and_b32_e32 v109, 0xffff0000, v38
	v_lshlrev_b32_e32 v110, 16, v39
	v_and_b32_e32 v111, 0xffff0000, v39
	v_pk_fma_f32 v[112:113], v[234:235], v[88:89], v[218:219]
	v_pk_fma_f32 v[152:153], v[236:237], v[90:91], v[220:221]
	v_pk_fma_f32 v[166:167], v[230:231], v[92:93], v[214:215]
	v_pk_fma_f32 v[198:199], v[232:233], v[94:95], v[216:217]
	v_pk_fma_f32 v[112:113], v[238:239], v[96:97], v[112:113]
	v_pk_fma_f32 v[152:153], v[240:241], v[98:99], v[152:153]
	v_pk_fma_f32 v[166:167], v[242:243], v[100:101], v[166:167]
	v_pk_fma_f32 v[198:199], v[244:245], v[102:103], v[198:199]
	v_pk_fma_f32 v[112:113], v[246:247], v[104:105], v[112:113]
	v_pk_fma_f32 v[152:153], v[248:249], v[106:107], v[152:153]
	v_pk_fma_f32 v[166:167], v[250:251], v[108:109], v[166:167]
	v_pk_fma_f32 v[198:199], v[252:253], v[110:111], v[198:199]
	v_fma_f32 v114, |v112|, v183, 1.0
	v_fma_f32 v115, |v113|, v183, 1.0
	v_fma_f32 v154, |v152|, v183, 1.0
	v_fma_f32 v155, |v153|, v183, 1.0
	v_fma_f32 v168, |v166|, v183, 1.0
	v_fma_f32 v169, |v167|, v183, 1.0
	v_fma_f32 v200, |v198|, v183, 1.0
	v_fma_f32 v201, |v199|, v183, 1.0
	v_mul_f32_e32 v116, v114, v115
	v_mul_f32_e32 v156, v154, v155
	v_mul_f32_e32 v170, v168, v169
	v_mul_f32_e32 v202, v200, v201
	v_pk_mul_f32 v[118:119], v[112:113], v[112:113]
	v_pk_mul_f32 v[158:159], v[152:153], v[152:153]
	v_pk_mul_f32 v[172:173], v[166:167], v[166:167]
	v_pk_mul_f32 v[204:205], v[198:199], v[198:199]
	v_rcp_f32_e32 v116, v116
	v_rcp_f32_e32 v156, v156
	v_rcp_f32_e32 v170, v170
	v_rcp_f32_e32 v202, v202
	v_pk_mul_f32 v[118:119], v[118:119], v[126:127]
	v_pk_mul_f32 v[158:159], v[158:159], v[126:127]
	v_pk_mul_f32 v[172:173], v[172:173], v[126:127]
	v_pk_mul_f32 v[204:205], v[204:205], v[126:127]
	v_pk_mul_f32 v[114:115], v[114:115], v[116:117] op_sel:[1,0] op_sel_hi:[0,0]
	v_pk_mul_f32 v[154:155], v[154:155], v[156:157] op_sel:[1,0] op_sel_hi:[0,0]
	v_pk_mul_f32 v[168:169], v[168:169], v[170:171] op_sel:[1,0] op_sel_hi:[0,0]
	v_pk_mul_f32 v[200:201], v[200:201], v[202:203] op_sel:[1,0] op_sel_hi:[0,0]
	v_exp_f32_e32 v118, v118
	v_exp_f32_e32 v119, v119
	v_exp_f32_e32 v158, v158
	v_exp_f32_e32 v159, v159
	v_exp_f32_e32 v172, v172
	v_exp_f32_e32 v173, v173
	v_exp_f32_e32 v204, v204
	v_exp_f32_e32 v205, v205
	v_pk_fma_f32 v[120:121], v[114:115], s[74:75], v[180:181] op_sel_hi:[1,0,0]
	v_pk_fma_f32 v[160:161], v[154:155], s[74:75], v[180:181] op_sel_hi:[1,0,0]
	v_pk_fma_f32 v[174:175], v[168:169], s[74:75], v[180:181] op_sel_hi:[1,0,0]
	v_pk_fma_f32 v[206:207], v[200:201], s[74:75], v[180:181] op_sel_hi:[1,0,0]
	v_pk_fma_f32 v[120:121], v[114:115], v[120:121], s[78:79] op_sel_hi:[1,1,0]
	v_pk_fma_f32 v[160:161], v[154:155], v[160:161], s[78:79] op_sel_hi:[1,1,0]
	v_pk_fma_f32 v[174:175], v[168:169], v[174:175], s[78:79] op_sel_hi:[1,1,0]
	v_pk_fma_f32 v[206:207], v[200:201], v[206:207], s[78:79] op_sel_hi:[1,1,0]
	v_pk_fma_f32 v[120:121], v[114:115], v[120:121], s[80:81] op_sel_hi:[1,1,0]
	v_pk_fma_f32 v[160:161], v[154:155], v[160:161], s[80:81] op_sel_hi:[1,1,0]
	v_pk_fma_f32 v[174:175], v[168:169], v[174:175], s[80:81] op_sel_hi:[1,1,0]
	v_pk_fma_f32 v[206:207], v[200:201], v[206:207], s[80:81] op_sel_hi:[1,1,0]
	v_pk_fma_f32 v[120:121], v[114:115], v[120:121], s[82:83] op_sel_hi:[1,1,0]
	v_pk_fma_f32 v[160:161], v[154:155], v[160:161], s[82:83] op_sel_hi:[1,1,0]
	v_pk_fma_f32 v[174:175], v[168:169], v[174:175], s[82:83] op_sel_hi:[1,1,0]
	v_pk_fma_f32 v[206:207], v[200:201], v[206:207], s[82:83] op_sel_hi:[1,1,0]
	v_pk_mul_f32 v[120:121], v[114:115], v[120:121]
	v_pk_mul_f32 v[160:161], v[154:155], v[160:161]
	v_pk_mul_f32 v[174:175], v[168:169], v[174:175]
	v_pk_mul_f32 v[206:207], v[200:201], v[206:207]
	v_pk_fma_f32 v[118:119], v[118:119], v[120:121], 1.0 op_sel_hi:[1,1,0] neg_lo:[1,0,0] neg_hi:[1,0,0]
	v_pk_fma_f32 v[158:159], v[158:159], v[160:161], 1.0 op_sel_hi:[1,1,0] neg_lo:[1,0,0] neg_hi:[1,0,0]
	v_pk_fma_f32 v[172:173], v[172:173], v[174:175], 1.0 op_sel_hi:[1,1,0] neg_lo:[1,0,0] neg_hi:[1,0,0]
	v_pk_fma_f32 v[204:205], v[204:205], v[206:207], 1.0 op_sel_hi:[1,1,0] neg_lo:[1,0,0] neg_hi:[1,0,0]
	v_bfi_b32 v119, s34, v119, v113
	v_bfi_b32 v118, s34, v118, v112
	v_bfi_b32 v159, s34, v159, v153
	v_bfi_b32 v158, s34, v158, v152
	v_bfi_b32 v173, s34, v173, v167
	v_bfi_b32 v172, s34, v172, v166
	v_bfi_b32 v205, s34, v205, v199
	v_bfi_b32 v204, s34, v204, v198
	v_pk_mul_f32 v[122:123], v[112:113], 0.5 op_sel_hi:[1,0]
	v_pk_mul_f32 v[162:163], v[152:153], 0.5 op_sel_hi:[1,0]
	v_pk_mul_f32 v[176:177], v[166:167], 0.5 op_sel_hi:[1,0]
	v_pk_mul_f32 v[208:209], v[198:199], 0.5 op_sel_hi:[1,0]
	v_lshlrev_b32_e32 v124, 16, v68
	v_and_b32_e32 v125, 0xffff0000, v68
	v_lshlrev_b32_e32 v164, 16, v69
	v_and_b32_e32 v165, 0xffff0000, v69
	v_lshlrev_b32_e32 v178, 16, v70
	v_and_b32_e32 v179, 0xffff0000, v70
	v_lshlrev_b32_e32 v210, 16, v71
	v_and_b32_e32 v211, 0xffff0000, v71
	v_pk_fma_f32 v[122:123], v[122:123], v[118:119], v[122:123]
	v_pk_fma_f32 v[162:163], v[162:163], v[158:159], v[162:163]
	v_pk_fma_f32 v[176:177], v[176:177], v[172:173], v[176:177]
	v_pk_fma_f32 v[208:209], v[208:209], v[204:205], v[208:209]
	v_pk_mul_f32 v[122:123], v[122:123], v[124:125]
	v_pk_mul_f32 v[162:163], v[162:163], v[164:165]
	v_pk_mul_f32 v[176:177], v[176:177], v[178:179]
	v_pk_mul_f32 v[208:209], v[208:209], v[210:211]
	v_cvt_pk_bf16_f32 v224, v122, v123
	v_cvt_pk_bf16_f32 v225, v162, v163
	v_cvt_pk_bf16_f32 v226, v176, v177
	v_cvt_pk_bf16_f32 v227, v208, v209
	global_store_dwordx4 v[228:229], v[224:227], off nt
	v_lshl_add_u64 v[228:229], v[228:229], 0, s[98:99]
	v_lshlrev_b32_e32 v88, 16, v40
	v_and_b32_e32 v89, 0xffff0000, v40
	v_lshlrev_b32_e32 v90, 16, v41
	v_and_b32_e32 v91, 0xffff0000, v41
	v_lshlrev_b32_e32 v92, 16, v42
	v_and_b32_e32 v93, 0xffff0000, v42
	v_lshlrev_b32_e32 v94, 16, v43
	v_and_b32_e32 v95, 0xffff0000, v43
	v_pk_fma_f32 v[112:113], v[234:235], v[96:97], v[218:219]
	v_pk_fma_f32 v[152:153], v[236:237], v[98:99], v[220:221]
	v_pk_fma_f32 v[166:167], v[230:231], v[100:101], v[214:215]
	v_pk_fma_f32 v[198:199], v[232:233], v[102:103], v[216:217]
	v_pk_fma_f32 v[112:113], v[238:239], v[104:105], v[112:113]
	v_pk_fma_f32 v[152:153], v[240:241], v[106:107], v[152:153]
	v_pk_fma_f32 v[166:167], v[242:243], v[108:109], v[166:167]
	v_pk_fma_f32 v[198:199], v[244:245], v[110:111], v[198:199]
	v_pk_fma_f32 v[112:113], v[246:247], v[88:89], v[112:113]
	v_pk_fma_f32 v[152:153], v[248:249], v[90:91], v[152:153]
	v_pk_fma_f32 v[166:167], v[250:251], v[92:93], v[166:167]
	v_pk_fma_f32 v[198:199], v[252:253], v[94:95], v[198:199]
	v_fma_f32 v114, |v112|, v183, 1.0
	v_fma_f32 v115, |v113|, v183, 1.0
	v_fma_f32 v154, |v152|, v183, 1.0
	v_fma_f32 v155, |v153|, v183, 1.0
	v_fma_f32 v168, |v166|, v183, 1.0
	v_fma_f32 v169, |v167|, v183, 1.0
	v_fma_f32 v200, |v198|, v183, 1.0
	v_fma_f32 v201, |v199|, v183, 1.0
	v_mul_f32_e32 v116, v114, v115
	v_mul_f32_e32 v156, v154, v155
	v_mul_f32_e32 v170, v168, v169
	v_mul_f32_e32 v202, v200, v201
	v_pk_mul_f32 v[118:119], v[112:113], v[112:113]
	v_pk_mul_f32 v[158:159], v[152:153], v[152:153]
	v_pk_mul_f32 v[172:173], v[166:167], v[166:167]
	v_pk_mul_f32 v[204:205], v[198:199], v[198:199]
	v_rcp_f32_e32 v116, v116
	v_rcp_f32_e32 v156, v156
	v_rcp_f32_e32 v170, v170
	v_rcp_f32_e32 v202, v202
	v_pk_mul_f32 v[118:119], v[118:119], v[126:127]
	v_pk_mul_f32 v[158:159], v[158:159], v[126:127]
	v_pk_mul_f32 v[172:173], v[172:173], v[126:127]
	v_pk_mul_f32 v[204:205], v[204:205], v[126:127]
	v_pk_mul_f32 v[114:115], v[114:115], v[116:117] op_sel:[1,0] op_sel_hi:[0,0]
	v_pk_mul_f32 v[154:155], v[154:155], v[156:157] op_sel:[1,0] op_sel_hi:[0,0]
	v_pk_mul_f32 v[168:169], v[168:169], v[170:171] op_sel:[1,0] op_sel_hi:[0,0]
	v_pk_mul_f32 v[200:201], v[200:201], v[202:203] op_sel:[1,0] op_sel_hi:[0,0]
	v_exp_f32_e32 v118, v118
	v_exp_f32_e32 v119, v119
	v_exp_f32_e32 v158, v158
	v_exp_f32_e32 v159, v159
	v_exp_f32_e32 v172, v172
	v_exp_f32_e32 v173, v173
	v_exp_f32_e32 v204, v204
	v_exp_f32_e32 v205, v205
	v_pk_fma_f32 v[120:121], v[114:115], s[74:75], v[180:181] op_sel_hi:[1,0,0]
	v_pk_fma_f32 v[160:161], v[154:155], s[74:75], v[180:181] op_sel_hi:[1,0,0]
	v_pk_fma_f32 v[174:175], v[168:169], s[74:75], v[180:181] op_sel_hi:[1,0,0]
	v_pk_fma_f32 v[206:207], v[200:201], s[74:75], v[180:181] op_sel_hi:[1,0,0]
	v_pk_fma_f32 v[120:121], v[114:115], v[120:121], s[78:79] op_sel_hi:[1,1,0]
	v_pk_fma_f32 v[160:161], v[154:155], v[160:161], s[78:79] op_sel_hi:[1,1,0]
	v_pk_fma_f32 v[174:175], v[168:169], v[174:175], s[78:79] op_sel_hi:[1,1,0]
	v_pk_fma_f32 v[206:207], v[200:201], v[206:207], s[78:79] op_sel_hi:[1,1,0]
	v_pk_fma_f32 v[120:121], v[114:115], v[120:121], s[80:81] op_sel_hi:[1,1,0]
	v_pk_fma_f32 v[160:161], v[154:155], v[160:161], s[80:81] op_sel_hi:[1,1,0]
	v_pk_fma_f32 v[174:175], v[168:169], v[174:175], s[80:81] op_sel_hi:[1,1,0]
	v_pk_fma_f32 v[206:207], v[200:201], v[206:207], s[80:81] op_sel_hi:[1,1,0]
	v_pk_fma_f32 v[120:121], v[114:115], v[120:121], s[82:83] op_sel_hi:[1,1,0]
	v_pk_fma_f32 v[160:161], v[154:155], v[160:161], s[82:83] op_sel_hi:[1,1,0]
	v_pk_fma_f32 v[174:175], v[168:169], v[174:175], s[82:83] op_sel_hi:[1,1,0]
	v_pk_fma_f32 v[206:207], v[200:201], v[206:207], s[82:83] op_sel_hi:[1,1,0]
	v_pk_mul_f32 v[120:121], v[114:115], v[120:121]
	v_pk_mul_f32 v[160:161], v[154:155], v[160:161]
	v_pk_mul_f32 v[174:175], v[168:169], v[174:175]
	v_pk_mul_f32 v[206:207], v[200:201], v[206:207]
	v_pk_fma_f32 v[118:119], v[118:119], v[120:121], 1.0 op_sel_hi:[1,1,0] neg_lo:[1,0,0] neg_hi:[1,0,0]
	v_pk_fma_f32 v[158:159], v[158:159], v[160:161], 1.0 op_sel_hi:[1,1,0] neg_lo:[1,0,0] neg_hi:[1,0,0]
	v_pk_fma_f32 v[172:173], v[172:173], v[174:175], 1.0 op_sel_hi:[1,1,0] neg_lo:[1,0,0] neg_hi:[1,0,0]
	v_pk_fma_f32 v[204:205], v[204:205], v[206:207], 1.0 op_sel_hi:[1,1,0] neg_lo:[1,0,0] neg_hi:[1,0,0]
	v_bfi_b32 v119, s34, v119, v113
	v_bfi_b32 v118, s34, v118, v112
	v_bfi_b32 v159, s34, v159, v153
	v_bfi_b32 v158, s34, v158, v152
	v_bfi_b32 v173, s34, v173, v167
	v_bfi_b32 v172, s34, v172, v166
	v_bfi_b32 v205, s34, v205, v199
	v_bfi_b32 v204, s34, v204, v198
	v_pk_mul_f32 v[122:123], v[112:113], 0.5 op_sel_hi:[1,0]
	v_pk_mul_f32 v[162:163], v[152:153], 0.5 op_sel_hi:[1,0]
	v_pk_mul_f32 v[176:177], v[166:167], 0.5 op_sel_hi:[1,0]
	v_pk_mul_f32 v[208:209], v[198:199], 0.5 op_sel_hi:[1,0]
	v_lshlrev_b32_e32 v124, 16, v72
	v_and_b32_e32 v125, 0xffff0000, v72
	v_lshlrev_b32_e32 v164, 16, v73
	v_and_b32_e32 v165, 0xffff0000, v73
	v_lshlrev_b32_e32 v178, 16, v74
	v_and_b32_e32 v179, 0xffff0000, v74
	v_lshlrev_b32_e32 v210, 16, v75
	v_and_b32_e32 v211, 0xffff0000, v75
	v_pk_fma_f32 v[122:123], v[122:123], v[118:119], v[122:123]
	v_pk_fma_f32 v[162:163], v[162:163], v[158:159], v[162:163]
	v_pk_fma_f32 v[176:177], v[176:177], v[172:173], v[176:177]
	v_pk_fma_f32 v[208:209], v[208:209], v[204:205], v[208:209]
	v_pk_mul_f32 v[122:123], v[122:123], v[124:125]
	v_pk_mul_f32 v[162:163], v[162:163], v[164:165]
	v_pk_mul_f32 v[176:177], v[176:177], v[178:179]
	v_pk_mul_f32 v[208:209], v[208:209], v[210:211]
	v_cvt_pk_bf16_f32 v224, v122, v123
	v_cvt_pk_bf16_f32 v225, v162, v163
	v_cvt_pk_bf16_f32 v226, v176, v177
	v_cvt_pk_bf16_f32 v227, v208, v209
	global_store_dwordx4 v[228:229], v[224:227], off nt
	v_lshl_add_u64 v[228:229], v[228:229], 0, s[98:99]
	v_lshlrev_b32_e32 v96, 16, v44
	v_and_b32_e32 v97, 0xffff0000, v44
	v_lshlrev_b32_e32 v98, 16, v45
	v_and_b32_e32 v99, 0xffff0000, v45
	v_lshlrev_b32_e32 v100, 16, v46
	v_and_b32_e32 v101, 0xffff0000, v46
	v_lshlrev_b32_e32 v102, 16, v47
	v_and_b32_e32 v103, 0xffff0000, v47
	v_pk_fma_f32 v[112:113], v[234:235], v[104:105], v[218:219]
	v_pk_fma_f32 v[152:153], v[236:237], v[106:107], v[220:221]
	v_pk_fma_f32 v[166:167], v[230:231], v[108:109], v[214:215]
	v_pk_fma_f32 v[198:199], v[232:233], v[110:111], v[216:217]
	v_pk_fma_f32 v[112:113], v[238:239], v[88:89], v[112:113]
	v_pk_fma_f32 v[152:153], v[240:241], v[90:91], v[152:153]
	v_pk_fma_f32 v[166:167], v[242:243], v[92:93], v[166:167]
	v_pk_fma_f32 v[198:199], v[244:245], v[94:95], v[198:199]
	v_pk_fma_f32 v[112:113], v[246:247], v[96:97], v[112:113]
	v_pk_fma_f32 v[152:153], v[248:249], v[98:99], v[152:153]
	v_pk_fma_f32 v[166:167], v[250:251], v[100:101], v[166:167]
	v_pk_fma_f32 v[198:199], v[252:253], v[102:103], v[198:199]
	v_fma_f32 v114, |v112|, v183, 1.0
	v_fma_f32 v115, |v113|, v183, 1.0
	v_fma_f32 v154, |v152|, v183, 1.0
	v_fma_f32 v155, |v153|, v183, 1.0
	v_fma_f32 v168, |v166|, v183, 1.0
	v_fma_f32 v169, |v167|, v183, 1.0
	v_fma_f32 v200, |v198|, v183, 1.0
	v_fma_f32 v201, |v199|, v183, 1.0
	v_mul_f32_e32 v116, v114, v115
	v_mul_f32_e32 v156, v154, v155
	v_mul_f32_e32 v170, v168, v169
	v_mul_f32_e32 v202, v200, v201
	v_pk_mul_f32 v[118:119], v[112:113], v[112:113]
	v_pk_mul_f32 v[158:159], v[152:153], v[152:153]
	v_pk_mul_f32 v[172:173], v[166:167], v[166:167]
	v_pk_mul_f32 v[204:205], v[198:199], v[198:199]
	v_rcp_f32_e32 v116, v116
	v_rcp_f32_e32 v156, v156
	v_rcp_f32_e32 v170, v170
	v_rcp_f32_e32 v202, v202
	v_pk_mul_f32 v[118:119], v[118:119], v[126:127]
	v_pk_mul_f32 v[158:159], v[158:159], v[126:127]
	v_pk_mul_f32 v[172:173], v[172:173], v[126:127]
	v_pk_mul_f32 v[204:205], v[204:205], v[126:127]
	v_pk_mul_f32 v[114:115], v[114:115], v[116:117] op_sel:[1,0] op_sel_hi:[0,0]
	v_pk_mul_f32 v[154:155], v[154:155], v[156:157] op_sel:[1,0] op_sel_hi:[0,0]
	v_pk_mul_f32 v[168:169], v[168:169], v[170:171] op_sel:[1,0] op_sel_hi:[0,0]
	v_pk_mul_f32 v[200:201], v[200:201], v[202:203] op_sel:[1,0] op_sel_hi:[0,0]
	v_exp_f32_e32 v118, v118
	v_exp_f32_e32 v119, v119
	v_exp_f32_e32 v158, v158
	v_exp_f32_e32 v159, v159
	v_exp_f32_e32 v172, v172
	v_exp_f32_e32 v173, v173
	v_exp_f32_e32 v204, v204
	v_exp_f32_e32 v205, v205
	v_pk_fma_f32 v[120:121], v[114:115], s[74:75], v[180:181] op_sel_hi:[1,0,0]
	v_pk_fma_f32 v[160:161], v[154:155], s[74:75], v[180:181] op_sel_hi:[1,0,0]
	v_pk_fma_f32 v[174:175], v[168:169], s[74:75], v[180:181] op_sel_hi:[1,0,0]
	v_pk_fma_f32 v[206:207], v[200:201], s[74:75], v[180:181] op_sel_hi:[1,0,0]
	v_pk_fma_f32 v[120:121], v[114:115], v[120:121], s[78:79] op_sel_hi:[1,1,0]
	v_pk_fma_f32 v[160:161], v[154:155], v[160:161], s[78:79] op_sel_hi:[1,1,0]
	v_pk_fma_f32 v[174:175], v[168:169], v[174:175], s[78:79] op_sel_hi:[1,1,0]
	v_pk_fma_f32 v[206:207], v[200:201], v[206:207], s[78:79] op_sel_hi:[1,1,0]
	v_pk_fma_f32 v[120:121], v[114:115], v[120:121], s[80:81] op_sel_hi:[1,1,0]
	v_pk_fma_f32 v[160:161], v[154:155], v[160:161], s[80:81] op_sel_hi:[1,1,0]
	v_pk_fma_f32 v[174:175], v[168:169], v[174:175], s[80:81] op_sel_hi:[1,1,0]
	v_pk_fma_f32 v[206:207], v[200:201], v[206:207], s[80:81] op_sel_hi:[1,1,0]
	v_pk_fma_f32 v[120:121], v[114:115], v[120:121], s[82:83] op_sel_hi:[1,1,0]
	v_pk_fma_f32 v[160:161], v[154:155], v[160:161], s[82:83] op_sel_hi:[1,1,0]
	v_pk_fma_f32 v[174:175], v[168:169], v[174:175], s[82:83] op_sel_hi:[1,1,0]
	v_pk_fma_f32 v[206:207], v[200:201], v[206:207], s[82:83] op_sel_hi:[1,1,0]
	v_pk_mul_f32 v[120:121], v[114:115], v[120:121]
	v_pk_mul_f32 v[160:161], v[154:155], v[160:161]
	v_pk_mul_f32 v[174:175], v[168:169], v[174:175]
	v_pk_mul_f32 v[206:207], v[200:201], v[206:207]
	v_pk_fma_f32 v[118:119], v[118:119], v[120:121], 1.0 op_sel_hi:[1,1,0] neg_lo:[1,0,0] neg_hi:[1,0,0]
	v_pk_fma_f32 v[158:159], v[158:159], v[160:161], 1.0 op_sel_hi:[1,1,0] neg_lo:[1,0,0] neg_hi:[1,0,0]
	v_pk_fma_f32 v[172:173], v[172:173], v[174:175], 1.0 op_sel_hi:[1,1,0] neg_lo:[1,0,0] neg_hi:[1,0,0]
	v_pk_fma_f32 v[204:205], v[204:205], v[206:207], 1.0 op_sel_hi:[1,1,0] neg_lo:[1,0,0] neg_hi:[1,0,0]
	v_bfi_b32 v119, s34, v119, v113
	v_bfi_b32 v118, s34, v118, v112
	v_bfi_b32 v159, s34, v159, v153
	v_bfi_b32 v158, s34, v158, v152
	v_bfi_b32 v173, s34, v173, v167
	v_bfi_b32 v172, s34, v172, v166
	v_bfi_b32 v205, s34, v205, v199
	v_bfi_b32 v204, s34, v204, v198
	v_pk_mul_f32 v[122:123], v[112:113], 0.5 op_sel_hi:[1,0]
	v_pk_mul_f32 v[162:163], v[152:153], 0.5 op_sel_hi:[1,0]
	v_pk_mul_f32 v[176:177], v[166:167], 0.5 op_sel_hi:[1,0]
	v_pk_mul_f32 v[208:209], v[198:199], 0.5 op_sel_hi:[1,0]
	v_lshlrev_b32_e32 v124, 16, v76
	v_and_b32_e32 v125, 0xffff0000, v76
	v_lshlrev_b32_e32 v164, 16, v77
	v_and_b32_e32 v165, 0xffff0000, v77
	v_lshlrev_b32_e32 v178, 16, v78
	v_and_b32_e32 v179, 0xffff0000, v78
	v_lshlrev_b32_e32 v210, 16, v79
	v_and_b32_e32 v211, 0xffff0000, v79
	v_pk_fma_f32 v[122:123], v[122:123], v[118:119], v[122:123]
	v_pk_fma_f32 v[162:163], v[162:163], v[158:159], v[162:163]
	v_pk_fma_f32 v[176:177], v[176:177], v[172:173], v[176:177]
	v_pk_fma_f32 v[208:209], v[208:209], v[204:205], v[208:209]
	v_pk_mul_f32 v[122:123], v[122:123], v[124:125]
	v_pk_mul_f32 v[162:163], v[162:163], v[164:165]
	v_pk_mul_f32 v[176:177], v[176:177], v[178:179]
	v_pk_mul_f32 v[208:209], v[208:209], v[210:211]
	v_cvt_pk_bf16_f32 v224, v122, v123
	v_cvt_pk_bf16_f32 v225, v162, v163
	v_cvt_pk_bf16_f32 v226, v176, v177
	v_cvt_pk_bf16_f32 v227, v208, v209
	global_store_dwordx4 v[228:229], v[224:227], off nt
	v_lshl_add_u64 v[228:229], v[228:229], 0, s[98:99]
	v_lshlrev_b32_e32 v104, 16, v48
	v_and_b32_e32 v105, 0xffff0000, v48
	v_lshlrev_b32_e32 v106, 16, v49
	v_and_b32_e32 v107, 0xffff0000, v49
	v_lshlrev_b32_e32 v108, 16, v50
	v_and_b32_e32 v109, 0xffff0000, v50
	v_lshlrev_b32_e32 v110, 16, v51
	v_and_b32_e32 v111, 0xffff0000, v51
	v_pk_fma_f32 v[112:113], v[234:235], v[88:89], v[218:219]
	v_pk_fma_f32 v[152:153], v[236:237], v[90:91], v[220:221]
	v_pk_fma_f32 v[166:167], v[230:231], v[92:93], v[214:215]
	v_pk_fma_f32 v[198:199], v[232:233], v[94:95], v[216:217]
	v_pk_fma_f32 v[112:113], v[238:239], v[96:97], v[112:113]
	v_pk_fma_f32 v[152:153], v[240:241], v[98:99], v[152:153]
	v_pk_fma_f32 v[166:167], v[242:243], v[100:101], v[166:167]
	v_pk_fma_f32 v[198:199], v[244:245], v[102:103], v[198:199]
	v_pk_fma_f32 v[112:113], v[246:247], v[104:105], v[112:113]
	v_pk_fma_f32 v[152:153], v[248:249], v[106:107], v[152:153]
	v_pk_fma_f32 v[166:167], v[250:251], v[108:109], v[166:167]
	v_pk_fma_f32 v[198:199], v[252:253], v[110:111], v[198:199]
	v_fma_f32 v114, |v112|, v183, 1.0
	v_fma_f32 v115, |v113|, v183, 1.0
	v_fma_f32 v154, |v152|, v183, 1.0
	v_fma_f32 v155, |v153|, v183, 1.0
	v_fma_f32 v168, |v166|, v183, 1.0
	v_fma_f32 v169, |v167|, v183, 1.0
	v_fma_f32 v200, |v198|, v183, 1.0
	v_fma_f32 v201, |v199|, v183, 1.0
	v_mul_f32_e32 v116, v114, v115
	v_mul_f32_e32 v156, v154, v155
	v_mul_f32_e32 v170, v168, v169
	v_mul_f32_e32 v202, v200, v201
	v_pk_mul_f32 v[118:119], v[112:113], v[112:113]
	v_pk_mul_f32 v[158:159], v[152:153], v[152:153]
	v_pk_mul_f32 v[172:173], v[166:167], v[166:167]
	v_pk_mul_f32 v[204:205], v[198:199], v[198:199]
	v_rcp_f32_e32 v116, v116
	v_rcp_f32_e32 v156, v156
	v_rcp_f32_e32 v170, v170
	v_rcp_f32_e32 v202, v202
	v_pk_mul_f32 v[118:119], v[118:119], v[126:127]
	v_pk_mul_f32 v[158:159], v[158:159], v[126:127]
	v_pk_mul_f32 v[172:173], v[172:173], v[126:127]
	v_pk_mul_f32 v[204:205], v[204:205], v[126:127]
	v_pk_mul_f32 v[114:115], v[114:115], v[116:117] op_sel:[1,0] op_sel_hi:[0,0]
	v_pk_mul_f32 v[154:155], v[154:155], v[156:157] op_sel:[1,0] op_sel_hi:[0,0]
	v_pk_mul_f32 v[168:169], v[168:169], v[170:171] op_sel:[1,0] op_sel_hi:[0,0]
	v_pk_mul_f32 v[200:201], v[200:201], v[202:203] op_sel:[1,0] op_sel_hi:[0,0]
	v_exp_f32_e32 v118, v118
	v_exp_f32_e32 v119, v119
	v_exp_f32_e32 v158, v158
	v_exp_f32_e32 v159, v159
	v_exp_f32_e32 v172, v172
	v_exp_f32_e32 v173, v173
	v_exp_f32_e32 v204, v204
	v_exp_f32_e32 v205, v205
	v_pk_fma_f32 v[120:121], v[114:115], s[74:75], v[180:181] op_sel_hi:[1,0,0]
	v_pk_fma_f32 v[160:161], v[154:155], s[74:75], v[180:181] op_sel_hi:[1,0,0]
	v_pk_fma_f32 v[174:175], v[168:169], s[74:75], v[180:181] op_sel_hi:[1,0,0]
	v_pk_fma_f32 v[206:207], v[200:201], s[74:75], v[180:181] op_sel_hi:[1,0,0]
	v_pk_fma_f32 v[120:121], v[114:115], v[120:121], s[78:79] op_sel_hi:[1,1,0]
	v_pk_fma_f32 v[160:161], v[154:155], v[160:161], s[78:79] op_sel_hi:[1,1,0]
	v_pk_fma_f32 v[174:175], v[168:169], v[174:175], s[78:79] op_sel_hi:[1,1,0]
	v_pk_fma_f32 v[206:207], v[200:201], v[206:207], s[78:79] op_sel_hi:[1,1,0]
	v_pk_fma_f32 v[120:121], v[114:115], v[120:121], s[80:81] op_sel_hi:[1,1,0]
	v_pk_fma_f32 v[160:161], v[154:155], v[160:161], s[80:81] op_sel_hi:[1,1,0]
	v_pk_fma_f32 v[174:175], v[168:169], v[174:175], s[80:81] op_sel_hi:[1,1,0]
	v_pk_fma_f32 v[206:207], v[200:201], v[206:207], s[80:81] op_sel_hi:[1,1,0]
	v_pk_fma_f32 v[120:121], v[114:115], v[120:121], s[82:83] op_sel_hi:[1,1,0]
	v_pk_fma_f32 v[160:161], v[154:155], v[160:161], s[82:83] op_sel_hi:[1,1,0]
	v_pk_fma_f32 v[174:175], v[168:169], v[174:175], s[82:83] op_sel_hi:[1,1,0]
	v_pk_fma_f32 v[206:207], v[200:201], v[206:207], s[82:83] op_sel_hi:[1,1,0]
	v_pk_mul_f32 v[120:121], v[114:115], v[120:121]
	v_pk_mul_f32 v[160:161], v[154:155], v[160:161]
	v_pk_mul_f32 v[174:175], v[168:169], v[174:175]
	v_pk_mul_f32 v[206:207], v[200:201], v[206:207]
	v_pk_fma_f32 v[118:119], v[118:119], v[120:121], 1.0 op_sel_hi:[1,1,0] neg_lo:[1,0,0] neg_hi:[1,0,0]
	v_pk_fma_f32 v[158:159], v[158:159], v[160:161], 1.0 op_sel_hi:[1,1,0] neg_lo:[1,0,0] neg_hi:[1,0,0]
	v_pk_fma_f32 v[172:173], v[172:173], v[174:175], 1.0 op_sel_hi:[1,1,0] neg_lo:[1,0,0] neg_hi:[1,0,0]
	v_pk_fma_f32 v[204:205], v[204:205], v[206:207], 1.0 op_sel_hi:[1,1,0] neg_lo:[1,0,0] neg_hi:[1,0,0]
	v_bfi_b32 v119, s34, v119, v113
	v_bfi_b32 v118, s34, v118, v112
	v_bfi_b32 v159, s34, v159, v153
	v_bfi_b32 v158, s34, v158, v152
	v_bfi_b32 v173, s34, v173, v167
	v_bfi_b32 v172, s34, v172, v166
	v_bfi_b32 v205, s34, v205, v199
	v_bfi_b32 v204, s34, v204, v198
	v_pk_mul_f32 v[122:123], v[112:113], 0.5 op_sel_hi:[1,0]
	v_pk_mul_f32 v[162:163], v[152:153], 0.5 op_sel_hi:[1,0]
	v_pk_mul_f32 v[176:177], v[166:167], 0.5 op_sel_hi:[1,0]
	v_pk_mul_f32 v[208:209], v[198:199], 0.5 op_sel_hi:[1,0]
	v_lshlrev_b32_e32 v124, 16, v80
	v_and_b32_e32 v125, 0xffff0000, v80
	v_lshlrev_b32_e32 v164, 16, v81
	v_and_b32_e32 v165, 0xffff0000, v81
	v_lshlrev_b32_e32 v178, 16, v82
	v_and_b32_e32 v179, 0xffff0000, v82
	v_lshlrev_b32_e32 v210, 16, v83
	v_and_b32_e32 v211, 0xffff0000, v83
	v_pk_fma_f32 v[122:123], v[122:123], v[118:119], v[122:123]
	v_pk_fma_f32 v[162:163], v[162:163], v[158:159], v[162:163]
	v_pk_fma_f32 v[176:177], v[176:177], v[172:173], v[176:177]
	v_pk_fma_f32 v[208:209], v[208:209], v[204:205], v[208:209]
	v_pk_mul_f32 v[122:123], v[122:123], v[124:125]
	v_pk_mul_f32 v[162:163], v[162:163], v[164:165]
	v_pk_mul_f32 v[176:177], v[176:177], v[178:179]
	v_pk_mul_f32 v[208:209], v[208:209], v[210:211]
	v_cvt_pk_bf16_f32 v224, v122, v123
	v_cvt_pk_bf16_f32 v225, v162, v163
	v_cvt_pk_bf16_f32 v226, v176, v177
	v_cvt_pk_bf16_f32 v227, v208, v209
	global_store_dwordx4 v[228:229], v[224:227], off nt
	v_lshl_add_u64 v[228:229], v[228:229], 0, s[98:99]
	v_lshlrev_b32_e32 v88, 16, v52
	v_and_b32_e32 v89, 0xffff0000, v52
	v_lshlrev_b32_e32 v90, 16, v53
	v_and_b32_e32 v91, 0xffff0000, v53
	v_lshlrev_b32_e32 v92, 16, v54
	v_and_b32_e32 v93, 0xffff0000, v54
	v_lshlrev_b32_e32 v94, 16, v55
	v_and_b32_e32 v95, 0xffff0000, v55
	v_pk_fma_f32 v[112:113], v[234:235], v[96:97], v[218:219]
	v_pk_fma_f32 v[152:153], v[236:237], v[98:99], v[220:221]
	v_pk_fma_f32 v[166:167], v[230:231], v[100:101], v[214:215]
	v_pk_fma_f32 v[198:199], v[232:233], v[102:103], v[216:217]
	v_pk_fma_f32 v[112:113], v[238:239], v[104:105], v[112:113]
	v_pk_fma_f32 v[152:153], v[240:241], v[106:107], v[152:153]
	v_pk_fma_f32 v[166:167], v[242:243], v[108:109], v[166:167]
	v_pk_fma_f32 v[198:199], v[244:245], v[110:111], v[198:199]
	v_pk_fma_f32 v[112:113], v[246:247], v[88:89], v[112:113]
	v_pk_fma_f32 v[152:153], v[248:249], v[90:91], v[152:153]
	v_pk_fma_f32 v[166:167], v[250:251], v[92:93], v[166:167]
	v_pk_fma_f32 v[198:199], v[252:253], v[94:95], v[198:199]
	v_fma_f32 v114, |v112|, v183, 1.0
	v_fma_f32 v115, |v113|, v183, 1.0
	v_fma_f32 v154, |v152|, v183, 1.0
	v_fma_f32 v155, |v153|, v183, 1.0
	v_fma_f32 v168, |v166|, v183, 1.0
	v_fma_f32 v169, |v167|, v183, 1.0
	v_fma_f32 v200, |v198|, v183, 1.0
	v_fma_f32 v201, |v199|, v183, 1.0
	v_mul_f32_e32 v116, v114, v115
	v_mul_f32_e32 v156, v154, v155
	v_mul_f32_e32 v170, v168, v169
	v_mul_f32_e32 v202, v200, v201
	v_pk_mul_f32 v[118:119], v[112:113], v[112:113]
	v_pk_mul_f32 v[158:159], v[152:153], v[152:153]
	v_pk_mul_f32 v[172:173], v[166:167], v[166:167]
	v_pk_mul_f32 v[204:205], v[198:199], v[198:199]
	v_rcp_f32_e32 v116, v116
	v_rcp_f32_e32 v156, v156
	v_rcp_f32_e32 v170, v170
	v_rcp_f32_e32 v202, v202
	v_pk_mul_f32 v[118:119], v[118:119], v[126:127]
	v_pk_mul_f32 v[158:159], v[158:159], v[126:127]
	v_pk_mul_f32 v[172:173], v[172:173], v[126:127]
	v_pk_mul_f32 v[204:205], v[204:205], v[126:127]
	v_pk_mul_f32 v[114:115], v[114:115], v[116:117] op_sel:[1,0] op_sel_hi:[0,0]
	v_pk_mul_f32 v[154:155], v[154:155], v[156:157] op_sel:[1,0] op_sel_hi:[0,0]
	v_pk_mul_f32 v[168:169], v[168:169], v[170:171] op_sel:[1,0] op_sel_hi:[0,0]
	v_pk_mul_f32 v[200:201], v[200:201], v[202:203] op_sel:[1,0] op_sel_hi:[0,0]
	v_exp_f32_e32 v118, v118
	v_exp_f32_e32 v119, v119
	v_exp_f32_e32 v158, v158
	v_exp_f32_e32 v159, v159
	v_exp_f32_e32 v172, v172
	v_exp_f32_e32 v173, v173
	v_exp_f32_e32 v204, v204
	v_exp_f32_e32 v205, v205
	v_pk_fma_f32 v[120:121], v[114:115], s[74:75], v[180:181] op_sel_hi:[1,0,0]
	v_pk_fma_f32 v[160:161], v[154:155], s[74:75], v[180:181] op_sel_hi:[1,0,0]
	v_pk_fma_f32 v[174:175], v[168:169], s[74:75], v[180:181] op_sel_hi:[1,0,0]
	v_pk_fma_f32 v[206:207], v[200:201], s[74:75], v[180:181] op_sel_hi:[1,0,0]
	v_pk_fma_f32 v[120:121], v[114:115], v[120:121], s[78:79] op_sel_hi:[1,1,0]
	v_pk_fma_f32 v[160:161], v[154:155], v[160:161], s[78:79] op_sel_hi:[1,1,0]
	v_pk_fma_f32 v[174:175], v[168:169], v[174:175], s[78:79] op_sel_hi:[1,1,0]
	v_pk_fma_f32 v[206:207], v[200:201], v[206:207], s[78:79] op_sel_hi:[1,1,0]
	v_pk_fma_f32 v[120:121], v[114:115], v[120:121], s[80:81] op_sel_hi:[1,1,0]
	v_pk_fma_f32 v[160:161], v[154:155], v[160:161], s[80:81] op_sel_hi:[1,1,0]
	v_pk_fma_f32 v[174:175], v[168:169], v[174:175], s[80:81] op_sel_hi:[1,1,0]
	v_pk_fma_f32 v[206:207], v[200:201], v[206:207], s[80:81] op_sel_hi:[1,1,0]
	v_pk_fma_f32 v[120:121], v[114:115], v[120:121], s[82:83] op_sel_hi:[1,1,0]
	v_pk_fma_f32 v[160:161], v[154:155], v[160:161], s[82:83] op_sel_hi:[1,1,0]
	v_pk_fma_f32 v[174:175], v[168:169], v[174:175], s[82:83] op_sel_hi:[1,1,0]
	v_pk_fma_f32 v[206:207], v[200:201], v[206:207], s[82:83] op_sel_hi:[1,1,0]
	v_pk_mul_f32 v[120:121], v[114:115], v[120:121]
	v_pk_mul_f32 v[160:161], v[154:155], v[160:161]
	v_pk_mul_f32 v[174:175], v[168:169], v[174:175]
	v_pk_mul_f32 v[206:207], v[200:201], v[206:207]
	v_pk_fma_f32 v[118:119], v[118:119], v[120:121], 1.0 op_sel_hi:[1,1,0] neg_lo:[1,0,0] neg_hi:[1,0,0]
	v_pk_fma_f32 v[158:159], v[158:159], v[160:161], 1.0 op_sel_hi:[1,1,0] neg_lo:[1,0,0] neg_hi:[1,0,0]
	v_pk_fma_f32 v[172:173], v[172:173], v[174:175], 1.0 op_sel_hi:[1,1,0] neg_lo:[1,0,0] neg_hi:[1,0,0]
	v_pk_fma_f32 v[204:205], v[204:205], v[206:207], 1.0 op_sel_hi:[1,1,0] neg_lo:[1,0,0] neg_hi:[1,0,0]
	v_bfi_b32 v119, s34, v119, v113
	v_bfi_b32 v118, s34, v118, v112
	v_bfi_b32 v159, s34, v159, v153
	v_bfi_b32 v158, s34, v158, v152
	v_bfi_b32 v173, s34, v173, v167
	v_bfi_b32 v172, s34, v172, v166
	v_bfi_b32 v205, s34, v205, v199
	v_bfi_b32 v204, s34, v204, v198
	v_pk_mul_f32 v[122:123], v[112:113], 0.5 op_sel_hi:[1,0]
	v_pk_mul_f32 v[162:163], v[152:153], 0.5 op_sel_hi:[1,0]
	v_pk_mul_f32 v[176:177], v[166:167], 0.5 op_sel_hi:[1,0]
	v_pk_mul_f32 v[208:209], v[198:199], 0.5 op_sel_hi:[1,0]
	v_lshlrev_b32_e32 v124, 16, v84
	v_and_b32_e32 v125, 0xffff0000, v84
	v_lshlrev_b32_e32 v164, 16, v85
	v_and_b32_e32 v165, 0xffff0000, v85
	v_lshlrev_b32_e32 v178, 16, v86
	v_and_b32_e32 v179, 0xffff0000, v86
	v_lshlrev_b32_e32 v210, 16, v87
	v_and_b32_e32 v211, 0xffff0000, v87
	v_pk_fma_f32 v[122:123], v[122:123], v[118:119], v[122:123]
	v_pk_fma_f32 v[162:163], v[162:163], v[158:159], v[162:163]
	v_pk_fma_f32 v[176:177], v[176:177], v[172:173], v[176:177]
	v_pk_fma_f32 v[208:209], v[208:209], v[204:205], v[208:209]
	v_pk_mul_f32 v[122:123], v[122:123], v[124:125]
	v_pk_mul_f32 v[162:163], v[162:163], v[164:165]
	v_pk_mul_f32 v[176:177], v[176:177], v[178:179]
	v_pk_mul_f32 v[208:209], v[208:209], v[210:211]
	v_cvt_pk_bf16_f32 v224, v122, v123
	v_cvt_pk_bf16_f32 v225, v162, v163
	v_cvt_pk_bf16_f32 v226, v176, v177
	v_cvt_pk_bf16_f32 v227, v208, v209
	v_cmp_ne_u32_e32 vcc, 31, v212
	s_and_saveexec_b64 s[100:101], vcc
	global_store_dwordx4 v[228:229], v[224:227], off nt
	s_mov_b64 exec, s[100:101]
	s_cmp_eq_u32 s32, 1
	s_mov_b32 s32, 0
	s_cbranch_scc1 .Lup_rows_ret1
	s_branch .Lup_rows_ret2

.LBB0_2312:
	s_cmp_eq_u32 s32, 0
	s_cbranch_scc1 .Lup_exit_cont
	s_mov_b32 s32, 2
	s_branch .Lup_rows
.Lup_rows_ret2:
.Lup_exit_cont:
	v_cndmask_b32_e64 v0, 0, 1, s[88:89]
	v_cmp_ne_u32_e64 s[2:3], 1, v0
	s_andn2_b64 vcc, exec, s[88:89]
	s_cbranch_vccnz .LBB0_2337
	s_add_u32 s10, s4, 0x1600044
	s_addc_u32 s11, s5, 0
	s_add_u32 s12, s4, 0xfa00000
	s_addc_u32 s13, s5, 0
	s_branch .LBB0_2317

.LBB0_2353:
	s_cmp_lt_i32 s24, 0
	s_cbranch_scc1 .LBB0_2346
	s_mul_i32 s37, s24, 0x160000
	v_mov_b32_e32 v0, v184
	s_mul_hi_u32 s36, s24, 0x160000
	s_add_u32 s4, s14, s37
	s_addc_u32 s5, s15, s36
	v_ashrrev_i32_e32 v1, 6, v0
	v_bfe_u32 v4, v0, 3, 3
	s_mul_i32 s88, s22, 0x160000
	v_bitop3_b32 v3, v4, v0, 7 bitop3:0x78
	v_readfirstlane_b32 s89, v1
	s_mul_hi_i32 s44, s22, 0x160000
	s_add_u32 s86, s20, s88
	v_lshlrev_b32_e32 v5, 4, v3
	v_lshl_or_b32 v3, s89, 5, v4
	s_addc_u32 s87, s21, s44
	v_mul_lo_u32 v3, v3, s35
	s_lshl_b32 s12, s89, 12
	s_lshl_b32 s31, s89, 2
	s_waitcnt lgkmcnt(0)
	s_barrier
	v_or_b32_e32 v3, v3, v5
	s_mov_b32 m0, s12
	s_or_b32 s13, s31, 1
	global_load_lds_dwordx4 v3, s[4:5]
	s_add_i32 m0, s12, 0x8000
	s_or_b32 s29, s31, 2
	global_load_lds_dwordx4 v3, s[86:87]
	v_lshl_or_b32 v3, s13, 3, v4
	v_mul_lo_u32 v3, v3, s35
	s_lshl_b32 s13, s13, 10
	v_or_b32_e32 v3, v3, v5
	s_mov_b32 m0, s13
	s_or_b32 s31, s31, 3
	global_load_lds_dwordx4 v3, s[4:5]
	s_add_i32 m0, s13, 0x8000
	v_and_b32_e32 v2, 7, v0
	global_load_lds_dwordx4 v3, s[86:87]
	v_lshl_or_b32 v3, s29, 3, v4
	v_mul_lo_u32 v3, v3, s35
	s_lshl_b32 s29, s29, 10
	v_or_b32_e32 v3, v3, v5
	s_mov_b32 m0, s29
	v_lshlrev_b32_e32 v1, 13, v1
	global_load_lds_dwordx4 v3, s[4:5]
	s_add_i32 m0, s29, 0x8000
	global_load_lds_dwordx4 v3, s[86:87]
	v_lshl_or_b32 v3, s31, 3, v4
	v_mul_lo_u32 v3, v3, s35
	s_lshl_b32 s31, s31, 10
	v_or_b32_e32 v3, v3, v5
	s_mov_b32 m0, s31
	global_load_lds_dwordx4 v3, s[4:5]
	s_add_i32 m0, s31, 0x8000
	s_add_u32 s4, s23, s37
	global_load_lds_dwordx4 v3, s[86:87]
	v_bfe_u32 v3, v0, 4, 2
	v_bitop3_b32 v6, v3, v0, 7 bitop3:0x78
	v_lshlrev_b32_e32 v151, 4, v6
	v_lshlrev_b32_e32 v6, 7, v0
	v_and_b32_e32 v6, 0x780, v6
	v_lshlrev_b32_e32 v0, 6, v0
	v_and_or_b32 v148, v0, s85, v6
	v_bitop3_b32 v0, v3, v2, 4 bitop3:0x36
	s_mul_i32 s86, s89, 0x2c000
	v_lshlrev_b32_e32 v150, 4, v0
	v_mov_b32_e32 v0, s86
	v_mad_u32_u24 v0, v4, s35, v0
	s_addc_u32 s5, s25, s36
	s_add_i32 s36, s86, 0xb000
	v_or_b32_e32 v134, v0, v5
	v_mov_b32_e32 v0, s36
	s_add_i32 s36, s86, 0x16000
	v_mov_b32_e32 v2, s36
	s_add_i32 s36, s86, 0x21000
	v_and_or_b32 v149, v1, s83, v6
	v_mov_b32_e32 v6, s36
	v_mad_u32_u24 v0, v4, s35, v0
	v_mad_u32_u24 v2, v4, s35, v2
	v_mad_u32_u24 v4, v4, s35, v6
	s_waitcnt vmcnt(0)
	v_or_b32_e32 v0, v0, v5
	v_mov_b32_e32 v1, v135
	v_or_b32_e32 v2, v2, v5
	v_mov_b32_e32 v3, v135
	v_or_b32_e32 v4, v4, v5
	v_mov_b32_e32 v5, v135
	s_waitcnt lgkmcnt(0)
	s_barrier
	v_lshl_add_u64 v[128:129], s[4:5], 0, v[134:135]
	v_lshl_add_u64 v[130:131], s[4:5], 0, v[0:1]
	v_lshl_add_u64 v[136:137], s[4:5], 0, v[2:3]
	v_lshl_add_u64 v[138:139], s[4:5], 0, v[4:5]
	s_add_u32 s4, s26, s88
	s_addc_u32 s5, s27, s44
	v_lshl_add_u64 v[140:141], s[4:5], 0, v[134:135]
	v_lshl_add_u64 v[142:143], s[4:5], 0, v[0:1]
	v_lshl_add_u64 v[144:145], s[4:5], 0, v[2:3]
	v_lshl_add_u64 v[146:147], s[4:5], 0, v[4:5]
	s_mov_b64 s[4:5], 0
	s_mov_b32 s44, 0
.LBB0_2355:
	s_waitcnt lgkmcnt(0)
	s_mov_b32 s99, 0x10000
	s_mov_b32 s100, 0x80
	s_mov_b32 s101, 0
	s_add_i32 m0, s12, 0x10000
	s_nop 0
	global_load_lds_dwordx4 v[128:129], off
	v_lshl_add_u64 v[128:129], v[128:129], 0, s[100:101]
	s_add_i32 m0, s12, 0x18000
	s_nop 0
	global_load_lds_dwordx4 v[140:141], off
	v_lshl_add_u64 v[140:141], v[140:141], 0, s[100:101]
	s_add_i32 m0, s13, 0x10000
	s_nop 0
	global_load_lds_dwordx4 v[130:131], off
	v_lshl_add_u64 v[130:131], v[130:131], 0, s[100:101]
	s_add_i32 m0, s13, 0x18000
	s_nop 0
	global_load_lds_dwordx4 v[142:143], off
	v_lshl_add_u64 v[142:143], v[142:143], 0, s[100:101]
	s_add_i32 m0, s29, 0x10000
	s_nop 0
	global_load_lds_dwordx4 v[136:137], off
	v_lshl_add_u64 v[136:137], v[136:137], 0, s[100:101]
	s_add_i32 m0, s29, 0x18000
	s_nop 0
	global_load_lds_dwordx4 v[144:145], off
	v_lshl_add_u64 v[144:145], v[144:145], 0, s[100:101]
	s_add_i32 m0, s31, 0x10000
	s_nop 0
	global_load_lds_dwordx4 v[138:139], off
	v_lshl_add_u64 v[138:139], v[138:139], 0, s[100:101]
	s_add_i32 m0, s31, 0x18000
	s_nop 0
	global_load_lds_dwordx4 v[146:147], off
	v_lshl_add_u64 v[146:147], v[146:147], 0, s[100:101]
	v_add_u32_e32 v164, v151, v149
	v_add_u32_e32 v134, v151, v148
	ds_read_b128 v[152:155], v164 offset:32768
	ds_read_b128 v[156:159], v164 offset:34816
	ds_read_b128 v[160:163], v164 offset:36864
	ds_read_b128 v[164:167], v164 offset:38912
	ds_read_b128 v[168:171], v134 offset:0
	ds_read_b128 v[172:175], v134 offset:2048
	ds_read_b128 v[176:179], v134 offset:4096
	ds_read_b128 v[180:183], v134 offset:6144
	ds_read_b128 v[198:201], v134 offset:8192
	ds_read_b128 v[202:205], v134 offset:10240
	ds_read_b128 v[206:209], v134 offset:12288
	ds_read_b128 v[210:213], v134 offset:14336
	s_waitcnt lgkmcnt(4)
	v_mfma_f32_16x16x32_bf16 v[124:127], v[168:171], v[152:155], 0
	v_mfma_f32_16x16x32_bf16 v[120:123], v[168:171], v[156:159], 0
	v_mfma_f32_16x16x32_bf16 v[116:119], v[168:171], v[160:163], 0
	v_mfma_f32_16x16x32_bf16 v[112:115], v[168:171], v[164:167], 0
	v_mfma_f32_16x16x32_bf16 v[108:111], v[172:175], v[152:155], 0
	v_mfma_f32_16x16x32_bf16 v[104:107], v[172:175], v[156:159], 0
	v_mfma_f32_16x16x32_bf16 v[100:103], v[172:175], v[160:163], 0
	v_mfma_f32_16x16x32_bf16 v[96:99], v[172:175], v[164:167], 0
	v_mfma_f32_16x16x32_bf16 v[92:95], v[176:179], v[152:155], 0
	v_mfma_f32_16x16x32_bf16 v[84:87], v[176:179], v[156:159], 0
	v_mfma_f32_16x16x32_bf16 v[80:83], v[176:179], v[160:163], 0
	v_mfma_f32_16x16x32_bf16 v[76:79], v[176:179], v[164:167], 0
	v_mfma_f32_16x16x32_bf16 v[72:75], v[180:183], v[152:155], 0
	v_mfma_f32_16x16x32_bf16 v[68:71], v[180:183], v[156:159], 0
	v_mfma_f32_16x16x32_bf16 v[64:67], v[180:183], v[160:163], 0
	v_mfma_f32_16x16x32_bf16 v[60:63], v[180:183], v[164:167], 0
	v_add_u32_e32 v180, v150, v149
	v_add_u32_e32 v134, v150, v148
	ds_read_b128 v[168:171], v180 offset:32768
	ds_read_b128 v[172:175], v180 offset:34816
	ds_read_b128 v[176:179], v180 offset:36864
	ds_read_b128 v[180:183], v180 offset:38912
	ds_read_b128 v[214:217], v134 offset:0
	ds_read_b128 v[218:221], v134 offset:2048
	ds_read_b128 v[222:225], v134 offset:4096
	ds_read_b128 v[226:229], v134 offset:6144
	s_waitcnt lgkmcnt(8)
	v_mfma_f32_16x16x32_bf16 v[56:59], v[198:201], v[152:155], 0
	v_mfma_f32_16x16x32_bf16 v[52:55], v[198:201], v[156:159], 0
	v_mfma_f32_16x16x32_bf16 v[48:51], v[198:201], v[160:163], 0
	v_mfma_f32_16x16x32_bf16 v[44:47], v[198:201], v[164:167], 0
	v_mfma_f32_16x16x32_bf16 v[40:43], v[202:205], v[152:155], 0
	v_mfma_f32_16x16x32_bf16 v[36:39], v[202:205], v[156:159], 0
	v_mfma_f32_16x16x32_bf16 v[32:35], v[202:205], v[160:163], 0
	v_mfma_f32_16x16x32_bf16 v[28:31], v[202:205], v[164:167], 0
	v_mfma_f32_16x16x32_bf16 v[24:27], v[206:209], v[152:155], 0
	v_mfma_f32_16x16x32_bf16 v[20:23], v[206:209], v[156:159], 0
	v_mfma_f32_16x16x32_bf16 v[16:19], v[206:209], v[160:163], 0
	v_mfma_f32_16x16x32_bf16 v[12:15], v[206:209], v[164:167], 0
	v_mfma_f32_16x16x32_bf16 v[8:11], v[210:213], v[152:155], 0
	v_mfma_f32_16x16x32_bf16 v[4:7], v[210:213], v[156:159], 0
	v_mfma_f32_16x16x32_bf16 v[0:3], v[210:213], v[160:163], 0
	v_mfma_f32_16x16x32_bf16 v[88:91], v[210:213], v[164:167], 0
	ds_read_b128 v[152:155], v134 offset:8192
	ds_read_b128 v[156:159], v134 offset:10240
	ds_read_b128 v[160:163], v134 offset:12288
	ds_read_b128 v[164:167], v134 offset:14336
	s_waitcnt lgkmcnt(4)
	v_mfma_f32_16x16x32_bf16 v[124:127], v[214:217], v[168:171], v[124:127]
	v_mfma_f32_16x16x32_bf16 v[120:123], v[214:217], v[172:175], v[120:123]
	v_mfma_f32_16x16x32_bf16 v[116:119], v[214:217], v[176:179], v[116:119]
	v_mfma_f32_16x16x32_bf16 v[112:115], v[214:217], v[180:183], v[112:115]
	v_mfma_f32_16x16x32_bf16 v[108:111], v[218:221], v[168:171], v[108:111]
	v_mfma_f32_16x16x32_bf16 v[104:107], v[218:221], v[172:175], v[104:107]
	v_mfma_f32_16x16x32_bf16 v[100:103], v[218:221], v[176:179], v[100:103]
	v_mfma_f32_16x16x32_bf16 v[96:99], v[218:221], v[180:183], v[96:99]
	v_mfma_f32_16x16x32_bf16 v[92:95], v[222:225], v[168:171], v[92:95]
	v_mfma_f32_16x16x32_bf16 v[84:87], v[222:225], v[172:175], v[84:87]
	v_mfma_f32_16x16x32_bf16 v[80:83], v[222:225], v[176:179], v[80:83]
	v_mfma_f32_16x16x32_bf16 v[76:79], v[222:225], v[180:183], v[76:79]
	v_mfma_f32_16x16x32_bf16 v[72:75], v[226:229], v[168:171], v[72:75]
	v_mfma_f32_16x16x32_bf16 v[68:71], v[226:229], v[172:175], v[68:71]
	v_mfma_f32_16x16x32_bf16 v[64:67], v[226:229], v[176:179], v[64:67]
	v_mfma_f32_16x16x32_bf16 v[60:63], v[226:229], v[180:183], v[60:63]
	s_waitcnt lgkmcnt(0)
	v_mfma_f32_16x16x32_bf16 v[56:59], v[152:155], v[168:171], v[56:59]
	s_waitcnt vmcnt(0)
	s_barrier
	v_add3_u32 v210, v151, v149, s99
	v_add3_u32 v134, v151, v148, s99
	v_mfma_f32_16x16x32_bf16 v[52:55], v[152:155], v[172:175], v[52:55]
	ds_read_b128 v[198:201], v210 offset:32768
	ds_read_b128 v[202:205], v210 offset:34816
	v_mfma_f32_16x16x32_bf16 v[48:51], v[152:155], v[176:179], v[48:51]
	ds_read_b128 v[206:209], v210 offset:36864
	ds_read_b128 v[210:213], v210 offset:38912
	v_mfma_f32_16x16x32_bf16 v[44:47], v[152:155], v[180:183], v[44:47]
	ds_read_b128 v[214:217], v134 offset:0
	ds_read_b128 v[218:221], v134 offset:2048
	v_mfma_f32_16x16x32_bf16 v[40:43], v[156:159], v[168:171], v[40:43]
	ds_read_b128 v[222:225], v134 offset:4096
	ds_read_b128 v[226:229], v134 offset:6144
	s_mov_b32 m0, s12
	v_mfma_f32_16x16x32_bf16 v[36:39], v[156:159], v[172:175], v[36:39]
	global_load_lds_dwordx4 v[128:129], off
	v_lshl_add_u64 v[128:129], v[128:129], 0, s[100:101]
	s_add_i32 m0, s12, 0x8000
	v_mfma_f32_16x16x32_bf16 v[32:35], v[156:159], v[176:179], v[32:35]
	global_load_lds_dwordx4 v[140:141], off
	v_lshl_add_u64 v[140:141], v[140:141], 0, s[100:101]
	s_mov_b32 m0, s13
	v_mfma_f32_16x16x32_bf16 v[28:31], v[156:159], v[180:183], v[28:31]
	global_load_lds_dwordx4 v[130:131], off
	v_lshl_add_u64 v[130:131], v[130:131], 0, s[100:101]
	s_add_i32 m0, s13, 0x8000
	v_mfma_f32_16x16x32_bf16 v[24:27], v[160:163], v[168:171], v[24:27]
	global_load_lds_dwordx4 v[142:143], off
	v_lshl_add_u64 v[142:143], v[142:143], 0, s[100:101]
	s_mov_b32 m0, s29
	v_mfma_f32_16x16x32_bf16 v[20:23], v[160:163], v[172:175], v[20:23]
	global_load_lds_dwordx4 v[136:137], off
	v_lshl_add_u64 v[136:137], v[136:137], 0, s[100:101]
	s_add_i32 m0, s29, 0x8000
	v_mfma_f32_16x16x32_bf16 v[16:19], v[160:163], v[176:179], v[16:19]
	global_load_lds_dwordx4 v[144:145], off
	v_lshl_add_u64 v[144:145], v[144:145], 0, s[100:101]
	s_mov_b32 m0, s31
	v_mfma_f32_16x16x32_bf16 v[12:15], v[160:163], v[180:183], v[12:15]
	global_load_lds_dwordx4 v[138:139], off
	v_lshl_add_u64 v[138:139], v[138:139], 0, s[100:101]
	s_add_i32 m0, s31, 0x8000
	v_mfma_f32_16x16x32_bf16 v[8:11], v[164:167], v[168:171], v[8:11]
	global_load_lds_dwordx4 v[146:147], off
	v_lshl_add_u64 v[146:147], v[146:147], 0, s[100:101]
	v_mfma_f32_16x16x32_bf16 v[4:7], v[164:167], v[172:175], v[4:7]
	v_mfma_f32_16x16x32_bf16 v[0:3], v[164:167], v[176:179], v[0:3]
	v_mfma_f32_16x16x32_bf16 v[88:91], v[164:167], v[180:183], v[88:91]
	ds_read_b128 v[152:155], v134 offset:8192
	ds_read_b128 v[156:159], v134 offset:10240
	ds_read_b128 v[160:163], v134 offset:12288
	ds_read_b128 v[164:167], v134 offset:14336
	s_waitcnt lgkmcnt(4)
	v_mfma_f32_16x16x32_bf16 v[124:127], v[214:217], v[198:201], v[124:127]
	v_mfma_f32_16x16x32_bf16 v[120:123], v[214:217], v[202:205], v[120:123]
	v_mfma_f32_16x16x32_bf16 v[116:119], v[214:217], v[206:209], v[116:119]
	v_mfma_f32_16x16x32_bf16 v[112:115], v[214:217], v[210:213], v[112:115]
	v_mfma_f32_16x16x32_bf16 v[108:111], v[218:221], v[198:201], v[108:111]
	v_mfma_f32_16x16x32_bf16 v[104:107], v[218:221], v[202:205], v[104:107]
	v_mfma_f32_16x16x32_bf16 v[100:103], v[218:221], v[206:209], v[100:103]
	v_mfma_f32_16x16x32_bf16 v[96:99], v[218:221], v[210:213], v[96:99]
	v_mfma_f32_16x16x32_bf16 v[92:95], v[222:225], v[198:201], v[92:95]
	v_mfma_f32_16x16x32_bf16 v[84:87], v[222:225], v[202:205], v[84:87]
	v_mfma_f32_16x16x32_bf16 v[80:83], v[222:225], v[206:209], v[80:83]
	v_mfma_f32_16x16x32_bf16 v[76:79], v[222:225], v[210:213], v[76:79]
	v_mfma_f32_16x16x32_bf16 v[72:75], v[226:229], v[198:201], v[72:75]
	v_mfma_f32_16x16x32_bf16 v[68:71], v[226:229], v[202:205], v[68:71]
	v_mfma_f32_16x16x32_bf16 v[64:67], v[226:229], v[206:209], v[64:67]
	v_mfma_f32_16x16x32_bf16 v[60:63], v[226:229], v[210:213], v[60:63]
	v_add3_u32 v226, v150, v149, s99
	v_add3_u32 v134, v150, v148, s99
	ds_read_b128 v[214:217], v226 offset:32768
	ds_read_b128 v[218:221], v226 offset:34816
	ds_read_b128 v[222:225], v226 offset:36864
	ds_read_b128 v[226:229], v226 offset:38912
	ds_read_b128 v[168:171], v134 offset:0
	ds_read_b128 v[172:175], v134 offset:2048
	ds_read_b128 v[176:179], v134 offset:4096
	ds_read_b128 v[180:183], v134 offset:6144
	s_waitcnt lgkmcnt(8)
	v_mfma_f32_16x16x32_bf16 v[56:59], v[152:155], v[198:201], v[56:59]
	v_mfma_f32_16x16x32_bf16 v[52:55], v[152:155], v[202:205], v[52:55]
	v_mfma_f32_16x16x32_bf16 v[48:51], v[152:155], v[206:209], v[48:51]
	v_mfma_f32_16x16x32_bf16 v[44:47], v[152:155], v[210:213], v[44:47]
	v_mfma_f32_16x16x32_bf16 v[40:43], v[156:159], v[198:201], v[40:43]
	v_mfma_f32_16x16x32_bf16 v[36:39], v[156:159], v[202:205], v[36:39]
	v_mfma_f32_16x16x32_bf16 v[32:35], v[156:159], v[206:209], v[32:35]
	v_mfma_f32_16x16x32_bf16 v[28:31], v[156:159], v[210:213], v[28:31]
	v_mfma_f32_16x16x32_bf16 v[24:27], v[160:163], v[198:201], v[24:27]
	v_mfma_f32_16x16x32_bf16 v[20:23], v[160:163], v[202:205], v[20:23]
	v_mfma_f32_16x16x32_bf16 v[16:19], v[160:163], v[206:209], v[16:19]
	v_mfma_f32_16x16x32_bf16 v[12:15], v[160:163], v[210:213], v[12:15]
	v_mfma_f32_16x16x32_bf16 v[8:11], v[164:167], v[198:201], v[8:11]
	v_mfma_f32_16x16x32_bf16 v[4:7], v[164:167], v[202:205], v[4:7]
	v_mfma_f32_16x16x32_bf16 v[0:3], v[164:167], v[206:209], v[0:3]
	v_mfma_f32_16x16x32_bf16 v[88:91], v[164:167], v[210:213], v[88:91]
	ds_read_b128 v[198:201], v134 offset:8192
	ds_read_b128 v[202:205], v134 offset:10240
	ds_read_b128 v[206:209], v134 offset:12288
	ds_read_b128 v[210:213], v134 offset:14336
	s_waitcnt lgkmcnt(4)
	v_mfma_f32_16x16x32_bf16 v[124:127], v[168:171], v[214:217], v[124:127]
	v_mfma_f32_16x16x32_bf16 v[120:123], v[168:171], v[218:221], v[120:123]
	v_mfma_f32_16x16x32_bf16 v[116:119], v[168:171], v[222:225], v[116:119]
	v_mfma_f32_16x16x32_bf16 v[112:115], v[168:171], v[226:229], v[112:115]
	v_mfma_f32_16x16x32_bf16 v[108:111], v[172:175], v[214:217], v[108:111]
	v_mfma_f32_16x16x32_bf16 v[104:107], v[172:175], v[218:221], v[104:107]
	v_mfma_f32_16x16x32_bf16 v[100:103], v[172:175], v[222:225], v[100:103]
	v_mfma_f32_16x16x32_bf16 v[96:99], v[172:175], v[226:229], v[96:99]
	v_mfma_f32_16x16x32_bf16 v[92:95], v[176:179], v[214:217], v[92:95]
	v_mfma_f32_16x16x32_bf16 v[84:87], v[176:179], v[218:221], v[84:87]
	v_mfma_f32_16x16x32_bf16 v[80:83], v[176:179], v[222:225], v[80:83]
	v_mfma_f32_16x16x32_bf16 v[76:79], v[176:179], v[226:229], v[76:79]
	v_mfma_f32_16x16x32_bf16 v[72:75], v[180:183], v[214:217], v[72:75]
	v_mfma_f32_16x16x32_bf16 v[68:71], v[180:183], v[218:221], v[68:71]
	v_mfma_f32_16x16x32_bf16 v[64:67], v[180:183], v[222:225], v[64:67]
	v_mfma_f32_16x16x32_bf16 v[60:63], v[180:183], v[226:229], v[60:63]
	s_waitcnt lgkmcnt(0)
	v_mfma_f32_16x16x32_bf16 v[56:59], v[198:201], v[214:217], v[56:59]
	s_waitcnt vmcnt(0)
	s_barrier
	v_add_u32_e32 v164, v151, v149
	v_add_u32_e32 v134, v151, v148
	v_mfma_f32_16x16x32_bf16 v[52:55], v[198:201], v[218:221], v[52:55]
	ds_read_b128 v[152:155], v164 offset:32768
	ds_read_b128 v[156:159], v164 offset:34816
	v_mfma_f32_16x16x32_bf16 v[48:51], v[198:201], v[222:225], v[48:51]
	ds_read_b128 v[160:163], v164 offset:36864
	ds_read_b128 v[164:167], v164 offset:38912
	v_mfma_f32_16x16x32_bf16 v[44:47], v[198:201], v[226:229], v[44:47]
	ds_read_b128 v[168:171], v134 offset:0
	ds_read_b128 v[172:175], v134 offset:2048
	v_mfma_f32_16x16x32_bf16 v[40:43], v[202:205], v[214:217], v[40:43]
	ds_read_b128 v[176:179], v134 offset:4096
	ds_read_b128 v[180:183], v134 offset:6144
	s_add_i32 m0, s12, 0x10000
	v_mfma_f32_16x16x32_bf16 v[36:39], v[202:205], v[218:221], v[36:39]
	global_load_lds_dwordx4 v[128:129], off
	v_lshl_add_u64 v[128:129], v[128:129], 0, s[100:101]
	s_add_i32 m0, s12, 0x18000
	v_mfma_f32_16x16x32_bf16 v[32:35], v[202:205], v[222:225], v[32:35]
	global_load_lds_dwordx4 v[140:141], off
	v_lshl_add_u64 v[140:141], v[140:141], 0, s[100:101]
	s_add_i32 m0, s13, 0x10000
	v_mfma_f32_16x16x32_bf16 v[28:31], v[202:205], v[226:229], v[28:31]
	global_load_lds_dwordx4 v[130:131], off
	v_lshl_add_u64 v[130:131], v[130:131], 0, s[100:101]
	s_add_i32 m0, s13, 0x18000
	v_mfma_f32_16x16x32_bf16 v[24:27], v[206:209], v[214:217], v[24:27]
	global_load_lds_dwordx4 v[142:143], off
	v_lshl_add_u64 v[142:143], v[142:143], 0, s[100:101]
	s_add_i32 m0, s29, 0x10000
	v_mfma_f32_16x16x32_bf16 v[20:23], v[206:209], v[218:221], v[20:23]
	global_load_lds_dwordx4 v[136:137], off
	v_lshl_add_u64 v[136:137], v[136:137], 0, s[100:101]
	s_add_i32 m0, s29, 0x18000
	v_mfma_f32_16x16x32_bf16 v[16:19], v[206:209], v[222:225], v[16:19]
	global_load_lds_dwordx4 v[144:145], off
	v_lshl_add_u64 v[144:145], v[144:145], 0, s[100:101]
	s_add_i32 m0, s31, 0x10000
	v_mfma_f32_16x16x32_bf16 v[12:15], v[206:209], v[226:229], v[12:15]
	global_load_lds_dwordx4 v[138:139], off
	v_lshl_add_u64 v[138:139], v[138:139], 0, s[100:101]
	s_add_i32 m0, s31, 0x18000
	v_mfma_f32_16x16x32_bf16 v[8:11], v[210:213], v[214:217], v[8:11]
	global_load_lds_dwordx4 v[146:147], off
	v_lshl_add_u64 v[146:147], v[146:147], 0, s[100:101]
	v_mfma_f32_16x16x32_bf16 v[4:7], v[210:213], v[218:221], v[4:7]
	v_mfma_f32_16x16x32_bf16 v[0:3], v[210:213], v[222:225], v[0:3]
	v_mfma_f32_16x16x32_bf16 v[88:91], v[210:213], v[226:229], v[88:91]
	s_movk_i32 s4, 0x100
